# K-loop: m0/address reorder removes s_nop before LDS-DMA pieces; mid-block setprio 0/1 flips removed
# baseline (speedup 1.0000x reference)
.LBB0_322:
	s_ashr_i32 s43, s42, 31
	s_lshl_b64 s[46:47], s[42:43], 19
	s_add_u32 s46, s12, s46
	s_addc_u32 s47, s13, s47
	s_and_b64 s[48:49], s[4:5], exec
	s_cselect_b32 s18, s47, s7
	s_cselect_b32 s43, s46, s6
	s_ashr_i32 s45, s44, 31
	s_lshl_b64 s[48:49], s[44:45], 19
	s_add_u32 s48, s59, s48
	s_addc_u32 s49, s60, s49
	s_and_b64 s[50:51], s[4:5], exec
	s_cselect_b32 s45, s49, s9
	s_cselect_b32 s55, s48, s8
	s_add_u32 s6, s6, 0x40080
	s_addc_u32 s7, s7, 0
	s_add_u32 s56, s8, 0x100
	s_addc_u32 s57, s9, 0
	s_mov_b32 s78, -2
	ds_read_b128 v[96:99], v209
	ds_read_b128 v[100:103], v209 offset:1024
	ds_read_b128 v[120:123], v209 offset:2048
	ds_read_b128 v[124:127], v209 offset:3072
	ds_read_b128 v[144:147], v210
	ds_read_b128 v[148:151], v210 offset:1024
	ds_read_b128 v[152:155], v210 offset:2048
	ds_read_b128 v[156:159], v210 offset:3072
	s_add_u32 s8, s6, 0xfffc0080
	s_addc_u32 s9, s7, -1
	s_cmp_eq_u32 s78, 12
	s_cselect_b32 s51, s18, s9
	s_cselect_b32 s50, s43, s8
	s_cselect_b32 s9, s45, s57
	s_cselect_b32 s8, s55, s56
	v_lshl_add_u64 v[206:207], s[6:7], 0, v[170:171]
	s_add_i32 m0, s17, 0xc000
	ds_read_b128 v[178:181], v211
	ds_read_b128 v[182:185], v211 offset:1024
	ds_read_b128 v[186:189], v211 offset:2048
	ds_read_b128 v[190:193], v211 offset:3072
	ds_read_b128 v[194:197], v211 offset:4096
	ds_read_b128 v[198:201], v211 offset:5120
	ds_read_b128 v[202:205], v211 offset:6144
	ds_read_b128 v[218:221], v211 offset:7168
	global_load_lds_dwordx4 v[206:207], off
	s_add_i32 m0, s17, 0xe000
	v_lshl_add_u64 v[206:207], s[6:7], 0, v[172:173]
	global_load_lds_dwordx4 v[206:207], off
	s_waitcnt vmcnt(8)
	s_waitcnt lgkmcnt(0)
	s_barrier
	s_setprio 1
	s_waitcnt lgkmcnt(0)
	v_mfma_f32_16x16x32_bf16 v[140:143], v[96:99], v[178:181], 0
	v_mfma_f32_16x16x32_bf16 v[136:139], v[120:123], v[178:181], 0
	v_mfma_f32_16x16x32_bf16 v[116:119], v[96:99], v[186:189], 0
	v_mfma_f32_16x16x32_bf16 v[112:115], v[120:123], v[186:189], 0
	v_mfma_f32_16x16x32_bf16 v[92:95], v[96:99], v[194:197], 0
	v_mfma_f32_16x16x32_bf16 v[88:91], v[120:123], v[194:197], 0
	v_mfma_f32_16x16x32_bf16 v[76:79], v[96:99], v[202:205], 0
	v_mfma_f32_16x16x32_bf16 v[72:75], v[120:123], v[202:205], 0
	v_mfma_f32_16x16x32_bf16 v[140:143], v[100:103], v[182:185], v[140:143]
	v_mfma_f32_16x16x32_bf16 v[136:139], v[124:127], v[182:185], v[136:139]
	v_mfma_f32_16x16x32_bf16 v[116:119], v[100:103], v[190:193], v[116:119]
	v_mfma_f32_16x16x32_bf16 v[112:115], v[124:127], v[190:193], v[112:115]
	v_mfma_f32_16x16x32_bf16 v[92:95], v[100:103], v[198:201], v[92:95]
	v_mfma_f32_16x16x32_bf16 v[88:91], v[124:127], v[198:201], v[88:91]
	v_mfma_f32_16x16x32_bf16 v[76:79], v[100:103], v[218:221], v[76:79]
	v_mfma_f32_16x16x32_bf16 v[72:75], v[124:127], v[218:221], v[72:75]
	v_mfma_f32_16x16x32_bf16 v[132:135], v[144:147], v[178:181], 0
	v_mfma_f32_16x16x32_bf16 v[128:131], v[152:155], v[178:181], 0
	v_mfma_f32_16x16x32_bf16 v[108:111], v[144:147], v[186:189], 0
	v_mfma_f32_16x16x32_bf16 v[104:107], v[152:155], v[186:189], 0
	v_mfma_f32_16x16x32_bf16 v[84:87], v[144:147], v[194:197], 0
	v_mfma_f32_16x16x32_bf16 v[80:83], v[152:155], v[194:197], 0
	v_mfma_f32_16x16x32_bf16 v[68:71], v[144:147], v[202:205], 0
	v_mfma_f32_16x16x32_bf16 v[64:67], v[152:155], v[202:205], 0
	v_mfma_f32_16x16x32_bf16 v[132:135], v[148:151], v[182:185], v[132:135]
	v_mfma_f32_16x16x32_bf16 v[128:131], v[156:159], v[182:185], v[128:131]
	v_mfma_f32_16x16x32_bf16 v[108:111], v[148:151], v[190:193], v[108:111]
	v_mfma_f32_16x16x32_bf16 v[104:107], v[156:159], v[190:193], v[104:107]
	s_setprio 2
	s_barrier
	v_mfma_f32_16x16x32_bf16 v[84:87], v[148:151], v[198:201], v[84:87]
	v_mfma_f32_16x16x32_bf16 v[80:83], v[156:159], v[198:201], v[80:83]
	v_mfma_f32_16x16x32_bf16 v[68:71], v[148:151], v[218:221], v[68:71]
	v_mfma_f32_16x16x32_bf16 v[64:67], v[156:159], v[218:221], v[64:67]
	s_setprio 0
	s_add_i32 s79, s73, s61
	v_lshl_add_u64 v[206:207], s[8:9], 0, v[162:163]
	s_mov_b32 m0, s79
	ds_read_b128 v[178:181], v211 offset:16384
	ds_read_b128 v[182:185], v211 offset:17408
	ds_read_b128 v[186:189], v211 offset:18432
	ds_read_b128 v[190:193], v211 offset:19456
	ds_read_b128 v[194:197], v211 offset:20480
	ds_read_b128 v[198:201], v211 offset:21504
	ds_read_b128 v[202:205], v211 offset:22528
	ds_read_b128 v[218:221], v211 offset:23552
	global_load_lds_dwordx4 v[206:207], off
	s_add_i32 m0, s79, 0x2000
	s_add_u32 s80, s8, 0x40000
	v_lshl_add_u64 v[222:223], s[8:9], 0, v[166:167]
	s_addc_u32 s81, s9, 0
	s_add_i32 s79, s74, s61
	global_load_lds_dwordx4 v[222:223], off
	v_lshl_add_u64 v[224:225], s[80:81], 0, v[162:163]
	s_mov_b32 m0, s79
	v_lshl_add_u64 v[226:227], s[50:51], 0, v[164:165]
	global_load_lds_dwordx4 v[224:225], off
	s_add_i32 m0, s79, 0x2000
	v_lshl_add_u64 v[224:225], s[80:81], 0, v[166:167]
	global_load_lds_dwordx4 v[224:225], off
	s_mov_b32 m0, s17
	v_lshl_add_u64 v[224:225], s[50:51], 0, v[160:161]
	global_load_lds_dwordx4 v[224:225], off
	s_mov_b32 m0, s62
	s_nop 0
	global_load_lds_dwordx4 v[226:227], off
	s_waitcnt vmcnt(8)
	s_waitcnt lgkmcnt(0)
	s_barrier
	s_setprio 1
	s_waitcnt lgkmcnt(0)
	v_mfma_f32_16x16x32_bf16 v[60:63], v[96:99], v[178:181], 0
	v_mfma_f32_16x16x32_bf16 v[56:59], v[120:123], v[178:181], 0
	v_mfma_f32_16x16x32_bf16 v[44:47], v[96:99], v[186:189], 0
	v_mfma_f32_16x16x32_bf16 v[40:43], v[120:123], v[186:189], 0
	v_mfma_f32_16x16x32_bf16 v[28:31], v[96:99], v[194:197], 0
	v_mfma_f32_16x16x32_bf16 v[24:27], v[120:123], v[194:197], 0
	v_mfma_f32_16x16x32_bf16 v[12:15], v[96:99], v[202:205], 0
	v_mfma_f32_16x16x32_bf16 v[8:11], v[120:123], v[202:205], 0
	v_mfma_f32_16x16x32_bf16 v[60:63], v[100:103], v[182:185], v[60:63]
	v_mfma_f32_16x16x32_bf16 v[56:59], v[124:127], v[182:185], v[56:59]
	v_mfma_f32_16x16x32_bf16 v[44:47], v[100:103], v[190:193], v[44:47]
	v_mfma_f32_16x16x32_bf16 v[40:43], v[124:127], v[190:193], v[40:43]
	v_mfma_f32_16x16x32_bf16 v[28:31], v[100:103], v[198:201], v[28:31]
	v_mfma_f32_16x16x32_bf16 v[24:27], v[124:127], v[198:201], v[24:27]
	v_mfma_f32_16x16x32_bf16 v[12:15], v[100:103], v[218:221], v[12:15]
	v_mfma_f32_16x16x32_bf16 v[8:11], v[124:127], v[218:221], v[8:11]
	v_mfma_f32_16x16x32_bf16 v[52:55], v[144:147], v[178:181], 0
	v_mfma_f32_16x16x32_bf16 v[48:51], v[152:155], v[178:181], 0
	v_mfma_f32_16x16x32_bf16 v[36:39], v[144:147], v[186:189], 0
	v_mfma_f32_16x16x32_bf16 v[32:35], v[152:155], v[186:189], 0
	v_mfma_f32_16x16x32_bf16 v[20:23], v[144:147], v[194:197], 0
	v_mfma_f32_16x16x32_bf16 v[16:19], v[152:155], v[194:197], 0
	v_mfma_f32_16x16x32_bf16 v[4:7], v[144:147], v[202:205], 0
	v_mfma_f32_16x16x32_bf16 v[0:3], v[152:155], v[202:205], 0
	v_mfma_f32_16x16x32_bf16 v[52:55], v[148:151], v[182:185], v[52:55]
	v_mfma_f32_16x16x32_bf16 v[48:51], v[156:159], v[182:185], v[48:51]
	v_mfma_f32_16x16x32_bf16 v[36:39], v[148:151], v[190:193], v[36:39]
	v_mfma_f32_16x16x32_bf16 v[32:35], v[156:159], v[190:193], v[32:35]
	s_setprio 2
	s_barrier
	v_mfma_f32_16x16x32_bf16 v[20:23], v[148:151], v[198:201], v[20:23]
	v_mfma_f32_16x16x32_bf16 v[16:19], v[156:159], v[198:201], v[16:19]
	v_mfma_f32_16x16x32_bf16 v[4:7], v[148:151], v[218:221], v[4:7]
	v_mfma_f32_16x16x32_bf16 v[0:3], v[156:159], v[218:221], v[0:3]
	s_setprio 0
	s_add_i32 s79, 0, 0x18000
	s_add_i32 s80, 0, 0x1c000
	v_add_u32_e32 v124, s79, v208
	v_add_u32_e32 v156, s80, v208
	ds_read_b128 v[96:99], v124
	ds_read_b128 v[100:103], v124 offset:1024
	ds_read_b128 v[120:123], v124 offset:2048
	ds_read_b128 v[124:127], v124 offset:3072
	ds_read_b128 v[144:147], v156
	ds_read_b128 v[148:151], v156 offset:1024
	ds_read_b128 v[152:155], v156 offset:2048
	ds_read_b128 v[156:159], v156 offset:3072
	s_add_u32 s50, s50, 0x40000
	s_addc_u32 s51, s51, 0
	s_mov_b32 m0, s63
	v_lshl_add_u64 v[228:229], s[50:51], 0, v[160:161]
	ds_read_b128 v[178:181], v211 offset:32768
	ds_read_b128 v[182:185], v211 offset:33792
	ds_read_b128 v[186:189], v211 offset:34816
	ds_read_b128 v[190:193], v211 offset:35840
	ds_read_b128 v[194:197], v211 offset:36864
	ds_read_b128 v[198:201], v211 offset:37888
	ds_read_b128 v[202:205], v211 offset:38912
	ds_read_b128 v[218:221], v211 offset:39936
	global_load_lds_dwordx4 v[228:229], off
	s_mov_b32 m0, s64
	v_lshl_add_u64 v[228:229], s[50:51], 0, v[164:165]
	global_load_lds_dwordx4 v[228:229], off
	s_waitcnt vmcnt(8)
	s_waitcnt lgkmcnt(0)
	s_barrier
	s_setprio 1
	s_waitcnt lgkmcnt(0)
	v_mfma_f32_16x16x32_bf16 v[140:143], v[96:99], v[178:181], v[140:143]
	v_mfma_f32_16x16x32_bf16 v[136:139], v[120:123], v[178:181], v[136:139]
	v_mfma_f32_16x16x32_bf16 v[116:119], v[96:99], v[186:189], v[116:119]
	v_mfma_f32_16x16x32_bf16 v[112:115], v[120:123], v[186:189], v[112:115]
	v_mfma_f32_16x16x32_bf16 v[92:95], v[96:99], v[194:197], v[92:95]
	v_mfma_f32_16x16x32_bf16 v[88:91], v[120:123], v[194:197], v[88:91]
	v_mfma_f32_16x16x32_bf16 v[76:79], v[96:99], v[202:205], v[76:79]
	v_mfma_f32_16x16x32_bf16 v[72:75], v[120:123], v[202:205], v[72:75]
	v_mfma_f32_16x16x32_bf16 v[140:143], v[100:103], v[182:185], v[140:143]
	v_mfma_f32_16x16x32_bf16 v[136:139], v[124:127], v[182:185], v[136:139]
	v_mfma_f32_16x16x32_bf16 v[116:119], v[100:103], v[190:193], v[116:119]
	v_mfma_f32_16x16x32_bf16 v[112:115], v[124:127], v[190:193], v[112:115]
	v_mfma_f32_16x16x32_bf16 v[92:95], v[100:103], v[198:201], v[92:95]
	v_mfma_f32_16x16x32_bf16 v[88:91], v[124:127], v[198:201], v[88:91]
	v_mfma_f32_16x16x32_bf16 v[76:79], v[100:103], v[218:221], v[76:79]
	v_mfma_f32_16x16x32_bf16 v[72:75], v[124:127], v[218:221], v[72:75]
	v_mfma_f32_16x16x32_bf16 v[132:135], v[144:147], v[178:181], v[132:135]
	v_mfma_f32_16x16x32_bf16 v[128:131], v[152:155], v[178:181], v[128:131]
	v_mfma_f32_16x16x32_bf16 v[108:111], v[144:147], v[186:189], v[108:111]
	v_mfma_f32_16x16x32_bf16 v[104:107], v[152:155], v[186:189], v[104:107]
	v_mfma_f32_16x16x32_bf16 v[84:87], v[144:147], v[194:197], v[84:87]
	v_mfma_f32_16x16x32_bf16 v[80:83], v[152:155], v[194:197], v[80:83]
	v_mfma_f32_16x16x32_bf16 v[68:71], v[144:147], v[202:205], v[68:71]
	v_mfma_f32_16x16x32_bf16 v[64:67], v[152:155], v[202:205], v[64:67]
	v_mfma_f32_16x16x32_bf16 v[132:135], v[148:151], v[182:185], v[132:135]
	v_mfma_f32_16x16x32_bf16 v[128:131], v[156:159], v[182:185], v[128:131]
	v_mfma_f32_16x16x32_bf16 v[108:111], v[148:151], v[190:193], v[108:111]
	v_mfma_f32_16x16x32_bf16 v[104:107], v[156:159], v[190:193], v[104:107]
	s_setprio 2
	s_barrier
	v_mfma_f32_16x16x32_bf16 v[84:87], v[148:151], v[198:201], v[84:87]
	v_mfma_f32_16x16x32_bf16 v[80:83], v[156:159], v[198:201], v[80:83]
	v_mfma_f32_16x16x32_bf16 v[68:71], v[148:151], v[218:221], v[68:71]
	v_mfma_f32_16x16x32_bf16 v[64:67], v[156:159], v[218:221], v[64:67]
	s_setprio 0
	s_add_i32 s50, s79, s61
	v_lshl_add_u64 v[206:207], v[206:207], 0, s[36:37]
	s_mov_b32 m0, s50
	ds_read_b128 v[178:181], v211 offset:49152
	ds_read_b128 v[182:185], v211 offset:50176
	ds_read_b128 v[186:189], v211 offset:51200
	ds_read_b128 v[190:193], v211 offset:52224
	ds_read_b128 v[194:197], v211 offset:53248
	ds_read_b128 v[198:201], v211 offset:54272
	ds_read_b128 v[202:205], v211 offset:55296
	ds_read_b128 v[218:221], v211 offset:56320
	global_load_lds_dwordx4 v[206:207], off
	s_add_i32 m0, s50, 0x2000
	s_add_u32 s8, s8, 0x40080
	v_lshl_add_u64 v[206:207], v[222:223], 0, s[36:37]
	s_addc_u32 s9, s9, 0
	s_add_i32 s50, s80, s61
	global_load_lds_dwordx4 v[206:207], off
	s_mov_b32 m0, s50
	v_lshl_add_u64 v[206:207], s[8:9], 0, v[162:163]
	global_load_lds_dwordx4 v[206:207], off
	s_add_i32 m0, s50, 0x2000
	v_lshl_add_u64 v[206:207], s[8:9], 0, v[166:167]
	global_load_lds_dwordx4 v[206:207], off
	s_mov_b32 m0, s68
	v_lshl_add_u64 v[206:207], v[224:225], 0, s[36:37]
	global_load_lds_dwordx4 v[206:207], off
	s_mov_b32 m0, s69
	v_lshl_add_u64 v[206:207], v[226:227], 0, s[36:37]
	global_load_lds_dwordx4 v[206:207], off
	s_waitcnt vmcnt(8)
	s_waitcnt lgkmcnt(0)
	s_barrier
	s_setprio 1
	s_waitcnt lgkmcnt(0)
	v_mfma_f32_16x16x32_bf16 v[60:63], v[96:99], v[178:181], v[60:63]
	v_mfma_f32_16x16x32_bf16 v[56:59], v[120:123], v[178:181], v[56:59]
	v_mfma_f32_16x16x32_bf16 v[44:47], v[96:99], v[186:189], v[44:47]
	v_mfma_f32_16x16x32_bf16 v[40:43], v[120:123], v[186:189], v[40:43]
	v_mfma_f32_16x16x32_bf16 v[28:31], v[96:99], v[194:197], v[28:31]
	v_mfma_f32_16x16x32_bf16 v[24:27], v[120:123], v[194:197], v[24:27]
	v_mfma_f32_16x16x32_bf16 v[12:15], v[96:99], v[202:205], v[12:15]
	v_mfma_f32_16x16x32_bf16 v[8:11], v[120:123], v[202:205], v[8:11]
	v_mfma_f32_16x16x32_bf16 v[60:63], v[100:103], v[182:185], v[60:63]
	v_mfma_f32_16x16x32_bf16 v[56:59], v[124:127], v[182:185], v[56:59]
	v_mfma_f32_16x16x32_bf16 v[44:47], v[100:103], v[190:193], v[44:47]
	v_mfma_f32_16x16x32_bf16 v[40:43], v[124:127], v[190:193], v[40:43]
	v_mfma_f32_16x16x32_bf16 v[28:31], v[100:103], v[198:201], v[28:31]
	v_mfma_f32_16x16x32_bf16 v[24:27], v[124:127], v[198:201], v[24:27]
	v_mfma_f32_16x16x32_bf16 v[12:15], v[100:103], v[218:221], v[12:15]
	v_mfma_f32_16x16x32_bf16 v[8:11], v[124:127], v[218:221], v[8:11]
	v_mfma_f32_16x16x32_bf16 v[52:55], v[144:147], v[178:181], v[52:55]
	v_mfma_f32_16x16x32_bf16 v[48:51], v[152:155], v[178:181], v[48:51]
	v_mfma_f32_16x16x32_bf16 v[36:39], v[144:147], v[186:189], v[36:39]
	v_mfma_f32_16x16x32_bf16 v[32:35], v[152:155], v[186:189], v[32:35]
	v_mfma_f32_16x16x32_bf16 v[20:23], v[144:147], v[194:197], v[20:23]
	v_mfma_f32_16x16x32_bf16 v[16:19], v[152:155], v[194:197], v[16:19]
	v_mfma_f32_16x16x32_bf16 v[4:7], v[144:147], v[202:205], v[4:7]
	v_mfma_f32_16x16x32_bf16 v[0:3], v[152:155], v[202:205], v[0:3]
	v_mfma_f32_16x16x32_bf16 v[52:55], v[148:151], v[182:185], v[52:55]
	v_mfma_f32_16x16x32_bf16 v[48:51], v[156:159], v[182:185], v[48:51]
	v_mfma_f32_16x16x32_bf16 v[36:39], v[148:151], v[190:193], v[36:39]
	v_mfma_f32_16x16x32_bf16 v[32:35], v[156:159], v[190:193], v[32:35]
	s_setprio 2
	s_barrier
	v_mfma_f32_16x16x32_bf16 v[20:23], v[148:151], v[198:201], v[20:23]
	v_mfma_f32_16x16x32_bf16 v[16:19], v[156:159], v[198:201], v[16:19]
	v_mfma_f32_16x16x32_bf16 v[4:7], v[148:151], v[218:221], v[4:7]
	v_mfma_f32_16x16x32_bf16 v[0:3], v[156:159], v[218:221], v[0:3]
	s_setprio 0
	s_add_i32 s78, s78, 2
	s_add_u32 s6, s6, 0x100
	s_addc_u32 s7, s7, 0
	s_add_u32 s56, s56, 0x100
	s_addc_u32 s57, s57, 0
	s_cmp_gt_u32 s78, 13
.LBB0_323:
	ds_read_b128 v[96:99], v209
	ds_read_b128 v[100:103], v209 offset:1024
	ds_read_b128 v[120:123], v209 offset:2048
	ds_read_b128 v[124:127], v209 offset:3072
	ds_read_b128 v[144:147], v210
	ds_read_b128 v[148:151], v210 offset:1024
	ds_read_b128 v[152:155], v210 offset:2048
	ds_read_b128 v[156:159], v210 offset:3072
	s_add_u32 s8, s6, 0xfffc0080
	s_addc_u32 s9, s7, -1
	s_cmp_eq_u32 s78, 12
	s_cselect_b32 s51, s18, s9
	s_cselect_b32 s50, s43, s8
	s_cselect_b32 s9, s45, s57
	s_cselect_b32 s8, s55, s56
	v_lshl_add_u64 v[206:207], s[6:7], 0, v[170:171]
	s_add_i32 m0, s17, 0xc000
	ds_read_b128 v[178:181], v211
	ds_read_b128 v[182:185], v211 offset:1024
	ds_read_b128 v[186:189], v211 offset:2048
	ds_read_b128 v[190:193], v211 offset:3072
	ds_read_b128 v[194:197], v211 offset:4096
	ds_read_b128 v[198:201], v211 offset:5120
	ds_read_b128 v[202:205], v211 offset:6144
	ds_read_b128 v[218:221], v211 offset:7168
	global_load_lds_dwordx4 v[206:207], off
	s_add_i32 m0, s17, 0xe000
	v_lshl_add_u64 v[206:207], s[6:7], 0, v[172:173]
	global_load_lds_dwordx4 v[206:207], off
	s_waitcnt vmcnt(8)
	s_waitcnt lgkmcnt(0)
	s_barrier
	s_setprio 1
	s_waitcnt lgkmcnt(0)
	v_mfma_f32_16x16x32_bf16 v[140:143], v[96:99], v[178:181], v[140:143]
	v_mfma_f32_16x16x32_bf16 v[136:139], v[120:123], v[178:181], v[136:139]
	v_mfma_f32_16x16x32_bf16 v[116:119], v[96:99], v[186:189], v[116:119]
	v_mfma_f32_16x16x32_bf16 v[112:115], v[120:123], v[186:189], v[112:115]
	v_mfma_f32_16x16x32_bf16 v[92:95], v[96:99], v[194:197], v[92:95]
	v_mfma_f32_16x16x32_bf16 v[88:91], v[120:123], v[194:197], v[88:91]
	v_mfma_f32_16x16x32_bf16 v[76:79], v[96:99], v[202:205], v[76:79]
	v_mfma_f32_16x16x32_bf16 v[72:75], v[120:123], v[202:205], v[72:75]
	v_mfma_f32_16x16x32_bf16 v[140:143], v[100:103], v[182:185], v[140:143]
	v_mfma_f32_16x16x32_bf16 v[136:139], v[124:127], v[182:185], v[136:139]
	v_mfma_f32_16x16x32_bf16 v[116:119], v[100:103], v[190:193], v[116:119]
	v_mfma_f32_16x16x32_bf16 v[112:115], v[124:127], v[190:193], v[112:115]
	v_mfma_f32_16x16x32_bf16 v[92:95], v[100:103], v[198:201], v[92:95]
	v_mfma_f32_16x16x32_bf16 v[88:91], v[124:127], v[198:201], v[88:91]
	v_mfma_f32_16x16x32_bf16 v[76:79], v[100:103], v[218:221], v[76:79]
	v_mfma_f32_16x16x32_bf16 v[72:75], v[124:127], v[218:221], v[72:75]
	v_mfma_f32_16x16x32_bf16 v[132:135], v[144:147], v[178:181], v[132:135]
	v_mfma_f32_16x16x32_bf16 v[128:131], v[152:155], v[178:181], v[128:131]
	v_mfma_f32_16x16x32_bf16 v[108:111], v[144:147], v[186:189], v[108:111]
	v_mfma_f32_16x16x32_bf16 v[104:107], v[152:155], v[186:189], v[104:107]
	v_mfma_f32_16x16x32_bf16 v[84:87], v[144:147], v[194:197], v[84:87]
	v_mfma_f32_16x16x32_bf16 v[80:83], v[152:155], v[194:197], v[80:83]
	v_mfma_f32_16x16x32_bf16 v[68:71], v[144:147], v[202:205], v[68:71]
	v_mfma_f32_16x16x32_bf16 v[64:67], v[152:155], v[202:205], v[64:67]
	v_mfma_f32_16x16x32_bf16 v[132:135], v[148:151], v[182:185], v[132:135]
	v_mfma_f32_16x16x32_bf16 v[128:131], v[156:159], v[182:185], v[128:131]
	v_mfma_f32_16x16x32_bf16 v[108:111], v[148:151], v[190:193], v[108:111]
	v_mfma_f32_16x16x32_bf16 v[104:107], v[156:159], v[190:193], v[104:107]
	s_setprio 2
	s_barrier
	v_mfma_f32_16x16x32_bf16 v[84:87], v[148:151], v[198:201], v[84:87]
	v_mfma_f32_16x16x32_bf16 v[80:83], v[156:159], v[198:201], v[80:83]
	v_mfma_f32_16x16x32_bf16 v[68:71], v[148:151], v[218:221], v[68:71]
	v_mfma_f32_16x16x32_bf16 v[64:67], v[156:159], v[218:221], v[64:67]
	s_setprio 0
	s_add_i32 s79, s73, s61
	v_lshl_add_u64 v[206:207], s[8:9], 0, v[162:163]
	s_mov_b32 m0, s79
	ds_read_b128 v[178:181], v211 offset:16384
	ds_read_b128 v[182:185], v211 offset:17408
	ds_read_b128 v[186:189], v211 offset:18432
	ds_read_b128 v[190:193], v211 offset:19456
	ds_read_b128 v[194:197], v211 offset:20480
	ds_read_b128 v[198:201], v211 offset:21504
	ds_read_b128 v[202:205], v211 offset:22528
	ds_read_b128 v[218:221], v211 offset:23552
	global_load_lds_dwordx4 v[206:207], off
	s_add_i32 m0, s79, 0x2000
	s_add_u32 s80, s8, 0x40000
	v_lshl_add_u64 v[222:223], s[8:9], 0, v[166:167]
	s_addc_u32 s81, s9, 0
	s_add_i32 s79, s74, s61
	global_load_lds_dwordx4 v[222:223], off
	v_lshl_add_u64 v[224:225], s[80:81], 0, v[162:163]
	s_mov_b32 m0, s79
	v_lshl_add_u64 v[226:227], s[50:51], 0, v[164:165]
	global_load_lds_dwordx4 v[224:225], off
	s_add_i32 m0, s79, 0x2000
	v_lshl_add_u64 v[224:225], s[80:81], 0, v[166:167]
	global_load_lds_dwordx4 v[224:225], off
	s_mov_b32 m0, s17
	v_lshl_add_u64 v[224:225], s[50:51], 0, v[160:161]
	global_load_lds_dwordx4 v[224:225], off
	s_mov_b32 m0, s62
	s_nop 0
	global_load_lds_dwordx4 v[226:227], off
	s_waitcnt vmcnt(8)
	s_waitcnt lgkmcnt(0)
	s_barrier
	s_setprio 1
	s_waitcnt lgkmcnt(0)
	v_mfma_f32_16x16x32_bf16 v[60:63], v[96:99], v[178:181], v[60:63]
	v_mfma_f32_16x16x32_bf16 v[56:59], v[120:123], v[178:181], v[56:59]
	v_mfma_f32_16x16x32_bf16 v[44:47], v[96:99], v[186:189], v[44:47]
	v_mfma_f32_16x16x32_bf16 v[40:43], v[120:123], v[186:189], v[40:43]
	v_mfma_f32_16x16x32_bf16 v[28:31], v[96:99], v[194:197], v[28:31]
	v_mfma_f32_16x16x32_bf16 v[24:27], v[120:123], v[194:197], v[24:27]
	v_mfma_f32_16x16x32_bf16 v[12:15], v[96:99], v[202:205], v[12:15]
	v_mfma_f32_16x16x32_bf16 v[8:11], v[120:123], v[202:205], v[8:11]
	v_mfma_f32_16x16x32_bf16 v[60:63], v[100:103], v[182:185], v[60:63]
	v_mfma_f32_16x16x32_bf16 v[56:59], v[124:127], v[182:185], v[56:59]
	v_mfma_f32_16x16x32_bf16 v[44:47], v[100:103], v[190:193], v[44:47]
	v_mfma_f32_16x16x32_bf16 v[40:43], v[124:127], v[190:193], v[40:43]
	v_mfma_f32_16x16x32_bf16 v[28:31], v[100:103], v[198:201], v[28:31]
	v_mfma_f32_16x16x32_bf16 v[24:27], v[124:127], v[198:201], v[24:27]
	v_mfma_f32_16x16x32_bf16 v[12:15], v[100:103], v[218:221], v[12:15]
	v_mfma_f32_16x16x32_bf16 v[8:11], v[124:127], v[218:221], v[8:11]
	v_mfma_f32_16x16x32_bf16 v[52:55], v[144:147], v[178:181], v[52:55]
	v_mfma_f32_16x16x32_bf16 v[48:51], v[152:155], v[178:181], v[48:51]
	v_mfma_f32_16x16x32_bf16 v[36:39], v[144:147], v[186:189], v[36:39]
	v_mfma_f32_16x16x32_bf16 v[32:35], v[152:155], v[186:189], v[32:35]
	v_mfma_f32_16x16x32_bf16 v[20:23], v[144:147], v[194:197], v[20:23]
	v_mfma_f32_16x16x32_bf16 v[16:19], v[152:155], v[194:197], v[16:19]
	v_mfma_f32_16x16x32_bf16 v[4:7], v[144:147], v[202:205], v[4:7]
	v_mfma_f32_16x16x32_bf16 v[0:3], v[152:155], v[202:205], v[0:3]
	v_mfma_f32_16x16x32_bf16 v[52:55], v[148:151], v[182:185], v[52:55]
	v_mfma_f32_16x16x32_bf16 v[48:51], v[156:159], v[182:185], v[48:51]
	v_mfma_f32_16x16x32_bf16 v[36:39], v[148:151], v[190:193], v[36:39]
	v_mfma_f32_16x16x32_bf16 v[32:35], v[156:159], v[190:193], v[32:35]
	s_setprio 2
	s_barrier
	v_mfma_f32_16x16x32_bf16 v[20:23], v[148:151], v[198:201], v[20:23]
	v_mfma_f32_16x16x32_bf16 v[16:19], v[156:159], v[198:201], v[16:19]
	v_mfma_f32_16x16x32_bf16 v[4:7], v[148:151], v[218:221], v[4:7]
	v_mfma_f32_16x16x32_bf16 v[0:3], v[156:159], v[218:221], v[0:3]
	s_setprio 0
	s_add_i32 s79, 0, 0x18000
	s_add_i32 s80, 0, 0x1c000
	v_add_u32_e32 v124, s79, v208
	v_add_u32_e32 v156, s80, v208
	ds_read_b128 v[96:99], v124
	ds_read_b128 v[100:103], v124 offset:1024
	ds_read_b128 v[120:123], v124 offset:2048
	ds_read_b128 v[124:127], v124 offset:3072
	ds_read_b128 v[144:147], v156
	ds_read_b128 v[148:151], v156 offset:1024
	ds_read_b128 v[152:155], v156 offset:2048
	ds_read_b128 v[156:159], v156 offset:3072
	s_add_u32 s50, s50, 0x40000
	s_addc_u32 s51, s51, 0
	s_mov_b32 m0, s63
	v_lshl_add_u64 v[228:229], s[50:51], 0, v[160:161]
	ds_read_b128 v[178:181], v211 offset:32768
	ds_read_b128 v[182:185], v211 offset:33792
	ds_read_b128 v[186:189], v211 offset:34816
	ds_read_b128 v[190:193], v211 offset:35840
	ds_read_b128 v[194:197], v211 offset:36864
	ds_read_b128 v[198:201], v211 offset:37888
	ds_read_b128 v[202:205], v211 offset:38912
	ds_read_b128 v[218:221], v211 offset:39936
	global_load_lds_dwordx4 v[228:229], off
	s_mov_b32 m0, s64
	v_lshl_add_u64 v[228:229], s[50:51], 0, v[164:165]
	global_load_lds_dwordx4 v[228:229], off
	s_waitcnt vmcnt(8)
	s_waitcnt lgkmcnt(0)
	s_barrier
	s_setprio 1
	s_waitcnt lgkmcnt(0)
	v_mfma_f32_16x16x32_bf16 v[140:143], v[96:99], v[178:181], v[140:143]
	v_mfma_f32_16x16x32_bf16 v[136:139], v[120:123], v[178:181], v[136:139]
	v_mfma_f32_16x16x32_bf16 v[116:119], v[96:99], v[186:189], v[116:119]
	v_mfma_f32_16x16x32_bf16 v[112:115], v[120:123], v[186:189], v[112:115]
	v_mfma_f32_16x16x32_bf16 v[92:95], v[96:99], v[194:197], v[92:95]
	v_mfma_f32_16x16x32_bf16 v[88:91], v[120:123], v[194:197], v[88:91]
	v_mfma_f32_16x16x32_bf16 v[76:79], v[96:99], v[202:205], v[76:79]
	v_mfma_f32_16x16x32_bf16 v[72:75], v[120:123], v[202:205], v[72:75]
	v_mfma_f32_16x16x32_bf16 v[140:143], v[100:103], v[182:185], v[140:143]
	v_mfma_f32_16x16x32_bf16 v[136:139], v[124:127], v[182:185], v[136:139]
	v_mfma_f32_16x16x32_bf16 v[116:119], v[100:103], v[190:193], v[116:119]
	v_mfma_f32_16x16x32_bf16 v[112:115], v[124:127], v[190:193], v[112:115]
	v_mfma_f32_16x16x32_bf16 v[92:95], v[100:103], v[198:201], v[92:95]
	v_mfma_f32_16x16x32_bf16 v[88:91], v[124:127], v[198:201], v[88:91]
	v_mfma_f32_16x16x32_bf16 v[76:79], v[100:103], v[218:221], v[76:79]
	v_mfma_f32_16x16x32_bf16 v[72:75], v[124:127], v[218:221], v[72:75]
	v_mfma_f32_16x16x32_bf16 v[132:135], v[144:147], v[178:181], v[132:135]
	v_mfma_f32_16x16x32_bf16 v[128:131], v[152:155], v[178:181], v[128:131]
	v_mfma_f32_16x16x32_bf16 v[108:111], v[144:147], v[186:189], v[108:111]
	v_mfma_f32_16x16x32_bf16 v[104:107], v[152:155], v[186:189], v[104:107]
	v_mfma_f32_16x16x32_bf16 v[84:87], v[144:147], v[194:197], v[84:87]
	v_mfma_f32_16x16x32_bf16 v[80:83], v[152:155], v[194:197], v[80:83]
	v_mfma_f32_16x16x32_bf16 v[68:71], v[144:147], v[202:205], v[68:71]
	v_mfma_f32_16x16x32_bf16 v[64:67], v[152:155], v[202:205], v[64:67]
	v_mfma_f32_16x16x32_bf16 v[132:135], v[148:151], v[182:185], v[132:135]
	v_mfma_f32_16x16x32_bf16 v[128:131], v[156:159], v[182:185], v[128:131]
	v_mfma_f32_16x16x32_bf16 v[108:111], v[148:151], v[190:193], v[108:111]
	v_mfma_f32_16x16x32_bf16 v[104:107], v[156:159], v[190:193], v[104:107]
	s_setprio 2
	s_barrier
	v_mfma_f32_16x16x32_bf16 v[84:87], v[148:151], v[198:201], v[84:87]
	v_mfma_f32_16x16x32_bf16 v[80:83], v[156:159], v[198:201], v[80:83]
	v_mfma_f32_16x16x32_bf16 v[68:71], v[148:151], v[218:221], v[68:71]
	v_mfma_f32_16x16x32_bf16 v[64:67], v[156:159], v[218:221], v[64:67]
	s_setprio 0
	s_add_i32 s50, s79, s61
	v_lshl_add_u64 v[206:207], v[206:207], 0, s[36:37]
	s_mov_b32 m0, s50
	ds_read_b128 v[178:181], v211 offset:49152
	ds_read_b128 v[182:185], v211 offset:50176
	ds_read_b128 v[186:189], v211 offset:51200
	ds_read_b128 v[190:193], v211 offset:52224
	ds_read_b128 v[194:197], v211 offset:53248
	ds_read_b128 v[198:201], v211 offset:54272
	ds_read_b128 v[202:205], v211 offset:55296
	ds_read_b128 v[218:221], v211 offset:56320
	global_load_lds_dwordx4 v[206:207], off
	s_add_i32 m0, s50, 0x2000
	s_add_u32 s8, s8, 0x40080
	v_lshl_add_u64 v[206:207], v[222:223], 0, s[36:37]
	s_addc_u32 s9, s9, 0
	s_add_i32 s50, s80, s61
	global_load_lds_dwordx4 v[206:207], off
	s_mov_b32 m0, s50
	v_lshl_add_u64 v[206:207], s[8:9], 0, v[162:163]
	global_load_lds_dwordx4 v[206:207], off
	s_add_i32 m0, s50, 0x2000
	v_lshl_add_u64 v[206:207], s[8:9], 0, v[166:167]
	global_load_lds_dwordx4 v[206:207], off
	s_mov_b32 m0, s68
	v_lshl_add_u64 v[206:207], v[224:225], 0, s[36:37]
	global_load_lds_dwordx4 v[206:207], off
	s_mov_b32 m0, s69
	v_lshl_add_u64 v[206:207], v[226:227], 0, s[36:37]
	global_load_lds_dwordx4 v[206:207], off
	s_waitcnt vmcnt(8)
	s_waitcnt lgkmcnt(0)
	s_barrier
	s_setprio 1
	s_waitcnt lgkmcnt(0)
	v_mfma_f32_16x16x32_bf16 v[60:63], v[96:99], v[178:181], v[60:63]
	v_mfma_f32_16x16x32_bf16 v[56:59], v[120:123], v[178:181], v[56:59]
	v_mfma_f32_16x16x32_bf16 v[44:47], v[96:99], v[186:189], v[44:47]
	v_mfma_f32_16x16x32_bf16 v[40:43], v[120:123], v[186:189], v[40:43]
	v_mfma_f32_16x16x32_bf16 v[28:31], v[96:99], v[194:197], v[28:31]
	v_mfma_f32_16x16x32_bf16 v[24:27], v[120:123], v[194:197], v[24:27]
	v_mfma_f32_16x16x32_bf16 v[12:15], v[96:99], v[202:205], v[12:15]
	v_mfma_f32_16x16x32_bf16 v[8:11], v[120:123], v[202:205], v[8:11]
	v_mfma_f32_16x16x32_bf16 v[60:63], v[100:103], v[182:185], v[60:63]
	v_mfma_f32_16x16x32_bf16 v[56:59], v[124:127], v[182:185], v[56:59]
	v_mfma_f32_16x16x32_bf16 v[44:47], v[100:103], v[190:193], v[44:47]
	v_mfma_f32_16x16x32_bf16 v[40:43], v[124:127], v[190:193], v[40:43]
	v_mfma_f32_16x16x32_bf16 v[28:31], v[100:103], v[198:201], v[28:31]
	v_mfma_f32_16x16x32_bf16 v[24:27], v[124:127], v[198:201], v[24:27]
	v_mfma_f32_16x16x32_bf16 v[12:15], v[100:103], v[218:221], v[12:15]
	v_mfma_f32_16x16x32_bf16 v[8:11], v[124:127], v[218:221], v[8:11]
	v_mfma_f32_16x16x32_bf16 v[52:55], v[144:147], v[178:181], v[52:55]
	v_mfma_f32_16x16x32_bf16 v[48:51], v[152:155], v[178:181], v[48:51]
	v_mfma_f32_16x16x32_bf16 v[36:39], v[144:147], v[186:189], v[36:39]
	v_mfma_f32_16x16x32_bf16 v[32:35], v[152:155], v[186:189], v[32:35]
	v_mfma_f32_16x16x32_bf16 v[20:23], v[144:147], v[194:197], v[20:23]
	v_mfma_f32_16x16x32_bf16 v[16:19], v[152:155], v[194:197], v[16:19]
	v_mfma_f32_16x16x32_bf16 v[4:7], v[144:147], v[202:205], v[4:7]
	v_mfma_f32_16x16x32_bf16 v[0:3], v[152:155], v[202:205], v[0:3]
	v_mfma_f32_16x16x32_bf16 v[52:55], v[148:151], v[182:185], v[52:55]
	v_mfma_f32_16x16x32_bf16 v[48:51], v[156:159], v[182:185], v[48:51]
	v_mfma_f32_16x16x32_bf16 v[36:39], v[148:151], v[190:193], v[36:39]
	v_mfma_f32_16x16x32_bf16 v[32:35], v[156:159], v[190:193], v[32:35]
	s_setprio 2
	s_barrier
	v_mfma_f32_16x16x32_bf16 v[20:23], v[148:151], v[198:201], v[20:23]
	v_mfma_f32_16x16x32_bf16 v[16:19], v[156:159], v[198:201], v[16:19]
	v_mfma_f32_16x16x32_bf16 v[4:7], v[148:151], v[218:221], v[4:7]
	v_mfma_f32_16x16x32_bf16 v[0:3], v[156:159], v[218:221], v[0:3]
	s_setprio 0
	s_add_i32 s78, s78, 2
	s_add_u32 s6, s6, 0x100
	s_addc_u32 s7, s7, 0
	s_add_u32 s56, s56, 0x100
	s_addc_u32 s57, s57, 0
	s_cmp_gt_u32 s78, 13
	s_cbranch_scc0 .LBB0_323

.LBB0_697:
	s_and_b32 s29, s69, 0x1000
	s_add_i32 s70, s66, s29
	s_ashr_i32 s29, s28, 31
	ds_read_b128 v[0:3], v195 offset:3072
	ds_read_b128 v[4:7], v195 offset:2048
	ds_read_b128 v[8:11], v195 offset:1024
	ds_read_b128 v[12:15], v195
	ds_read_b128 v[16:19], v203 offset:3072
	ds_read_b128 v[20:23], v203 offset:2048
	ds_read_b128 v[24:27], v203 offset:1024
	ds_read_b128 v[28:31], v203
	s_lshl_b64 s[36:37], s[28:29], 20
	s_add_u32 s36, s50, s36
	s_addc_u32 s37, s51, s37
	s_and_b64 s[38:39], s[4:5], exec
	s_cselect_b32 s29, s37, s45
	s_cselect_b32 s71, s36, s44
	s_ashr_i32 s31, s30, 31
	s_lshl_b64 s[38:39], s[30:31], 20
	s_add_u32 s38, s54, s38
	s_addc_u32 s39, s55, s39
	s_and_b64 s[48:49], s[4:5], exec
	s_cselect_b32 s31, s39, s47
	s_cselect_b32 s72, s38, s46
	s_add_u32 s48, s44, 0x80080
	s_addc_u32 s49, s45, 0
	s_add_i32 s73, s56, 0xc000
	v_lshl_add_u64 v[64:65], s[48:49], 0, v[176:177]
	s_mov_b32 m0, s73
	s_add_i32 s74, s56, 0xe000
	ds_read_b128 v[32:35], v211
	ds_read_b128 v[36:39], v211 offset:1024
	ds_read_b128 v[40:43], v211 offset:2048
	ds_read_b128 v[44:47], v211 offset:3072
	ds_read_b128 v[48:51], v211 offset:4096
	ds_read_b128 v[52:55], v211 offset:5120
	ds_read_b128 v[56:59], v211 offset:6144
	ds_read_b128 v[60:63], v211 offset:7168
	global_load_lds_dwordx4 v[64:65], off
	s_mov_b32 m0, s74
	v_lshl_add_u64 v[64:65], s[48:49], 0, v[178:179]
	global_load_lds_dwordx4 v[64:65], off
	s_waitcnt vmcnt(8)
	s_waitcnt lgkmcnt(0)
	s_barrier
	s_setprio 1
	s_waitcnt lgkmcnt(0)
	v_mfma_f32_16x16x32_bf16 v[88:91], v[28:31], v[56:59], 0
	v_mfma_f32_16x16x32_bf16 v[64:67], v[28:31], v[32:35], 0
	v_mfma_f32_16x16x32_bf16 v[68:71], v[20:23], v[32:35], 0
	v_mfma_f32_16x16x32_bf16 v[72:75], v[28:31], v[40:43], 0
	v_mfma_f32_16x16x32_bf16 v[76:79], v[20:23], v[40:43], 0
	v_mfma_f32_16x16x32_bf16 v[80:83], v[28:31], v[48:51], 0
	v_mfma_f32_16x16x32_bf16 v[84:87], v[20:23], v[48:51], 0
	v_mfma_f32_16x16x32_bf16 v[96:99], v[24:27], v[60:63], v[88:91]
	v_mfma_f32_16x16x32_bf16 v[88:91], v[20:23], v[56:59], 0
	v_mfma_f32_16x16x32_bf16 v[64:67], v[24:27], v[36:39], v[64:67]
	v_mfma_f32_16x16x32_bf16 v[68:71], v[16:19], v[36:39], v[68:71]
	v_mfma_f32_16x16x32_bf16 v[72:75], v[24:27], v[44:47], v[72:75]
	v_mfma_f32_16x16x32_bf16 v[76:79], v[16:19], v[44:47], v[76:79]
	v_mfma_f32_16x16x32_bf16 v[80:83], v[24:27], v[52:55], v[80:83]
	v_mfma_f32_16x16x32_bf16 v[84:87], v[16:19], v[52:55], v[84:87]
	v_mfma_f32_16x16x32_bf16 v[100:103], v[16:19], v[60:63], v[88:91]
	v_mfma_f32_16x16x32_bf16 v[88:91], v[12:15], v[32:35], 0
	v_mfma_f32_16x16x32_bf16 v[32:35], v[4:7], v[32:35], 0
	v_mfma_f32_16x16x32_bf16 v[112:115], v[8:11], v[36:39], v[88:91]
	v_mfma_f32_16x16x32_bf16 v[32:35], v[0:3], v[36:39], v[32:35]
	v_mfma_f32_16x16x32_bf16 v[36:39], v[12:15], v[40:43], 0
	v_mfma_f32_16x16x32_bf16 v[40:43], v[4:7], v[40:43], 0
	v_mfma_f32_16x16x32_bf16 v[36:39], v[8:11], v[44:47], v[36:39]
	v_mfma_f32_16x16x32_bf16 v[40:43], v[0:3], v[44:47], v[40:43]
	v_mfma_f32_16x16x32_bf16 v[44:47], v[12:15], v[48:51], 0
	v_mfma_f32_16x16x32_bf16 v[48:51], v[4:7], v[48:51], 0
	v_mfma_f32_16x16x32_bf16 v[44:47], v[8:11], v[52:55], v[44:47]
	v_mfma_f32_16x16x32_bf16 v[48:51], v[0:3], v[52:55], v[48:51]
	s_setprio 2
	s_barrier
	v_mfma_f32_16x16x32_bf16 v[52:55], v[12:15], v[56:59], 0
	v_mfma_f32_16x16x32_bf16 v[56:59], v[4:7], v[56:59], 0
	v_mfma_f32_16x16x32_bf16 v[52:55], v[8:11], v[60:63], v[52:55]
	v_mfma_f32_16x16x32_bf16 v[56:59], v[0:3], v[60:63], v[56:59]
	s_setprio 0
	s_add_i32 s75, s68, s43
	v_lshl_add_u64 v[174:175], s[46:47], 0, v[176:177]
	s_add_i32 s76, s75, 0x2000
	v_lshl_add_u64 v[128:129], v[174:175], 0, s[24:25]
	s_mov_b32 m0, s75
	v_lshl_add_u64 v[200:201], s[46:47], 0, v[178:179]
	s_add_u32 s48, s46, 0x80100
	ds_read_b128 v[60:63], v211 offset:16384
	ds_read_b128 v[88:91], v211 offset:17408
	ds_read_b128 v[92:95], v211 offset:18432
	ds_read_b128 v[104:107], v211 offset:19456
	ds_read_b128 v[108:111], v211 offset:20480
	ds_read_b128 v[116:119], v211 offset:21504
	ds_read_b128 v[120:123], v211 offset:22528
	ds_read_b128 v[124:127], v211 offset:23552
	global_load_lds_dwordx4 v[128:129], off
	v_lshl_add_u64 v[128:129], v[200:201], 0, s[24:25]
	s_mov_b32 m0, s76
	s_addc_u32 s49, s47, 0
	s_add_i32 s77, s67, s43
	global_load_lds_dwordx4 v[128:129], off
	v_lshl_add_u64 v[128:129], s[48:49], 0, v[176:177]
	s_mov_b32 m0, s77
	s_add_i32 s78, s77, 0x2000
	global_load_lds_dwordx4 v[128:129], off
	v_lshl_add_u64 v[128:129], s[48:49], 0, v[178:179]
	s_mov_b32 m0, s78
	v_lshl_add_u64 v[208:209], s[44:45], 0, v[176:177]
	global_load_lds_dwordx4 v[128:129], off
	v_lshl_add_u64 v[128:129], v[208:209], 0, s[24:25]
	s_mov_b32 m0, s56
	v_lshl_add_u64 v[252:253], s[44:45], 0, v[178:179]
	global_load_lds_dwordx4 v[128:129], off
	s_mov_b32 m0, s57
	v_lshl_add_u64 v[128:129], v[252:253], 0, s[24:25]
	global_load_lds_dwordx4 v[128:129], off
	s_waitcnt vmcnt(8)
	s_waitcnt lgkmcnt(0)
	s_barrier
	s_setprio 1
	s_waitcnt lgkmcnt(0)
	v_mfma_f32_16x16x32_bf16 v[134:137], v[20:23], v[60:63], 0
	v_mfma_f32_16x16x32_bf16 v[142:145], v[20:23], v[92:95], 0
	v_mfma_f32_16x16x32_bf16 v[150:153], v[20:23], v[108:111], 0
	v_mfma_f32_16x16x32_bf16 v[20:23], v[20:23], v[120:123], 0
	v_mfma_f32_16x16x32_bf16 v[128:131], v[28:31], v[60:63], 0
	v_mfma_f32_16x16x32_bf16 v[134:137], v[16:19], v[88:91], v[134:137]
	v_mfma_f32_16x16x32_bf16 v[138:141], v[28:31], v[92:95], 0
	v_mfma_f32_16x16x32_bf16 v[142:145], v[16:19], v[104:107], v[142:145]
	v_mfma_f32_16x16x32_bf16 v[146:149], v[28:31], v[108:111], 0
	v_mfma_f32_16x16x32_bf16 v[150:153], v[16:19], v[116:119], v[150:153]
	v_mfma_f32_16x16x32_bf16 v[28:31], v[28:31], v[120:123], 0
	v_mfma_f32_16x16x32_bf16 v[16:19], v[16:19], v[124:127], v[20:23]
	v_mfma_f32_16x16x32_bf16 v[130:133], v[24:27], v[88:91], v[128:131]
	v_mfma_f32_16x16x32_bf16 v[138:141], v[24:27], v[104:107], v[138:141]
	v_mfma_f32_16x16x32_bf16 v[146:149], v[24:27], v[116:119], v[146:149]
	v_mfma_f32_16x16x32_bf16 v[154:157], v[24:27], v[124:127], v[28:31]
	v_mfma_f32_16x16x32_bf16 v[24:27], v[4:7], v[60:63], 0
	v_mfma_f32_16x16x32_bf16 v[158:161], v[0:3], v[88:91], v[24:27]
	v_mfma_f32_16x16x32_bf16 v[24:27], v[12:15], v[92:95], 0
	v_mfma_f32_16x16x32_bf16 v[162:165], v[8:11], v[104:107], v[24:27]
	v_mfma_f32_16x16x32_bf16 v[24:27], v[4:7], v[92:95], 0
	v_mfma_f32_16x16x32_bf16 v[166:169], v[0:3], v[104:107], v[24:27]
	v_mfma_f32_16x16x32_bf16 v[24:27], v[12:15], v[108:111], 0
	v_mfma_f32_16x16x32_bf16 v[20:23], v[12:15], v[60:63], 0
	v_mfma_f32_16x16x32_bf16 v[170:173], v[8:11], v[116:119], v[24:27]
	v_mfma_f32_16x16x32_bf16 v[24:27], v[4:7], v[108:111], 0
	v_mfma_f32_16x16x32_bf16 v[4:7], v[4:7], v[120:123], 0
	v_mfma_f32_16x16x32_bf16 v[20:23], v[8:11], v[88:91], v[20:23]
	s_setprio 2
	s_barrier
	v_mfma_f32_16x16x32_bf16 v[190:193], v[0:3], v[116:119], v[24:27]
	v_mfma_f32_16x16x32_bf16 v[12:15], v[12:15], v[120:123], 0
	v_mfma_f32_16x16x32_bf16 v[0:3], v[0:3], v[124:127], v[4:7]
	v_mfma_f32_16x16x32_bf16 v[196:199], v[8:11], v[124:127], v[12:15]
	s_setprio 0
	s_add_i32 s79, 0, 0x18000
	s_add_i32 s81, 0, 0x1c000
	v_add_u32_e32 v128, s79, v189
	v_add_u32_e32 v129, s81, v189
	ds_read_b128 v[4:7], v128
	ds_read_b128 v[8:11], v128 offset:1024
	ds_read_b128 v[204:207], v128 offset:2048
	ds_read_b128 v[212:215], v128 offset:3072
	ds_read_b128 v[216:219], v129
	ds_read_b128 v[220:223], v129 offset:1024
	ds_read_b128 v[224:227], v129 offset:2048
	ds_read_b128 v[228:231], v129 offset:3072
	s_add_u32 s48, s44, 0x80100
	s_addc_u32 s49, s45, 0
	s_mov_b32 m0, s58
	v_lshl_add_u64 v[88:89], s[48:49], 0, v[176:177]
	ds_read_b128 v[12:15], v211 offset:32768
	ds_read_b128 v[24:27], v211 offset:33792
	ds_read_b128 v[28:31], v211 offset:34816
	ds_read_b128 v[60:63], v211 offset:35840
	ds_read_b128 v[232:235], v211 offset:36864
	ds_read_b128 v[236:239], v211 offset:37888
	ds_read_b128 v[240:243], v211 offset:38912
	ds_read_b128 v[244:247], v211 offset:39936
	global_load_lds_dwordx4 v[88:89], off
	s_mov_b32 m0, s59
	v_lshl_add_u64 v[88:89], s[48:49], 0, v[178:179]
	global_load_lds_dwordx4 v[88:89], off
	s_waitcnt vmcnt(8)
	s_waitcnt lgkmcnt(0)
	s_barrier
	s_setprio 1
	s_waitcnt lgkmcnt(0)
	v_mfma_f32_16x16x32_bf16 v[64:67], v[4:7], v[12:15], v[64:67]
	v_mfma_f32_16x16x32_bf16 v[124:127], v[8:11], v[24:27], v[64:67]
	v_mfma_f32_16x16x32_bf16 v[64:67], v[204:207], v[12:15], v[68:71]
	v_mfma_f32_16x16x32_bf16 v[120:123], v[212:215], v[24:27], v[64:67]
	v_mfma_f32_16x16x32_bf16 v[64:67], v[4:7], v[28:31], v[72:75]
	v_mfma_f32_16x16x32_bf16 v[108:111], v[8:11], v[60:63], v[64:67]
	v_mfma_f32_16x16x32_bf16 v[64:67], v[204:207], v[28:31], v[76:79]
	v_mfma_f32_16x16x32_bf16 v[104:107], v[212:215], v[60:63], v[64:67]
	v_mfma_f32_16x16x32_bf16 v[64:67], v[4:7], v[232:235], v[80:83]
	v_mfma_f32_16x16x32_bf16 v[92:95], v[8:11], v[236:239], v[64:67]
	v_mfma_f32_16x16x32_bf16 v[64:67], v[204:207], v[232:235], v[84:87]
	v_mfma_f32_16x16x32_bf16 v[88:91], v[212:215], v[236:239], v[64:67]
	v_mfma_f32_16x16x32_bf16 v[64:67], v[4:7], v[240:243], v[96:99]
	v_mfma_f32_16x16x32_bf16 v[76:79], v[8:11], v[244:247], v[64:67]
	v_mfma_f32_16x16x32_bf16 v[64:67], v[204:207], v[240:243], v[100:103]
	v_mfma_f32_16x16x32_bf16 v[72:75], v[212:215], v[244:247], v[64:67]
	v_mfma_f32_16x16x32_bf16 v[64:67], v[216:219], v[12:15], v[112:115]
	v_mfma_f32_16x16x32_bf16 v[12:15], v[224:227], v[12:15], v[32:35]
	v_mfma_f32_16x16x32_bf16 v[112:115], v[228:231], v[24:27], v[12:15]
	v_mfma_f32_16x16x32_bf16 v[12:15], v[216:219], v[28:31], v[36:39]
	v_mfma_f32_16x16x32_bf16 v[100:103], v[220:223], v[60:63], v[12:15]
	v_mfma_f32_16x16x32_bf16 v[12:15], v[224:227], v[28:31], v[40:43]
	v_mfma_f32_16x16x32_bf16 v[96:99], v[228:231], v[60:63], v[12:15]
	v_mfma_f32_16x16x32_bf16 v[12:15], v[216:219], v[232:235], v[44:47]
	v_mfma_f32_16x16x32_bf16 v[84:87], v[220:223], v[236:239], v[12:15]
	v_mfma_f32_16x16x32_bf16 v[12:15], v[224:227], v[232:235], v[48:51]
	v_mfma_f32_16x16x32_bf16 v[80:83], v[228:231], v[236:239], v[12:15]
	v_mfma_f32_16x16x32_bf16 v[12:15], v[216:219], v[240:243], v[52:55]
	s_setprio 2
	s_barrier
	v_mfma_f32_16x16x32_bf16 v[68:71], v[220:223], v[244:247], v[12:15]
	v_mfma_f32_16x16x32_bf16 v[12:15], v[224:227], v[240:243], v[56:59]
	v_mfma_f32_16x16x32_bf16 v[116:119], v[220:223], v[24:27], v[64:67]
	v_mfma_f32_16x16x32_bf16 v[64:67], v[228:231], v[244:247], v[12:15]
	s_setprio 0
	s_add_i32 s79, s79, s43
	s_add_i32 s80, s79, 0x2000
	s_nop 1
	v_lshl_add_u64 v[12:13], v[174:175], 0, s[26:27]
	s_mov_b32 m0, s79
	s_add_u32 s48, s46, 0x80180
	ds_read_b128 v[32:35], v211 offset:49152
	ds_read_b128 v[36:39], v211 offset:50176
	ds_read_b128 v[232:235], v211 offset:51200
	ds_read_b128 v[236:239], v211 offset:52224
	ds_read_b128 v[240:243], v211 offset:53248
	ds_read_b128 v[244:247], v211 offset:54272
	ds_read_b128 v[248:251], v211 offset:55296
	ds_read_b128 v[184:187], v211 offset:56320
	global_load_lds_dwordx4 v[12:13], off
	v_lshl_add_u64 v[12:13], v[200:201], 0, s[26:27]
	s_mov_b32 m0, s80
	s_addc_u32 s49, s47, 0
	s_add_i32 s81, s81, s43
	global_load_lds_dwordx4 v[12:13], off
	v_lshl_add_u64 v[12:13], s[48:49], 0, v[176:177]
	s_mov_b32 m0, s81
	s_add_i32 s82, s81, 0x2000
	global_load_lds_dwordx4 v[12:13], off
	s_mov_b32 m0, s82
	v_lshl_add_u64 v[12:13], s[48:49], 0, v[178:179]
	global_load_lds_dwordx4 v[12:13], off
	s_mov_b32 m0, s61
	v_lshl_add_u64 v[12:13], v[208:209], 0, s[26:27]
	global_load_lds_dwordx4 v[12:13], off
	s_mov_b32 m0, s62
	v_lshl_add_u64 v[12:13], v[252:253], 0, s[26:27]
	global_load_lds_dwordx4 v[12:13], off
	s_waitcnt vmcnt(8)
	s_waitcnt lgkmcnt(0)
	s_barrier
	s_setprio 1
	s_waitcnt lgkmcnt(0)
	v_mfma_f32_16x16x32_bf16 v[12:15], v[4:7], v[32:35], v[130:133]
	v_mfma_f32_16x16x32_bf16 v[60:63], v[8:11], v[36:39], v[12:15]
	v_mfma_f32_16x16x32_bf16 v[12:15], v[204:207], v[32:35], v[134:137]
	v_mfma_f32_16x16x32_bf16 v[56:59], v[212:215], v[36:39], v[12:15]
	v_mfma_f32_16x16x32_bf16 v[12:15], v[4:7], v[232:235], v[138:141]
	v_mfma_f32_16x16x32_bf16 v[44:47], v[8:11], v[236:239], v[12:15]
	v_mfma_f32_16x16x32_bf16 v[12:15], v[204:207], v[232:235], v[142:145]
	v_mfma_f32_16x16x32_bf16 v[40:43], v[212:215], v[236:239], v[12:15]
	v_mfma_f32_16x16x32_bf16 v[12:15], v[4:7], v[240:243], v[146:149]
	v_mfma_f32_16x16x32_bf16 v[28:31], v[8:11], v[244:247], v[12:15]
	v_mfma_f32_16x16x32_bf16 v[12:15], v[204:207], v[240:243], v[150:153]
	v_mfma_f32_16x16x32_bf16 v[4:7], v[4:7], v[248:251], v[154:157]
	v_mfma_f32_16x16x32_bf16 v[24:27], v[212:215], v[244:247], v[12:15]
	v_mfma_f32_16x16x32_bf16 v[12:15], v[8:11], v[184:187], v[4:7]
	v_mfma_f32_16x16x32_bf16 v[4:7], v[204:207], v[248:251], v[16:19]
	v_mfma_f32_16x16x32_bf16 v[8:11], v[212:215], v[184:187], v[4:7]
	v_mfma_f32_16x16x32_bf16 v[4:7], v[216:219], v[32:35], v[20:23]
	v_mfma_f32_16x16x32_bf16 v[52:55], v[220:223], v[36:39], v[4:7]
	v_mfma_f32_16x16x32_bf16 v[4:7], v[224:227], v[32:35], v[158:161]
	v_mfma_f32_16x16x32_bf16 v[48:51], v[228:231], v[36:39], v[4:7]
	v_mfma_f32_16x16x32_bf16 v[4:7], v[216:219], v[232:235], v[162:165]
	v_mfma_f32_16x16x32_bf16 v[36:39], v[220:223], v[236:239], v[4:7]
	v_mfma_f32_16x16x32_bf16 v[4:7], v[224:227], v[232:235], v[166:169]
	v_mfma_f32_16x16x32_bf16 v[32:35], v[228:231], v[236:239], v[4:7]
	v_mfma_f32_16x16x32_bf16 v[4:7], v[216:219], v[240:243], v[170:173]
	v_mfma_f32_16x16x32_bf16 v[20:23], v[220:223], v[244:247], v[4:7]
	v_mfma_f32_16x16x32_bf16 v[4:7], v[224:227], v[240:243], v[190:193]
	v_mfma_f32_16x16x32_bf16 v[16:19], v[228:231], v[244:247], v[4:7]
	s_setprio 2
	s_barrier
	v_mfma_f32_16x16x32_bf16 v[4:7], v[216:219], v[248:251], v[196:199]
	v_mfma_f32_16x16x32_bf16 v[0:3], v[224:227], v[248:251], v[0:3]
	v_mfma_f32_16x16x32_bf16 v[4:7], v[220:223], v[184:187], v[4:7]
	v_mfma_f32_16x16x32_bf16 v[0:3], v[228:231], v[184:187], v[0:3]
	s_setprio 0
	s_add_u32 s44, s44, 0x80180
	s_addc_u32 s45, s45, 0
	s_add_u32 s83, s46, 0x200
	s_addc_u32 s84, s47, 0
	s_mov_b32 s46, 0
	s_add_i32 s85, s46, 2
	s_and_b32 s47, s85, 6
	s_cmp_lg_u32 s47, 0
	s_cbranch_scc1 .LBB0_700
	s_branch .LBB0_699

.LBB0_700:
	ds_read_b128 v[130:133], v203
	ds_read_b128 v[134:137], v203 offset:1024
	ds_read_b128 v[138:141], v203 offset:2048
	ds_read_b128 v[142:145], v203 offset:3072
	ds_read_b128 v[146:149], v195
	ds_read_b128 v[150:153], v195 offset:1024
	ds_read_b128 v[154:157], v195 offset:2048
	ds_read_b128 v[158:161], v195 offset:3072
	s_add_u32 s47, s44, 0xfff80080
	s_addc_u32 s48, s45, -1
	s_cmp_eq_u32 s46, 28
	s_cselect_b32 s49, s29, s48
	s_cselect_b32 s48, s71, s47
	s_cselect_b32 s47, s31, s84
	s_cselect_b32 s46, s72, s83
	s_mov_b32 m0, s73
	v_lshl_add_u64 v[174:175], s[44:45], 0, v[180:181]
	ds_read_b128 v[162:165], v211
	ds_read_b128 v[166:169], v211 offset:1024
	ds_read_b128 v[170:173], v211 offset:2048
	ds_read_b128 v[184:187], v211 offset:3072
	ds_read_b128 v[190:193], v211 offset:4096
	ds_read_b128 v[196:199], v211 offset:5120
	ds_read_b128 v[204:207], v211 offset:6144
	ds_read_b128 v[212:215], v211 offset:7168
	global_load_lds_dwordx4 v[174:175], off
	s_mov_b32 m0, s74
	v_lshl_add_u64 v[174:175], s[44:45], 0, v[182:183]
	global_load_lds_dwordx4 v[174:175], off
	s_waitcnt vmcnt(8)
	s_waitcnt lgkmcnt(0)
	s_barrier
	s_setprio 1
	s_waitcnt lgkmcnt(0)
	v_mfma_f32_16x16x32_bf16 v[124:127], v[130:133], v[162:165], v[124:127]
	v_mfma_f32_16x16x32_bf16 v[120:123], v[138:141], v[162:165], v[120:123]
	v_mfma_f32_16x16x32_bf16 v[108:111], v[130:133], v[170:173], v[108:111]
	v_mfma_f32_16x16x32_bf16 v[104:107], v[138:141], v[170:173], v[104:107]
	v_mfma_f32_16x16x32_bf16 v[92:95], v[130:133], v[190:193], v[92:95]
	v_mfma_f32_16x16x32_bf16 v[88:91], v[138:141], v[190:193], v[88:91]
	v_mfma_f32_16x16x32_bf16 v[76:79], v[130:133], v[204:207], v[76:79]
	v_mfma_f32_16x16x32_bf16 v[72:75], v[138:141], v[204:207], v[72:75]
	v_mfma_f32_16x16x32_bf16 v[124:127], v[134:137], v[166:169], v[124:127]
	v_mfma_f32_16x16x32_bf16 v[120:123], v[142:145], v[166:169], v[120:123]
	v_mfma_f32_16x16x32_bf16 v[108:111], v[134:137], v[184:187], v[108:111]
	v_mfma_f32_16x16x32_bf16 v[104:107], v[142:145], v[184:187], v[104:107]
	v_mfma_f32_16x16x32_bf16 v[92:95], v[134:137], v[196:199], v[92:95]
	v_mfma_f32_16x16x32_bf16 v[88:91], v[142:145], v[196:199], v[88:91]
	v_mfma_f32_16x16x32_bf16 v[76:79], v[134:137], v[212:215], v[76:79]
	v_mfma_f32_16x16x32_bf16 v[72:75], v[142:145], v[212:215], v[72:75]
	v_mfma_f32_16x16x32_bf16 v[116:119], v[146:149], v[162:165], v[116:119]
	v_mfma_f32_16x16x32_bf16 v[112:115], v[154:157], v[162:165], v[112:115]
	v_mfma_f32_16x16x32_bf16 v[100:103], v[146:149], v[170:173], v[100:103]
	v_mfma_f32_16x16x32_bf16 v[96:99], v[154:157], v[170:173], v[96:99]
	v_mfma_f32_16x16x32_bf16 v[84:87], v[146:149], v[190:193], v[84:87]
	v_mfma_f32_16x16x32_bf16 v[80:83], v[154:157], v[190:193], v[80:83]
	v_mfma_f32_16x16x32_bf16 v[68:71], v[146:149], v[204:207], v[68:71]
	v_mfma_f32_16x16x32_bf16 v[64:67], v[154:157], v[204:207], v[64:67]
	v_mfma_f32_16x16x32_bf16 v[116:119], v[150:153], v[166:169], v[116:119]
	v_mfma_f32_16x16x32_bf16 v[112:115], v[158:161], v[166:169], v[112:115]
	v_mfma_f32_16x16x32_bf16 v[100:103], v[150:153], v[184:187], v[100:103]
	v_mfma_f32_16x16x32_bf16 v[96:99], v[158:161], v[184:187], v[96:99]
	s_setprio 2
	s_barrier
	v_mfma_f32_16x16x32_bf16 v[84:87], v[150:153], v[196:199], v[84:87]
	v_mfma_f32_16x16x32_bf16 v[80:83], v[158:161], v[196:199], v[80:83]
	v_mfma_f32_16x16x32_bf16 v[68:71], v[150:153], v[212:215], v[68:71]
	v_mfma_f32_16x16x32_bf16 v[64:67], v[158:161], v[212:215], v[64:67]
	s_setprio 0
	s_mov_b32 m0, s75
	v_lshl_add_u64 v[174:175], s[46:47], 0, v[176:177]
	s_add_u32 s86, s46, 0x80000
	ds_read_b128 v[162:165], v211 offset:16384
	ds_read_b128 v[166:169], v211 offset:17408
	ds_read_b128 v[170:173], v211 offset:18432
	ds_read_b128 v[184:187], v211 offset:19456
	ds_read_b128 v[190:193], v211 offset:20480
	ds_read_b128 v[196:199], v211 offset:21504
	ds_read_b128 v[204:207], v211 offset:22528
	ds_read_b128 v[212:215], v211 offset:23552
	global_load_lds_dwordx4 v[174:175], off
	v_lshl_add_u64 v[200:201], s[46:47], 0, v[178:179]
	s_mov_b32 m0, s76
	s_addc_u32 s87, s47, 0
	global_load_lds_dwordx4 v[200:201], off
	v_lshl_add_u64 v[208:209], s[86:87], 0, v[176:177]
	s_mov_b32 m0, s77
	v_lshl_add_u64 v[216:217], s[48:49], 0, v[178:179]
	global_load_lds_dwordx4 v[208:209], off
	s_mov_b32 m0, s78
	v_lshl_add_u64 v[208:209], s[86:87], 0, v[178:179]
	global_load_lds_dwordx4 v[208:209], off
	s_mov_b32 m0, s56
	v_lshl_add_u64 v[208:209], s[48:49], 0, v[176:177]
	global_load_lds_dwordx4 v[208:209], off
	s_mov_b32 m0, s57
	s_nop 0
	global_load_lds_dwordx4 v[216:217], off
	s_waitcnt vmcnt(8)
	s_waitcnt lgkmcnt(0)
	s_barrier
	s_setprio 1
	s_waitcnt lgkmcnt(0)
	v_mfma_f32_16x16x32_bf16 v[60:63], v[130:133], v[162:165], v[60:63]
	v_mfma_f32_16x16x32_bf16 v[56:59], v[138:141], v[162:165], v[56:59]
	v_mfma_f32_16x16x32_bf16 v[44:47], v[130:133], v[170:173], v[44:47]
	v_mfma_f32_16x16x32_bf16 v[40:43], v[138:141], v[170:173], v[40:43]
	v_mfma_f32_16x16x32_bf16 v[28:31], v[130:133], v[190:193], v[28:31]
	v_mfma_f32_16x16x32_bf16 v[24:27], v[138:141], v[190:193], v[24:27]
	v_mfma_f32_16x16x32_bf16 v[12:15], v[130:133], v[204:207], v[12:15]
	v_mfma_f32_16x16x32_bf16 v[8:11], v[138:141], v[204:207], v[8:11]
	v_mfma_f32_16x16x32_bf16 v[60:63], v[134:137], v[166:169], v[60:63]
	v_mfma_f32_16x16x32_bf16 v[56:59], v[142:145], v[166:169], v[56:59]
	v_mfma_f32_16x16x32_bf16 v[44:47], v[134:137], v[184:187], v[44:47]
	v_mfma_f32_16x16x32_bf16 v[40:43], v[142:145], v[184:187], v[40:43]
	v_mfma_f32_16x16x32_bf16 v[28:31], v[134:137], v[196:199], v[28:31]
	v_mfma_f32_16x16x32_bf16 v[24:27], v[142:145], v[196:199], v[24:27]
	v_mfma_f32_16x16x32_bf16 v[12:15], v[134:137], v[212:215], v[12:15]
	v_mfma_f32_16x16x32_bf16 v[8:11], v[142:145], v[212:215], v[8:11]
	v_mfma_f32_16x16x32_bf16 v[52:55], v[146:149], v[162:165], v[52:55]
	v_mfma_f32_16x16x32_bf16 v[48:51], v[154:157], v[162:165], v[48:51]
	v_mfma_f32_16x16x32_bf16 v[36:39], v[146:149], v[170:173], v[36:39]
	v_mfma_f32_16x16x32_bf16 v[32:35], v[154:157], v[170:173], v[32:35]
	v_mfma_f32_16x16x32_bf16 v[20:23], v[146:149], v[190:193], v[20:23]
	v_mfma_f32_16x16x32_bf16 v[16:19], v[154:157], v[190:193], v[16:19]
	v_mfma_f32_16x16x32_bf16 v[4:7], v[146:149], v[204:207], v[4:7]
	v_mfma_f32_16x16x32_bf16 v[0:3], v[154:157], v[204:207], v[0:3]
	v_mfma_f32_16x16x32_bf16 v[52:55], v[150:153], v[166:169], v[52:55]
	v_mfma_f32_16x16x32_bf16 v[48:51], v[158:161], v[166:169], v[48:51]
	v_mfma_f32_16x16x32_bf16 v[36:39], v[150:153], v[184:187], v[36:39]
	v_mfma_f32_16x16x32_bf16 v[32:35], v[158:161], v[184:187], v[32:35]
	s_setprio 2
	s_barrier
	v_mfma_f32_16x16x32_bf16 v[20:23], v[150:153], v[196:199], v[20:23]
	v_mfma_f32_16x16x32_bf16 v[16:19], v[158:161], v[196:199], v[16:19]
	v_mfma_f32_16x16x32_bf16 v[4:7], v[150:153], v[212:215], v[4:7]
	v_mfma_f32_16x16x32_bf16 v[0:3], v[158:161], v[212:215], v[0:3]
	s_setprio 0
	ds_read_b128 v[130:133], v128
	ds_read_b128 v[134:137], v128 offset:1024
	ds_read_b128 v[138:141], v128 offset:2048
	ds_read_b128 v[142:145], v128 offset:3072
	ds_read_b128 v[146:149], v129
	ds_read_b128 v[150:153], v129 offset:1024
	ds_read_b128 v[154:157], v129 offset:2048
	ds_read_b128 v[158:161], v129 offset:3072
	s_add_u32 s48, s48, 0x80000
	s_addc_u32 s49, s49, 0
	s_mov_b32 m0, s58
	v_lshl_add_u64 v[218:219], s[48:49], 0, v[176:177]
	ds_read_b128 v[162:165], v211 offset:32768
	ds_read_b128 v[166:169], v211 offset:33792
	ds_read_b128 v[170:173], v211 offset:34816
	ds_read_b128 v[184:187], v211 offset:35840
	ds_read_b128 v[190:193], v211 offset:36864
	ds_read_b128 v[196:199], v211 offset:37888
	ds_read_b128 v[204:207], v211 offset:38912
	ds_read_b128 v[212:215], v211 offset:39936
	global_load_lds_dwordx4 v[218:219], off
	s_mov_b32 m0, s59
	v_lshl_add_u64 v[218:219], s[48:49], 0, v[178:179]
	global_load_lds_dwordx4 v[218:219], off
	s_waitcnt vmcnt(8)
	s_waitcnt lgkmcnt(0)
	s_barrier
	s_setprio 1
	s_waitcnt lgkmcnt(0)
	v_mfma_f32_16x16x32_bf16 v[124:127], v[130:133], v[162:165], v[124:127]
	v_mfma_f32_16x16x32_bf16 v[120:123], v[138:141], v[162:165], v[120:123]
	v_mfma_f32_16x16x32_bf16 v[108:111], v[130:133], v[170:173], v[108:111]
	v_mfma_f32_16x16x32_bf16 v[104:107], v[138:141], v[170:173], v[104:107]
	v_mfma_f32_16x16x32_bf16 v[92:95], v[130:133], v[190:193], v[92:95]
	v_mfma_f32_16x16x32_bf16 v[88:91], v[138:141], v[190:193], v[88:91]
	v_mfma_f32_16x16x32_bf16 v[76:79], v[130:133], v[204:207], v[76:79]
	v_mfma_f32_16x16x32_bf16 v[72:75], v[138:141], v[204:207], v[72:75]
	v_mfma_f32_16x16x32_bf16 v[124:127], v[134:137], v[166:169], v[124:127]
	v_mfma_f32_16x16x32_bf16 v[120:123], v[142:145], v[166:169], v[120:123]
	v_mfma_f32_16x16x32_bf16 v[108:111], v[134:137], v[184:187], v[108:111]
	v_mfma_f32_16x16x32_bf16 v[104:107], v[142:145], v[184:187], v[104:107]
	v_mfma_f32_16x16x32_bf16 v[92:95], v[134:137], v[196:199], v[92:95]
	v_mfma_f32_16x16x32_bf16 v[88:91], v[142:145], v[196:199], v[88:91]
	v_mfma_f32_16x16x32_bf16 v[76:79], v[134:137], v[212:215], v[76:79]
	v_mfma_f32_16x16x32_bf16 v[72:75], v[142:145], v[212:215], v[72:75]
	v_mfma_f32_16x16x32_bf16 v[116:119], v[146:149], v[162:165], v[116:119]
	v_mfma_f32_16x16x32_bf16 v[112:115], v[154:157], v[162:165], v[112:115]
	v_mfma_f32_16x16x32_bf16 v[100:103], v[146:149], v[170:173], v[100:103]
	v_mfma_f32_16x16x32_bf16 v[96:99], v[154:157], v[170:173], v[96:99]
	v_mfma_f32_16x16x32_bf16 v[84:87], v[146:149], v[190:193], v[84:87]
	v_mfma_f32_16x16x32_bf16 v[80:83], v[154:157], v[190:193], v[80:83]
	v_mfma_f32_16x16x32_bf16 v[68:71], v[146:149], v[204:207], v[68:71]
	v_mfma_f32_16x16x32_bf16 v[64:67], v[154:157], v[204:207], v[64:67]
	v_mfma_f32_16x16x32_bf16 v[116:119], v[150:153], v[166:169], v[116:119]
	v_mfma_f32_16x16x32_bf16 v[112:115], v[158:161], v[166:169], v[112:115]
	v_mfma_f32_16x16x32_bf16 v[100:103], v[150:153], v[184:187], v[100:103]
	v_mfma_f32_16x16x32_bf16 v[96:99], v[158:161], v[184:187], v[96:99]
	s_setprio 2
	s_barrier
	v_mfma_f32_16x16x32_bf16 v[84:87], v[150:153], v[196:199], v[84:87]
	v_mfma_f32_16x16x32_bf16 v[80:83], v[158:161], v[196:199], v[80:83]
	v_mfma_f32_16x16x32_bf16 v[68:71], v[150:153], v[212:215], v[68:71]
	v_mfma_f32_16x16x32_bf16 v[64:67], v[158:161], v[212:215], v[64:67]
	s_setprio 0
	s_mov_b32 m0, s79
	v_lshl_add_u64 v[174:175], v[174:175], 0, s[20:21]
	s_add_u32 s46, s46, 0x80080
	ds_read_b128 v[162:165], v211 offset:49152
	ds_read_b128 v[166:169], v211 offset:50176
	ds_read_b128 v[170:173], v211 offset:51200
	ds_read_b128 v[184:187], v211 offset:52224
	ds_read_b128 v[190:193], v211 offset:53248
	ds_read_b128 v[196:199], v211 offset:54272
	ds_read_b128 v[204:207], v211 offset:55296
	ds_read_b128 v[212:215], v211 offset:56320
	global_load_lds_dwordx4 v[174:175], off
	v_lshl_add_u64 v[174:175], v[200:201], 0, s[20:21]
	s_mov_b32 m0, s80
	s_addc_u32 s47, s47, 0
	global_load_lds_dwordx4 v[174:175], off
	s_mov_b32 m0, s81
	v_lshl_add_u64 v[174:175], s[46:47], 0, v[176:177]
	global_load_lds_dwordx4 v[174:175], off
	s_mov_b32 m0, s82
	v_lshl_add_u64 v[174:175], s[46:47], 0, v[178:179]
	global_load_lds_dwordx4 v[174:175], off
	s_mov_b32 m0, s61
	v_lshl_add_u64 v[174:175], v[208:209], 0, s[20:21]
	global_load_lds_dwordx4 v[174:175], off
	s_mov_b32 m0, s62
	v_lshl_add_u64 v[174:175], v[216:217], 0, s[20:21]
	global_load_lds_dwordx4 v[174:175], off
	s_waitcnt vmcnt(8)
	s_waitcnt lgkmcnt(0)
	s_barrier
	s_setprio 1
	s_waitcnt lgkmcnt(0)
	v_mfma_f32_16x16x32_bf16 v[60:63], v[130:133], v[162:165], v[60:63]
	v_mfma_f32_16x16x32_bf16 v[56:59], v[138:141], v[162:165], v[56:59]
	v_mfma_f32_16x16x32_bf16 v[44:47], v[130:133], v[170:173], v[44:47]
	v_mfma_f32_16x16x32_bf16 v[40:43], v[138:141], v[170:173], v[40:43]
	v_mfma_f32_16x16x32_bf16 v[28:31], v[130:133], v[190:193], v[28:31]
	v_mfma_f32_16x16x32_bf16 v[24:27], v[138:141], v[190:193], v[24:27]
	v_mfma_f32_16x16x32_bf16 v[12:15], v[130:133], v[204:207], v[12:15]
	v_mfma_f32_16x16x32_bf16 v[8:11], v[138:141], v[204:207], v[8:11]
	v_mfma_f32_16x16x32_bf16 v[60:63], v[134:137], v[166:169], v[60:63]
	v_mfma_f32_16x16x32_bf16 v[56:59], v[142:145], v[166:169], v[56:59]
	v_mfma_f32_16x16x32_bf16 v[44:47], v[134:137], v[184:187], v[44:47]
	v_mfma_f32_16x16x32_bf16 v[40:43], v[142:145], v[184:187], v[40:43]
	v_mfma_f32_16x16x32_bf16 v[28:31], v[134:137], v[196:199], v[28:31]
	v_mfma_f32_16x16x32_bf16 v[24:27], v[142:145], v[196:199], v[24:27]
	v_mfma_f32_16x16x32_bf16 v[12:15], v[134:137], v[212:215], v[12:15]
	v_mfma_f32_16x16x32_bf16 v[8:11], v[142:145], v[212:215], v[8:11]
	v_mfma_f32_16x16x32_bf16 v[52:55], v[146:149], v[162:165], v[52:55]
	v_mfma_f32_16x16x32_bf16 v[48:51], v[154:157], v[162:165], v[48:51]
	v_mfma_f32_16x16x32_bf16 v[36:39], v[146:149], v[170:173], v[36:39]
	v_mfma_f32_16x16x32_bf16 v[32:35], v[154:157], v[170:173], v[32:35]
	v_mfma_f32_16x16x32_bf16 v[20:23], v[146:149], v[190:193], v[20:23]
	v_mfma_f32_16x16x32_bf16 v[16:19], v[154:157], v[190:193], v[16:19]
	v_mfma_f32_16x16x32_bf16 v[4:7], v[146:149], v[204:207], v[4:7]
	v_mfma_f32_16x16x32_bf16 v[0:3], v[154:157], v[204:207], v[0:3]
	v_mfma_f32_16x16x32_bf16 v[52:55], v[150:153], v[166:169], v[52:55]
	v_mfma_f32_16x16x32_bf16 v[48:51], v[158:161], v[166:169], v[48:51]
	v_mfma_f32_16x16x32_bf16 v[36:39], v[150:153], v[184:187], v[36:39]
	v_mfma_f32_16x16x32_bf16 v[32:35], v[158:161], v[184:187], v[32:35]
	s_setprio 2
	s_barrier
	v_mfma_f32_16x16x32_bf16 v[20:23], v[150:153], v[196:199], v[20:23]
	v_mfma_f32_16x16x32_bf16 v[16:19], v[158:161], v[196:199], v[16:19]
	v_mfma_f32_16x16x32_bf16 v[4:7], v[150:153], v[212:215], v[4:7]
	v_mfma_f32_16x16x32_bf16 v[0:3], v[158:161], v[212:215], v[0:3]
	s_setprio 0
	s_add_i32 s70, s70, 1
	s_add_u32 s44, s44, 0x100
	s_addc_u32 s45, s45, 0
	s_add_u32 s83, s83, 0x100
	s_addc_u32 s84, s84, 0
	s_cmp_gt_u32 s85, 29
	s_cbranch_scc0 .LBB0_698
	s_lshl_b32 s29, s41, 12
	s_and_b32 s29, s29, 0x1000
	s_add_i32 s29, s29, 0
	v_mbcnt_lo_u32_b32 v128, -1, 0
	v_mbcnt_hi_u32_b32 v128, -1, v128
	s_add_i32 s29, s29, s63
	v_lshlrev_b32_e32 v128, 4, v128
	s_add_i32 s29, s29, 0x20400
	v_and_b32_e32 v128, 0xf0, v128
	v_add_u32_e32 v128, s29, v128
	ds_read2_b32 v[214:215], v128 offset0:3 offset1:67
	ds_read2_b32 v[206:207], v128 offset0:131 offset1:195
	v_add_u32_e32 v128, 12, v128
	ds_read2st64_b32 v[196:197], v128 offset0:8 offset1:9
	ds_read2st64_b32 v[190:191], v128 offset0:10 offset1:11
	s_and_b64 vcc, exec, s[22:23]
	s_waitcnt lgkmcnt(0)
	v_mov_b32_e32 v210, v215
	v_mov_b32_e32 v202, v207
	v_mov_b32_e32 v194, v197
	v_mov_b32_e32 v188, v191
	s_cbranch_vccz .LBB0_703
	s_barrier

.LBB0_783:
	s_ashr_i32 s23, s22, 31
	s_lshl_b64 s[26:27], s[22:23], 19
	s_add_u32 s26, s43, s26
	s_addc_u32 s27, s44, s27
	s_and_b64 s[28:29], s[4:5], exec
	s_cselect_b32 s23, s27, s37
	s_cselect_b32 s31, s26, s36
	s_ashr_i32 s25, s24, 31
	s_lshl_b64 s[28:29], s[24:25], 19
	s_add_u32 s28, s45, s28
	s_addc_u32 s29, s46, s29
	s_and_b64 s[40:41], s[4:5], exec
	s_cselect_b32 s25, s29, s39
	s_cselect_b32 s62, s28, s38
	s_add_u32 s36, s36, 0x40080
	s_addc_u32 s37, s37, 0
	s_add_u32 s63, s38, 0x100
	s_addc_u32 s64, s39, 0
	s_mov_b32 s65, -2
	ds_read_b128 v[144:147], v163
	ds_read_b128 v[148:151], v163 offset:1024
	ds_read_b128 v[152:155], v163 offset:2048
	ds_read_b128 v[156:159], v163 offset:3072
	ds_read_b128 v[168:171], v164
	ds_read_b128 v[172:175], v164 offset:1024
	ds_read_b128 v[176:179], v164 offset:2048
	ds_read_b128 v[180:183], v164 offset:3072
	s_add_u32 s38, s36, 0xfffc0080
	s_addc_u32 s39, s37, -1
	s_cmp_eq_u32 s65, 12
	s_cselect_b32 s41, s23, s39
	s_cselect_b32 s40, s31, s38
	s_cselect_b32 s39, s25, s64
	s_cselect_b32 s38, s62, s63
	v_lshl_add_u64 v[160:161], s[36:37], 0, v[136:137]
	s_add_i32 m0, s50, 0xc000
	ds_read_b128 v[184:187], v165
	ds_read_b128 v[188:191], v165 offset:1024
	ds_read_b128 v[192:195], v165 offset:2048
	ds_read_b128 v[196:199], v165 offset:3072
	ds_read_b128 v[200:203], v165 offset:4096
	ds_read_b128 v[204:207], v165 offset:5120
	ds_read_b128 v[208:211], v165 offset:6144
	ds_read_b128 v[212:215], v165 offset:7168
	global_load_lds_dwordx4 v[160:161], off
	s_add_i32 m0, s50, 0xe000
	v_lshl_add_u64 v[160:161], s[36:37], 0, v[138:139]
	global_load_lds_dwordx4 v[160:161], off
	s_waitcnt vmcnt(8)
	s_waitcnt lgkmcnt(0)
	s_barrier
	s_setprio 1
	s_waitcnt lgkmcnt(0)
	v_mfma_f32_16x16x32_bf16 v[124:127], v[144:147], v[184:187], 0
	v_mfma_f32_16x16x32_bf16 v[120:123], v[152:155], v[184:187], 0
	v_mfma_f32_16x16x32_bf16 v[108:111], v[144:147], v[192:195], 0
	v_mfma_f32_16x16x32_bf16 v[104:107], v[152:155], v[192:195], 0
	v_mfma_f32_16x16x32_bf16 v[92:95], v[144:147], v[200:203], 0
	v_mfma_f32_16x16x32_bf16 v[88:91], v[152:155], v[200:203], 0
	v_mfma_f32_16x16x32_bf16 v[76:79], v[144:147], v[208:211], 0
	v_mfma_f32_16x16x32_bf16 v[72:75], v[152:155], v[208:211], 0
	v_mfma_f32_16x16x32_bf16 v[124:127], v[148:151], v[188:191], v[124:127]
	v_mfma_f32_16x16x32_bf16 v[120:123], v[156:159], v[188:191], v[120:123]
	v_mfma_f32_16x16x32_bf16 v[108:111], v[148:151], v[196:199], v[108:111]
	v_mfma_f32_16x16x32_bf16 v[104:107], v[156:159], v[196:199], v[104:107]
	v_mfma_f32_16x16x32_bf16 v[92:95], v[148:151], v[204:207], v[92:95]
	v_mfma_f32_16x16x32_bf16 v[88:91], v[156:159], v[204:207], v[88:91]
	v_mfma_f32_16x16x32_bf16 v[76:79], v[148:151], v[212:215], v[76:79]
	v_mfma_f32_16x16x32_bf16 v[72:75], v[156:159], v[212:215], v[72:75]
	v_mfma_f32_16x16x32_bf16 v[116:119], v[168:171], v[184:187], 0
	v_mfma_f32_16x16x32_bf16 v[112:115], v[176:179], v[184:187], 0
	v_mfma_f32_16x16x32_bf16 v[100:103], v[168:171], v[192:195], 0
	v_mfma_f32_16x16x32_bf16 v[96:99], v[176:179], v[192:195], 0
	v_mfma_f32_16x16x32_bf16 v[84:87], v[168:171], v[200:203], 0
	v_mfma_f32_16x16x32_bf16 v[80:83], v[176:179], v[200:203], 0
	v_mfma_f32_16x16x32_bf16 v[68:71], v[168:171], v[208:211], 0
	v_mfma_f32_16x16x32_bf16 v[64:67], v[176:179], v[208:211], 0
	v_mfma_f32_16x16x32_bf16 v[116:119], v[172:175], v[188:191], v[116:119]
	v_mfma_f32_16x16x32_bf16 v[112:115], v[180:183], v[188:191], v[112:115]
	v_mfma_f32_16x16x32_bf16 v[100:103], v[172:175], v[196:199], v[100:103]
	v_mfma_f32_16x16x32_bf16 v[96:99], v[180:183], v[196:199], v[96:99]
	s_setprio 2
	s_barrier
	v_mfma_f32_16x16x32_bf16 v[84:87], v[172:175], v[204:207], v[84:87]
	v_mfma_f32_16x16x32_bf16 v[80:83], v[180:183], v[204:207], v[80:83]
	v_mfma_f32_16x16x32_bf16 v[68:71], v[172:175], v[212:215], v[68:71]
	v_mfma_f32_16x16x32_bf16 v[64:67], v[180:183], v[212:215], v[64:67]
	s_setprio 0
	s_add_i32 s66, s59, s47
	v_lshl_add_u64 v[160:161], s[38:39], 0, v[132:133]
	s_mov_b32 m0, s66
	ds_read_b128 v[184:187], v165 offset:16384
	ds_read_b128 v[188:191], v165 offset:17408
	ds_read_b128 v[192:195], v165 offset:18432
	ds_read_b128 v[196:199], v165 offset:19456
	ds_read_b128 v[200:203], v165 offset:20480
	ds_read_b128 v[204:207], v165 offset:21504
	ds_read_b128 v[208:211], v165 offset:22528
	ds_read_b128 v[212:215], v165 offset:23552
	global_load_lds_dwordx4 v[160:161], off
	s_add_i32 m0, s66, 0x2000
	s_add_u32 s66, s38, 0x40000
	v_lshl_add_u64 v[216:217], s[38:39], 0, v[128:129]
	s_addc_u32 s67, s39, 0
	s_add_i32 s68, s60, s47
	global_load_lds_dwordx4 v[216:217], off
	v_lshl_add_u64 v[218:219], s[66:67], 0, v[132:133]
	s_mov_b32 m0, s68
	v_lshl_add_u64 v[220:221], s[40:41], 0, v[130:131]
	global_load_lds_dwordx4 v[218:219], off
	s_add_i32 m0, s68, 0x2000
	v_lshl_add_u64 v[218:219], s[66:67], 0, v[128:129]
	global_load_lds_dwordx4 v[218:219], off
	s_mov_b32 m0, s50
	v_lshl_add_u64 v[218:219], s[40:41], 0, v[134:135]
	global_load_lds_dwordx4 v[218:219], off
	s_mov_b32 m0, s51
	s_nop 0
	global_load_lds_dwordx4 v[220:221], off
	s_waitcnt vmcnt(8)
	s_waitcnt lgkmcnt(0)
	s_barrier
	s_setprio 1
	s_waitcnt lgkmcnt(0)
	v_mfma_f32_16x16x32_bf16 v[60:63], v[144:147], v[184:187], 0
	v_mfma_f32_16x16x32_bf16 v[56:59], v[152:155], v[184:187], 0
	v_mfma_f32_16x16x32_bf16 v[44:47], v[144:147], v[192:195], 0
	v_mfma_f32_16x16x32_bf16 v[40:43], v[152:155], v[192:195], 0
	v_mfma_f32_16x16x32_bf16 v[28:31], v[144:147], v[200:203], 0
	v_mfma_f32_16x16x32_bf16 v[24:27], v[152:155], v[200:203], 0
	v_mfma_f32_16x16x32_bf16 v[12:15], v[144:147], v[208:211], 0
	v_mfma_f32_16x16x32_bf16 v[8:11], v[152:155], v[208:211], 0
	v_mfma_f32_16x16x32_bf16 v[60:63], v[148:151], v[188:191], v[60:63]
	v_mfma_f32_16x16x32_bf16 v[56:59], v[156:159], v[188:191], v[56:59]
	v_mfma_f32_16x16x32_bf16 v[44:47], v[148:151], v[196:199], v[44:47]
	v_mfma_f32_16x16x32_bf16 v[40:43], v[156:159], v[196:199], v[40:43]
	v_mfma_f32_16x16x32_bf16 v[28:31], v[148:151], v[204:207], v[28:31]
	v_mfma_f32_16x16x32_bf16 v[24:27], v[156:159], v[204:207], v[24:27]
	v_mfma_f32_16x16x32_bf16 v[12:15], v[148:151], v[212:215], v[12:15]
	v_mfma_f32_16x16x32_bf16 v[8:11], v[156:159], v[212:215], v[8:11]
	v_mfma_f32_16x16x32_bf16 v[52:55], v[168:171], v[184:187], 0
	v_mfma_f32_16x16x32_bf16 v[48:51], v[176:179], v[184:187], 0
	v_mfma_f32_16x16x32_bf16 v[36:39], v[168:171], v[192:195], 0
	v_mfma_f32_16x16x32_bf16 v[32:35], v[176:179], v[192:195], 0
	v_mfma_f32_16x16x32_bf16 v[20:23], v[168:171], v[200:203], 0
	v_mfma_f32_16x16x32_bf16 v[16:19], v[176:179], v[200:203], 0
	v_mfma_f32_16x16x32_bf16 v[4:7], v[168:171], v[208:211], 0
	v_mfma_f32_16x16x32_bf16 v[0:3], v[176:179], v[208:211], 0
	v_mfma_f32_16x16x32_bf16 v[52:55], v[172:175], v[188:191], v[52:55]
	v_mfma_f32_16x16x32_bf16 v[48:51], v[180:183], v[188:191], v[48:51]
	v_mfma_f32_16x16x32_bf16 v[36:39], v[172:175], v[196:199], v[36:39]
	v_mfma_f32_16x16x32_bf16 v[32:35], v[180:183], v[196:199], v[32:35]
	s_setprio 2
	s_barrier
	v_mfma_f32_16x16x32_bf16 v[20:23], v[172:175], v[204:207], v[20:23]
	v_mfma_f32_16x16x32_bf16 v[16:19], v[180:183], v[204:207], v[16:19]
	v_mfma_f32_16x16x32_bf16 v[4:7], v[172:175], v[212:215], v[4:7]
	v_mfma_f32_16x16x32_bf16 v[0:3], v[180:183], v[212:215], v[0:3]
	s_setprio 0
	s_add_i32 s66, 0, 0x18000
	s_add_i32 s67, 0, 0x1c000
	v_add_u32_e32 v156, s66, v162
	v_add_u32_e32 v167, s67, v162
	ds_read_b128 v[144:147], v156
	ds_read_b128 v[148:151], v156 offset:1024
	ds_read_b128 v[152:155], v156 offset:2048
	ds_read_b128 v[156:159], v156 offset:3072
	ds_read_b128 v[168:171], v167
	ds_read_b128 v[172:175], v167 offset:1024
	ds_read_b128 v[176:179], v167 offset:2048
	ds_read_b128 v[180:183], v167 offset:3072
	s_add_u32 s40, s40, 0x40000
	s_addc_u32 s41, s41, 0
	s_mov_b32 m0, s54
	v_lshl_add_u64 v[222:223], s[40:41], 0, v[134:135]
	ds_read_b128 v[184:187], v165 offset:32768
	ds_read_b128 v[188:191], v165 offset:33792
	ds_read_b128 v[192:195], v165 offset:34816
	ds_read_b128 v[196:199], v165 offset:35840
	ds_read_b128 v[200:203], v165 offset:36864
	ds_read_b128 v[204:207], v165 offset:37888
	ds_read_b128 v[208:211], v165 offset:38912
	ds_read_b128 v[212:215], v165 offset:39936
	global_load_lds_dwordx4 v[222:223], off
	s_mov_b32 m0, s55
	v_lshl_add_u64 v[222:223], s[40:41], 0, v[130:131]
	global_load_lds_dwordx4 v[222:223], off
	s_waitcnt vmcnt(8)
	s_waitcnt lgkmcnt(0)
	s_barrier
	s_setprio 1
	s_waitcnt lgkmcnt(0)
	v_mfma_f32_16x16x32_bf16 v[124:127], v[144:147], v[184:187], v[124:127]
	v_mfma_f32_16x16x32_bf16 v[120:123], v[152:155], v[184:187], v[120:123]
	v_mfma_f32_16x16x32_bf16 v[108:111], v[144:147], v[192:195], v[108:111]
	v_mfma_f32_16x16x32_bf16 v[104:107], v[152:155], v[192:195], v[104:107]
	v_mfma_f32_16x16x32_bf16 v[92:95], v[144:147], v[200:203], v[92:95]
	v_mfma_f32_16x16x32_bf16 v[88:91], v[152:155], v[200:203], v[88:91]
	v_mfma_f32_16x16x32_bf16 v[76:79], v[144:147], v[208:211], v[76:79]
	v_mfma_f32_16x16x32_bf16 v[72:75], v[152:155], v[208:211], v[72:75]
	v_mfma_f32_16x16x32_bf16 v[124:127], v[148:151], v[188:191], v[124:127]
	v_mfma_f32_16x16x32_bf16 v[120:123], v[156:159], v[188:191], v[120:123]
	v_mfma_f32_16x16x32_bf16 v[108:111], v[148:151], v[196:199], v[108:111]
	v_mfma_f32_16x16x32_bf16 v[104:107], v[156:159], v[196:199], v[104:107]
	v_mfma_f32_16x16x32_bf16 v[92:95], v[148:151], v[204:207], v[92:95]
	v_mfma_f32_16x16x32_bf16 v[88:91], v[156:159], v[204:207], v[88:91]
	v_mfma_f32_16x16x32_bf16 v[76:79], v[148:151], v[212:215], v[76:79]
	v_mfma_f32_16x16x32_bf16 v[72:75], v[156:159], v[212:215], v[72:75]
	v_mfma_f32_16x16x32_bf16 v[116:119], v[168:171], v[184:187], v[116:119]
	v_mfma_f32_16x16x32_bf16 v[112:115], v[176:179], v[184:187], v[112:115]
	v_mfma_f32_16x16x32_bf16 v[100:103], v[168:171], v[192:195], v[100:103]
	v_mfma_f32_16x16x32_bf16 v[96:99], v[176:179], v[192:195], v[96:99]
	v_mfma_f32_16x16x32_bf16 v[84:87], v[168:171], v[200:203], v[84:87]
	v_mfma_f32_16x16x32_bf16 v[80:83], v[176:179], v[200:203], v[80:83]
	v_mfma_f32_16x16x32_bf16 v[68:71], v[168:171], v[208:211], v[68:71]
	v_mfma_f32_16x16x32_bf16 v[64:67], v[176:179], v[208:211], v[64:67]
	v_mfma_f32_16x16x32_bf16 v[116:119], v[172:175], v[188:191], v[116:119]
	v_mfma_f32_16x16x32_bf16 v[112:115], v[180:183], v[188:191], v[112:115]
	v_mfma_f32_16x16x32_bf16 v[100:103], v[172:175], v[196:199], v[100:103]
	v_mfma_f32_16x16x32_bf16 v[96:99], v[180:183], v[196:199], v[96:99]
	s_setprio 2
	s_barrier
	v_mfma_f32_16x16x32_bf16 v[84:87], v[172:175], v[204:207], v[84:87]
	v_mfma_f32_16x16x32_bf16 v[80:83], v[180:183], v[204:207], v[80:83]
	v_mfma_f32_16x16x32_bf16 v[68:71], v[172:175], v[212:215], v[68:71]
	v_mfma_f32_16x16x32_bf16 v[64:67], v[180:183], v[212:215], v[64:67]
	s_setprio 0
	s_add_i32 s40, s66, s47
	v_lshl_add_u64 v[160:161], v[160:161], 0, s[16:17]
	s_mov_b32 m0, s40
	ds_read_b128 v[184:187], v165 offset:49152
	ds_read_b128 v[188:191], v165 offset:50176
	ds_read_b128 v[192:195], v165 offset:51200
	ds_read_b128 v[196:199], v165 offset:52224
	ds_read_b128 v[200:203], v165 offset:53248
	ds_read_b128 v[204:207], v165 offset:54272
	ds_read_b128 v[208:211], v165 offset:55296
	ds_read_b128 v[212:215], v165 offset:56320
	global_load_lds_dwordx4 v[160:161], off
	s_add_i32 m0, s40, 0x2000
	s_add_u32 s38, s38, 0x40080
	v_lshl_add_u64 v[160:161], v[216:217], 0, s[16:17]
	s_addc_u32 s39, s39, 0
	s_add_i32 s40, s67, s47
	global_load_lds_dwordx4 v[160:161], off
	s_mov_b32 m0, s40
	v_lshl_add_u64 v[160:161], s[38:39], 0, v[132:133]
	global_load_lds_dwordx4 v[160:161], off
	s_add_i32 m0, s40, 0x2000
	v_lshl_add_u64 v[160:161], s[38:39], 0, v[128:129]
	global_load_lds_dwordx4 v[160:161], off
	s_mov_b32 m0, s57
	v_lshl_add_u64 v[160:161], v[218:219], 0, s[16:17]
	global_load_lds_dwordx4 v[160:161], off
	s_mov_b32 m0, s58
	v_lshl_add_u64 v[160:161], v[220:221], 0, s[16:17]
	global_load_lds_dwordx4 v[160:161], off
	s_waitcnt vmcnt(8)
	s_waitcnt lgkmcnt(0)
	s_barrier
	s_setprio 1
	s_waitcnt lgkmcnt(0)
	v_mfma_f32_16x16x32_bf16 v[60:63], v[144:147], v[184:187], v[60:63]
	v_mfma_f32_16x16x32_bf16 v[56:59], v[152:155], v[184:187], v[56:59]
	v_mfma_f32_16x16x32_bf16 v[44:47], v[144:147], v[192:195], v[44:47]
	v_mfma_f32_16x16x32_bf16 v[40:43], v[152:155], v[192:195], v[40:43]
	v_mfma_f32_16x16x32_bf16 v[28:31], v[144:147], v[200:203], v[28:31]
	v_mfma_f32_16x16x32_bf16 v[24:27], v[152:155], v[200:203], v[24:27]
	v_mfma_f32_16x16x32_bf16 v[12:15], v[144:147], v[208:211], v[12:15]
	v_mfma_f32_16x16x32_bf16 v[8:11], v[152:155], v[208:211], v[8:11]
	v_mfma_f32_16x16x32_bf16 v[60:63], v[148:151], v[188:191], v[60:63]
	v_mfma_f32_16x16x32_bf16 v[56:59], v[156:159], v[188:191], v[56:59]
	v_mfma_f32_16x16x32_bf16 v[44:47], v[148:151], v[196:199], v[44:47]
	v_mfma_f32_16x16x32_bf16 v[40:43], v[156:159], v[196:199], v[40:43]
	v_mfma_f32_16x16x32_bf16 v[28:31], v[148:151], v[204:207], v[28:31]
	v_mfma_f32_16x16x32_bf16 v[24:27], v[156:159], v[204:207], v[24:27]
	v_mfma_f32_16x16x32_bf16 v[12:15], v[148:151], v[212:215], v[12:15]
	v_mfma_f32_16x16x32_bf16 v[8:11], v[156:159], v[212:215], v[8:11]
	v_mfma_f32_16x16x32_bf16 v[52:55], v[168:171], v[184:187], v[52:55]
	v_mfma_f32_16x16x32_bf16 v[48:51], v[176:179], v[184:187], v[48:51]
	v_mfma_f32_16x16x32_bf16 v[36:39], v[168:171], v[192:195], v[36:39]
	v_mfma_f32_16x16x32_bf16 v[32:35], v[176:179], v[192:195], v[32:35]
	v_mfma_f32_16x16x32_bf16 v[20:23], v[168:171], v[200:203], v[20:23]
	v_mfma_f32_16x16x32_bf16 v[16:19], v[176:179], v[200:203], v[16:19]
	v_mfma_f32_16x16x32_bf16 v[4:7], v[168:171], v[208:211], v[4:7]
	v_mfma_f32_16x16x32_bf16 v[0:3], v[176:179], v[208:211], v[0:3]
	v_mfma_f32_16x16x32_bf16 v[52:55], v[172:175], v[188:191], v[52:55]
	v_mfma_f32_16x16x32_bf16 v[48:51], v[180:183], v[188:191], v[48:51]
	v_mfma_f32_16x16x32_bf16 v[36:39], v[172:175], v[196:199], v[36:39]
	v_mfma_f32_16x16x32_bf16 v[32:35], v[180:183], v[196:199], v[32:35]
	s_setprio 2
	s_barrier
	v_mfma_f32_16x16x32_bf16 v[20:23], v[172:175], v[204:207], v[20:23]
	v_mfma_f32_16x16x32_bf16 v[16:19], v[180:183], v[204:207], v[16:19]
	v_mfma_f32_16x16x32_bf16 v[4:7], v[172:175], v[212:215], v[4:7]
	v_mfma_f32_16x16x32_bf16 v[0:3], v[180:183], v[212:215], v[0:3]
	s_setprio 0
	s_add_i32 s65, s65, 2
	s_add_u32 s36, s36, 0x100
	s_addc_u32 s37, s37, 0
	s_add_u32 s63, s63, 0x100
	s_addc_u32 s64, s64, 0
	s_cmp_gt_u32 s65, 13
.LBB0_784:
	ds_read_b128 v[144:147], v163
	ds_read_b128 v[148:151], v163 offset:1024
	ds_read_b128 v[152:155], v163 offset:2048
	ds_read_b128 v[156:159], v163 offset:3072
	ds_read_b128 v[168:171], v164
	ds_read_b128 v[172:175], v164 offset:1024
	ds_read_b128 v[176:179], v164 offset:2048
	ds_read_b128 v[180:183], v164 offset:3072
	s_add_u32 s38, s36, 0xfffc0080
	s_addc_u32 s39, s37, -1
	s_cmp_eq_u32 s65, 12
	s_cselect_b32 s41, s23, s39
	s_cselect_b32 s40, s31, s38
	s_cselect_b32 s39, s25, s64
	s_cselect_b32 s38, s62, s63
	v_lshl_add_u64 v[160:161], s[36:37], 0, v[136:137]
	s_add_i32 m0, s50, 0xc000
	ds_read_b128 v[184:187], v165
	ds_read_b128 v[188:191], v165 offset:1024
	ds_read_b128 v[192:195], v165 offset:2048
	ds_read_b128 v[196:199], v165 offset:3072
	ds_read_b128 v[200:203], v165 offset:4096
	ds_read_b128 v[204:207], v165 offset:5120
	ds_read_b128 v[208:211], v165 offset:6144
	ds_read_b128 v[212:215], v165 offset:7168
	global_load_lds_dwordx4 v[160:161], off
	s_add_i32 m0, s50, 0xe000
	v_lshl_add_u64 v[160:161], s[36:37], 0, v[138:139]
	global_load_lds_dwordx4 v[160:161], off
	s_waitcnt vmcnt(8)
	s_waitcnt lgkmcnt(0)
	s_barrier
	s_setprio 1
	s_waitcnt lgkmcnt(0)
	v_mfma_f32_16x16x32_bf16 v[124:127], v[144:147], v[184:187], v[124:127]
	v_mfma_f32_16x16x32_bf16 v[120:123], v[152:155], v[184:187], v[120:123]
	v_mfma_f32_16x16x32_bf16 v[108:111], v[144:147], v[192:195], v[108:111]
	v_mfma_f32_16x16x32_bf16 v[104:107], v[152:155], v[192:195], v[104:107]
	v_mfma_f32_16x16x32_bf16 v[92:95], v[144:147], v[200:203], v[92:95]
	v_mfma_f32_16x16x32_bf16 v[88:91], v[152:155], v[200:203], v[88:91]
	v_mfma_f32_16x16x32_bf16 v[76:79], v[144:147], v[208:211], v[76:79]
	v_mfma_f32_16x16x32_bf16 v[72:75], v[152:155], v[208:211], v[72:75]
	v_mfma_f32_16x16x32_bf16 v[124:127], v[148:151], v[188:191], v[124:127]
	v_mfma_f32_16x16x32_bf16 v[120:123], v[156:159], v[188:191], v[120:123]
	v_mfma_f32_16x16x32_bf16 v[108:111], v[148:151], v[196:199], v[108:111]
	v_mfma_f32_16x16x32_bf16 v[104:107], v[156:159], v[196:199], v[104:107]
	v_mfma_f32_16x16x32_bf16 v[92:95], v[148:151], v[204:207], v[92:95]
	v_mfma_f32_16x16x32_bf16 v[88:91], v[156:159], v[204:207], v[88:91]
	v_mfma_f32_16x16x32_bf16 v[76:79], v[148:151], v[212:215], v[76:79]
	v_mfma_f32_16x16x32_bf16 v[72:75], v[156:159], v[212:215], v[72:75]
	v_mfma_f32_16x16x32_bf16 v[116:119], v[168:171], v[184:187], v[116:119]
	v_mfma_f32_16x16x32_bf16 v[112:115], v[176:179], v[184:187], v[112:115]
	v_mfma_f32_16x16x32_bf16 v[100:103], v[168:171], v[192:195], v[100:103]
	v_mfma_f32_16x16x32_bf16 v[96:99], v[176:179], v[192:195], v[96:99]
	v_mfma_f32_16x16x32_bf16 v[84:87], v[168:171], v[200:203], v[84:87]
	v_mfma_f32_16x16x32_bf16 v[80:83], v[176:179], v[200:203], v[80:83]
	v_mfma_f32_16x16x32_bf16 v[68:71], v[168:171], v[208:211], v[68:71]
	v_mfma_f32_16x16x32_bf16 v[64:67], v[176:179], v[208:211], v[64:67]
	v_mfma_f32_16x16x32_bf16 v[116:119], v[172:175], v[188:191], v[116:119]
	v_mfma_f32_16x16x32_bf16 v[112:115], v[180:183], v[188:191], v[112:115]
	v_mfma_f32_16x16x32_bf16 v[100:103], v[172:175], v[196:199], v[100:103]
	v_mfma_f32_16x16x32_bf16 v[96:99], v[180:183], v[196:199], v[96:99]
	s_setprio 2
	s_barrier
	v_mfma_f32_16x16x32_bf16 v[84:87], v[172:175], v[204:207], v[84:87]
	v_mfma_f32_16x16x32_bf16 v[80:83], v[180:183], v[204:207], v[80:83]
	v_mfma_f32_16x16x32_bf16 v[68:71], v[172:175], v[212:215], v[68:71]
	v_mfma_f32_16x16x32_bf16 v[64:67], v[180:183], v[212:215], v[64:67]
	s_setprio 0
	s_add_i32 s66, s59, s47
	v_lshl_add_u64 v[160:161], s[38:39], 0, v[132:133]
	s_mov_b32 m0, s66
	ds_read_b128 v[184:187], v165 offset:16384
	ds_read_b128 v[188:191], v165 offset:17408
	ds_read_b128 v[192:195], v165 offset:18432
	ds_read_b128 v[196:199], v165 offset:19456
	ds_read_b128 v[200:203], v165 offset:20480
	ds_read_b128 v[204:207], v165 offset:21504
	ds_read_b128 v[208:211], v165 offset:22528
	ds_read_b128 v[212:215], v165 offset:23552
	global_load_lds_dwordx4 v[160:161], off
	s_add_i32 m0, s66, 0x2000
	s_add_u32 s66, s38, 0x40000
	v_lshl_add_u64 v[216:217], s[38:39], 0, v[128:129]
	s_addc_u32 s67, s39, 0
	s_add_i32 s68, s60, s47
	global_load_lds_dwordx4 v[216:217], off
	v_lshl_add_u64 v[218:219], s[66:67], 0, v[132:133]
	s_mov_b32 m0, s68
	v_lshl_add_u64 v[220:221], s[40:41], 0, v[130:131]
	global_load_lds_dwordx4 v[218:219], off
	s_add_i32 m0, s68, 0x2000
	v_lshl_add_u64 v[218:219], s[66:67], 0, v[128:129]
	global_load_lds_dwordx4 v[218:219], off
	s_mov_b32 m0, s50
	v_lshl_add_u64 v[218:219], s[40:41], 0, v[134:135]
	global_load_lds_dwordx4 v[218:219], off
	s_mov_b32 m0, s51
	s_nop 0
	global_load_lds_dwordx4 v[220:221], off
	s_waitcnt vmcnt(8)
	s_waitcnt lgkmcnt(0)
	s_barrier
	s_setprio 1
	s_waitcnt lgkmcnt(0)
	v_mfma_f32_16x16x32_bf16 v[60:63], v[144:147], v[184:187], v[60:63]
	v_mfma_f32_16x16x32_bf16 v[56:59], v[152:155], v[184:187], v[56:59]
	v_mfma_f32_16x16x32_bf16 v[44:47], v[144:147], v[192:195], v[44:47]
	v_mfma_f32_16x16x32_bf16 v[40:43], v[152:155], v[192:195], v[40:43]
	v_mfma_f32_16x16x32_bf16 v[28:31], v[144:147], v[200:203], v[28:31]
	v_mfma_f32_16x16x32_bf16 v[24:27], v[152:155], v[200:203], v[24:27]
	v_mfma_f32_16x16x32_bf16 v[12:15], v[144:147], v[208:211], v[12:15]
	v_mfma_f32_16x16x32_bf16 v[8:11], v[152:155], v[208:211], v[8:11]
	v_mfma_f32_16x16x32_bf16 v[60:63], v[148:151], v[188:191], v[60:63]
	v_mfma_f32_16x16x32_bf16 v[56:59], v[156:159], v[188:191], v[56:59]
	v_mfma_f32_16x16x32_bf16 v[44:47], v[148:151], v[196:199], v[44:47]
	v_mfma_f32_16x16x32_bf16 v[40:43], v[156:159], v[196:199], v[40:43]
	v_mfma_f32_16x16x32_bf16 v[28:31], v[148:151], v[204:207], v[28:31]
	v_mfma_f32_16x16x32_bf16 v[24:27], v[156:159], v[204:207], v[24:27]
	v_mfma_f32_16x16x32_bf16 v[12:15], v[148:151], v[212:215], v[12:15]
	v_mfma_f32_16x16x32_bf16 v[8:11], v[156:159], v[212:215], v[8:11]
	v_mfma_f32_16x16x32_bf16 v[52:55], v[168:171], v[184:187], v[52:55]
	v_mfma_f32_16x16x32_bf16 v[48:51], v[176:179], v[184:187], v[48:51]
	v_mfma_f32_16x16x32_bf16 v[36:39], v[168:171], v[192:195], v[36:39]
	v_mfma_f32_16x16x32_bf16 v[32:35], v[176:179], v[192:195], v[32:35]
	v_mfma_f32_16x16x32_bf16 v[20:23], v[168:171], v[200:203], v[20:23]
	v_mfma_f32_16x16x32_bf16 v[16:19], v[176:179], v[200:203], v[16:19]
	v_mfma_f32_16x16x32_bf16 v[4:7], v[168:171], v[208:211], v[4:7]
	v_mfma_f32_16x16x32_bf16 v[0:3], v[176:179], v[208:211], v[0:3]
	v_mfma_f32_16x16x32_bf16 v[52:55], v[172:175], v[188:191], v[52:55]
	v_mfma_f32_16x16x32_bf16 v[48:51], v[180:183], v[188:191], v[48:51]
	v_mfma_f32_16x16x32_bf16 v[36:39], v[172:175], v[196:199], v[36:39]
	v_mfma_f32_16x16x32_bf16 v[32:35], v[180:183], v[196:199], v[32:35]
	s_setprio 2
	s_barrier
	v_mfma_f32_16x16x32_bf16 v[20:23], v[172:175], v[204:207], v[20:23]
	v_mfma_f32_16x16x32_bf16 v[16:19], v[180:183], v[204:207], v[16:19]
	v_mfma_f32_16x16x32_bf16 v[4:7], v[172:175], v[212:215], v[4:7]
	v_mfma_f32_16x16x32_bf16 v[0:3], v[180:183], v[212:215], v[0:3]
	s_setprio 0
	s_add_i32 s66, 0, 0x18000
	s_add_i32 s67, 0, 0x1c000
	v_add_u32_e32 v156, s66, v162
	v_add_u32_e32 v167, s67, v162
	ds_read_b128 v[144:147], v156
	ds_read_b128 v[148:151], v156 offset:1024
	ds_read_b128 v[152:155], v156 offset:2048
	ds_read_b128 v[156:159], v156 offset:3072
	ds_read_b128 v[168:171], v167
	ds_read_b128 v[172:175], v167 offset:1024
	ds_read_b128 v[176:179], v167 offset:2048
	ds_read_b128 v[180:183], v167 offset:3072
	s_add_u32 s40, s40, 0x40000
	s_addc_u32 s41, s41, 0
	s_mov_b32 m0, s54
	v_lshl_add_u64 v[222:223], s[40:41], 0, v[134:135]
	ds_read_b128 v[184:187], v165 offset:32768
	ds_read_b128 v[188:191], v165 offset:33792
	ds_read_b128 v[192:195], v165 offset:34816
	ds_read_b128 v[196:199], v165 offset:35840
	ds_read_b128 v[200:203], v165 offset:36864
	ds_read_b128 v[204:207], v165 offset:37888
	ds_read_b128 v[208:211], v165 offset:38912
	ds_read_b128 v[212:215], v165 offset:39936
	global_load_lds_dwordx4 v[222:223], off
	s_mov_b32 m0, s55
	v_lshl_add_u64 v[222:223], s[40:41], 0, v[130:131]
	global_load_lds_dwordx4 v[222:223], off
	s_waitcnt vmcnt(8)
	s_waitcnt lgkmcnt(0)
	s_barrier
	s_setprio 1
	s_waitcnt lgkmcnt(0)
	v_mfma_f32_16x16x32_bf16 v[124:127], v[144:147], v[184:187], v[124:127]
	v_mfma_f32_16x16x32_bf16 v[120:123], v[152:155], v[184:187], v[120:123]
	v_mfma_f32_16x16x32_bf16 v[108:111], v[144:147], v[192:195], v[108:111]
	v_mfma_f32_16x16x32_bf16 v[104:107], v[152:155], v[192:195], v[104:107]
	v_mfma_f32_16x16x32_bf16 v[92:95], v[144:147], v[200:203], v[92:95]
	v_mfma_f32_16x16x32_bf16 v[88:91], v[152:155], v[200:203], v[88:91]
	v_mfma_f32_16x16x32_bf16 v[76:79], v[144:147], v[208:211], v[76:79]
	v_mfma_f32_16x16x32_bf16 v[72:75], v[152:155], v[208:211], v[72:75]
	v_mfma_f32_16x16x32_bf16 v[124:127], v[148:151], v[188:191], v[124:127]
	v_mfma_f32_16x16x32_bf16 v[120:123], v[156:159], v[188:191], v[120:123]
	v_mfma_f32_16x16x32_bf16 v[108:111], v[148:151], v[196:199], v[108:111]
	v_mfma_f32_16x16x32_bf16 v[104:107], v[156:159], v[196:199], v[104:107]
	v_mfma_f32_16x16x32_bf16 v[92:95], v[148:151], v[204:207], v[92:95]
	v_mfma_f32_16x16x32_bf16 v[88:91], v[156:159], v[204:207], v[88:91]
	v_mfma_f32_16x16x32_bf16 v[76:79], v[148:151], v[212:215], v[76:79]
	v_mfma_f32_16x16x32_bf16 v[72:75], v[156:159], v[212:215], v[72:75]
	v_mfma_f32_16x16x32_bf16 v[116:119], v[168:171], v[184:187], v[116:119]
	v_mfma_f32_16x16x32_bf16 v[112:115], v[176:179], v[184:187], v[112:115]
	v_mfma_f32_16x16x32_bf16 v[100:103], v[168:171], v[192:195], v[100:103]
	v_mfma_f32_16x16x32_bf16 v[96:99], v[176:179], v[192:195], v[96:99]
	v_mfma_f32_16x16x32_bf16 v[84:87], v[168:171], v[200:203], v[84:87]
	v_mfma_f32_16x16x32_bf16 v[80:83], v[176:179], v[200:203], v[80:83]
	v_mfma_f32_16x16x32_bf16 v[68:71], v[168:171], v[208:211], v[68:71]
	v_mfma_f32_16x16x32_bf16 v[64:67], v[176:179], v[208:211], v[64:67]
	v_mfma_f32_16x16x32_bf16 v[116:119], v[172:175], v[188:191], v[116:119]
	v_mfma_f32_16x16x32_bf16 v[112:115], v[180:183], v[188:191], v[112:115]
	v_mfma_f32_16x16x32_bf16 v[100:103], v[172:175], v[196:199], v[100:103]
	v_mfma_f32_16x16x32_bf16 v[96:99], v[180:183], v[196:199], v[96:99]
	s_setprio 2
	s_barrier
	v_mfma_f32_16x16x32_bf16 v[84:87], v[172:175], v[204:207], v[84:87]
	v_mfma_f32_16x16x32_bf16 v[80:83], v[180:183], v[204:207], v[80:83]
	v_mfma_f32_16x16x32_bf16 v[68:71], v[172:175], v[212:215], v[68:71]
	v_mfma_f32_16x16x32_bf16 v[64:67], v[180:183], v[212:215], v[64:67]
	s_setprio 0
	s_add_i32 s40, s66, s47
	v_lshl_add_u64 v[160:161], v[160:161], 0, s[16:17]
	s_mov_b32 m0, s40
	ds_read_b128 v[184:187], v165 offset:49152
	ds_read_b128 v[188:191], v165 offset:50176
	ds_read_b128 v[192:195], v165 offset:51200
	ds_read_b128 v[196:199], v165 offset:52224
	ds_read_b128 v[200:203], v165 offset:53248
	ds_read_b128 v[204:207], v165 offset:54272
	ds_read_b128 v[208:211], v165 offset:55296
	ds_read_b128 v[212:215], v165 offset:56320
	global_load_lds_dwordx4 v[160:161], off
	s_add_i32 m0, s40, 0x2000
	s_add_u32 s38, s38, 0x40080
	v_lshl_add_u64 v[160:161], v[216:217], 0, s[16:17]
	s_addc_u32 s39, s39, 0
	s_add_i32 s40, s67, s47
	global_load_lds_dwordx4 v[160:161], off
	s_mov_b32 m0, s40
	v_lshl_add_u64 v[160:161], s[38:39], 0, v[132:133]
	global_load_lds_dwordx4 v[160:161], off
	s_add_i32 m0, s40, 0x2000
	v_lshl_add_u64 v[160:161], s[38:39], 0, v[128:129]
	global_load_lds_dwordx4 v[160:161], off
	s_mov_b32 m0, s57
	v_lshl_add_u64 v[160:161], v[218:219], 0, s[16:17]
	global_load_lds_dwordx4 v[160:161], off
	s_mov_b32 m0, s58
	v_lshl_add_u64 v[160:161], v[220:221], 0, s[16:17]
	global_load_lds_dwordx4 v[160:161], off
	s_waitcnt vmcnt(8)
	s_waitcnt lgkmcnt(0)
	s_barrier
	s_setprio 1
	s_waitcnt lgkmcnt(0)
	v_mfma_f32_16x16x32_bf16 v[60:63], v[144:147], v[184:187], v[60:63]
	v_mfma_f32_16x16x32_bf16 v[56:59], v[152:155], v[184:187], v[56:59]
	v_mfma_f32_16x16x32_bf16 v[44:47], v[144:147], v[192:195], v[44:47]
	v_mfma_f32_16x16x32_bf16 v[40:43], v[152:155], v[192:195], v[40:43]
	v_mfma_f32_16x16x32_bf16 v[28:31], v[144:147], v[200:203], v[28:31]
	v_mfma_f32_16x16x32_bf16 v[24:27], v[152:155], v[200:203], v[24:27]
	v_mfma_f32_16x16x32_bf16 v[12:15], v[144:147], v[208:211], v[12:15]
	v_mfma_f32_16x16x32_bf16 v[8:11], v[152:155], v[208:211], v[8:11]
	v_mfma_f32_16x16x32_bf16 v[60:63], v[148:151], v[188:191], v[60:63]
	v_mfma_f32_16x16x32_bf16 v[56:59], v[156:159], v[188:191], v[56:59]
	v_mfma_f32_16x16x32_bf16 v[44:47], v[148:151], v[196:199], v[44:47]
	v_mfma_f32_16x16x32_bf16 v[40:43], v[156:159], v[196:199], v[40:43]
	v_mfma_f32_16x16x32_bf16 v[28:31], v[148:151], v[204:207], v[28:31]
	v_mfma_f32_16x16x32_bf16 v[24:27], v[156:159], v[204:207], v[24:27]
	v_mfma_f32_16x16x32_bf16 v[12:15], v[148:151], v[212:215], v[12:15]
	v_mfma_f32_16x16x32_bf16 v[8:11], v[156:159], v[212:215], v[8:11]
	v_mfma_f32_16x16x32_bf16 v[52:55], v[168:171], v[184:187], v[52:55]
	v_mfma_f32_16x16x32_bf16 v[48:51], v[176:179], v[184:187], v[48:51]
	v_mfma_f32_16x16x32_bf16 v[36:39], v[168:171], v[192:195], v[36:39]
	v_mfma_f32_16x16x32_bf16 v[32:35], v[176:179], v[192:195], v[32:35]
	v_mfma_f32_16x16x32_bf16 v[20:23], v[168:171], v[200:203], v[20:23]
	v_mfma_f32_16x16x32_bf16 v[16:19], v[176:179], v[200:203], v[16:19]
	v_mfma_f32_16x16x32_bf16 v[4:7], v[168:171], v[208:211], v[4:7]
	v_mfma_f32_16x16x32_bf16 v[0:3], v[176:179], v[208:211], v[0:3]
	v_mfma_f32_16x16x32_bf16 v[52:55], v[172:175], v[188:191], v[52:55]
	v_mfma_f32_16x16x32_bf16 v[48:51], v[180:183], v[188:191], v[48:51]
	v_mfma_f32_16x16x32_bf16 v[36:39], v[172:175], v[196:199], v[36:39]
	v_mfma_f32_16x16x32_bf16 v[32:35], v[180:183], v[196:199], v[32:35]
	s_setprio 2
	s_barrier
	v_mfma_f32_16x16x32_bf16 v[20:23], v[172:175], v[204:207], v[20:23]
	v_mfma_f32_16x16x32_bf16 v[16:19], v[180:183], v[204:207], v[16:19]
	v_mfma_f32_16x16x32_bf16 v[4:7], v[172:175], v[212:215], v[4:7]
	v_mfma_f32_16x16x32_bf16 v[0:3], v[180:183], v[212:215], v[0:3]
	s_setprio 0
	s_add_i32 s65, s65, 2
	s_add_u32 s36, s36, 0x100
	s_addc_u32 s37, s37, 0
	s_add_u32 s63, s63, 0x100
	s_addc_u32 s64, s64, 0
	s_cmp_gt_u32 s65, 13
	s_cbranch_scc0 .LBB0_784

.LBB0_865:
	s_add_u32 s62, s28, 0x100
	s_addc_u32 s63, s29, 0
	s_mov_b32 s64, -2
	ds_read_b128 v[120:123], v233
	ds_read_b128 v[124:127], v233 offset:1024
	ds_read_b128 v[136:139], v233 offset:2048
	ds_read_b128 v[140:143], v233 offset:3072
	ds_read_b128 v[144:147], v234
	ds_read_b128 v[148:151], v234 offset:1024
	ds_read_b128 v[152:155], v234 offset:2048
	ds_read_b128 v[156:159], v234 offset:3072
	s_add_u32 s28, s26, 0x100
	s_addc_u32 s29, s27, 0
	s_cmp_eq_u32 s64, 40
	s_cselect_b32 s37, s7, s29
	s_cselect_b32 s36, s6, s28
	s_cselect_b32 s31, s25, s63
	s_cselect_b32 s30, s24, s62
	v_lshl_add_u64 v[208:209], s[26:27], 0, v[192:193]
	s_add_i32 m0, s44, 0xc000
	ds_read_b128 v[160:163], v235
	ds_read_b128 v[164:167], v235 offset:1024
	ds_read_b128 v[168:171], v235 offset:2048
	ds_read_b128 v[172:175], v235 offset:3072
	ds_read_b128 v[176:179], v235 offset:4096
	ds_read_b128 v[180:183], v235 offset:5120
	ds_read_b128 v[200:203], v235 offset:6144
	ds_read_b128 v[204:207], v235 offset:7168
	global_load_lds_dwordx4 v[208:209], off
	s_add_i32 m0, s44, 0xe000
	v_lshl_add_u64 v[208:209], s[26:27], 0, v[194:195]
	global_load_lds_dwordx4 v[208:209], off
	s_waitcnt vmcnt(8)
	s_waitcnt lgkmcnt(0)
	s_barrier
	s_setprio 1
	s_waitcnt lgkmcnt(0)
	v_mfma_f32_16x16x32_bf16 v[132:135], v[120:123], v[160:163], 0
	v_mfma_f32_16x16x32_bf16 v[128:131], v[136:139], v[160:163], 0
	v_mfma_f32_16x16x32_bf16 v[108:111], v[120:123], v[168:171], 0
	v_mfma_f32_16x16x32_bf16 v[104:107], v[136:139], v[168:171], 0
	v_mfma_f32_16x16x32_bf16 v[92:95], v[120:123], v[176:179], 0
	v_mfma_f32_16x16x32_bf16 v[88:91], v[136:139], v[176:179], 0
	v_mfma_f32_16x16x32_bf16 v[76:79], v[120:123], v[200:203], 0
	v_mfma_f32_16x16x32_bf16 v[72:75], v[136:139], v[200:203], 0
	v_mfma_f32_16x16x32_bf16 v[132:135], v[124:127], v[164:167], v[132:135]
	v_mfma_f32_16x16x32_bf16 v[128:131], v[140:143], v[164:167], v[128:131]
	v_mfma_f32_16x16x32_bf16 v[108:111], v[124:127], v[172:175], v[108:111]
	v_mfma_f32_16x16x32_bf16 v[104:107], v[140:143], v[172:175], v[104:107]
	v_mfma_f32_16x16x32_bf16 v[92:95], v[124:127], v[180:183], v[92:95]
	v_mfma_f32_16x16x32_bf16 v[88:91], v[140:143], v[180:183], v[88:91]
	v_mfma_f32_16x16x32_bf16 v[76:79], v[124:127], v[204:207], v[76:79]
	v_mfma_f32_16x16x32_bf16 v[72:75], v[140:143], v[204:207], v[72:75]
	v_mfma_f32_16x16x32_bf16 v[116:119], v[144:147], v[160:163], 0
	v_mfma_f32_16x16x32_bf16 v[112:115], v[152:155], v[160:163], 0
	v_mfma_f32_16x16x32_bf16 v[100:103], v[144:147], v[168:171], 0
	v_mfma_f32_16x16x32_bf16 v[96:99], v[152:155], v[168:171], 0
	v_mfma_f32_16x16x32_bf16 v[84:87], v[144:147], v[176:179], 0
	v_mfma_f32_16x16x32_bf16 v[80:83], v[152:155], v[176:179], 0
	v_mfma_f32_16x16x32_bf16 v[68:71], v[144:147], v[200:203], 0
	v_mfma_f32_16x16x32_bf16 v[64:67], v[152:155], v[200:203], 0
	v_mfma_f32_16x16x32_bf16 v[116:119], v[148:151], v[164:167], v[116:119]
	v_mfma_f32_16x16x32_bf16 v[112:115], v[156:159], v[164:167], v[112:115]
	v_mfma_f32_16x16x32_bf16 v[100:103], v[148:151], v[172:175], v[100:103]
	v_mfma_f32_16x16x32_bf16 v[96:99], v[156:159], v[172:175], v[96:99]
	s_setprio 2
	s_barrier
	v_mfma_f32_16x16x32_bf16 v[84:87], v[148:151], v[180:183], v[84:87]
	v_mfma_f32_16x16x32_bf16 v[80:83], v[156:159], v[180:183], v[80:83]
	v_mfma_f32_16x16x32_bf16 v[68:71], v[148:151], v[204:207], v[68:71]
	v_mfma_f32_16x16x32_bf16 v[64:67], v[156:159], v[204:207], v[64:67]
	s_setprio 0
	s_add_i32 s26, s56, s43
	v_lshl_add_u64 v[208:209], s[30:31], 0, v[186:187]
	s_mov_b32 m0, s26
	ds_read_b128 v[160:163], v235 offset:16384
	ds_read_b128 v[164:167], v235 offset:17408
	ds_read_b128 v[168:171], v235 offset:18432
	ds_read_b128 v[172:175], v235 offset:19456
	ds_read_b128 v[176:179], v235 offset:20480
	ds_read_b128 v[180:183], v235 offset:21504
	ds_read_b128 v[200:203], v235 offset:22528
	ds_read_b128 v[204:207], v235 offset:23552
	global_load_lds_dwordx4 v[208:209], off
	s_add_i32 m0, s26, 0x2000
	s_add_u32 s26, s30, 0xb0000
	v_lshl_add_u64 v[210:211], s[30:31], 0, v[190:191]
	s_addc_u32 s27, s31, 0
	s_add_i32 s65, s57, s43
	global_load_lds_dwordx4 v[210:211], off
	v_lshl_add_u64 v[212:213], s[26:27], 0, v[186:187]
	s_mov_b32 m0, s65
	v_lshl_add_u64 v[214:215], s[36:37], 0, v[188:189]
	global_load_lds_dwordx4 v[212:213], off
	s_add_i32 m0, s65, 0x2000
	v_lshl_add_u64 v[212:213], s[26:27], 0, v[190:191]
	global_load_lds_dwordx4 v[212:213], off
	s_mov_b32 m0, s44
	v_lshl_add_u64 v[212:213], s[36:37], 0, v[184:185]
	global_load_lds_dwordx4 v[212:213], off
	s_mov_b32 m0, s45
	s_nop 0
	global_load_lds_dwordx4 v[214:215], off
	s_waitcnt vmcnt(8)
	s_waitcnt lgkmcnt(0)
	s_barrier
	s_setprio 1
	s_waitcnt lgkmcnt(0)
	v_mfma_f32_16x16x32_bf16 v[60:63], v[120:123], v[160:163], 0
	v_mfma_f32_16x16x32_bf16 v[56:59], v[136:139], v[160:163], 0
	v_mfma_f32_16x16x32_bf16 v[44:47], v[120:123], v[168:171], 0
	v_mfma_f32_16x16x32_bf16 v[40:43], v[136:139], v[168:171], 0
	v_mfma_f32_16x16x32_bf16 v[28:31], v[120:123], v[176:179], 0
	v_mfma_f32_16x16x32_bf16 v[24:27], v[136:139], v[176:179], 0
	v_mfma_f32_16x16x32_bf16 v[12:15], v[120:123], v[200:203], 0
	v_mfma_f32_16x16x32_bf16 v[8:11], v[136:139], v[200:203], 0
	v_mfma_f32_16x16x32_bf16 v[60:63], v[124:127], v[164:167], v[60:63]
	v_mfma_f32_16x16x32_bf16 v[56:59], v[140:143], v[164:167], v[56:59]
	v_mfma_f32_16x16x32_bf16 v[44:47], v[124:127], v[172:175], v[44:47]
	v_mfma_f32_16x16x32_bf16 v[40:43], v[140:143], v[172:175], v[40:43]
	v_mfma_f32_16x16x32_bf16 v[28:31], v[124:127], v[180:183], v[28:31]
	v_mfma_f32_16x16x32_bf16 v[24:27], v[140:143], v[180:183], v[24:27]
	v_mfma_f32_16x16x32_bf16 v[12:15], v[124:127], v[204:207], v[12:15]
	v_mfma_f32_16x16x32_bf16 v[8:11], v[140:143], v[204:207], v[8:11]
	v_mfma_f32_16x16x32_bf16 v[52:55], v[144:147], v[160:163], 0
	v_mfma_f32_16x16x32_bf16 v[48:51], v[152:155], v[160:163], 0
	v_mfma_f32_16x16x32_bf16 v[36:39], v[144:147], v[168:171], 0
	v_mfma_f32_16x16x32_bf16 v[32:35], v[152:155], v[168:171], 0
	v_mfma_f32_16x16x32_bf16 v[20:23], v[144:147], v[176:179], 0
	v_mfma_f32_16x16x32_bf16 v[16:19], v[152:155], v[176:179], 0
	v_mfma_f32_16x16x32_bf16 v[4:7], v[144:147], v[200:203], 0
	v_mfma_f32_16x16x32_bf16 v[0:3], v[152:155], v[200:203], 0
	v_mfma_f32_16x16x32_bf16 v[52:55], v[148:151], v[164:167], v[52:55]
	v_mfma_f32_16x16x32_bf16 v[48:51], v[156:159], v[164:167], v[48:51]
	v_mfma_f32_16x16x32_bf16 v[36:39], v[148:151], v[172:175], v[36:39]
	v_mfma_f32_16x16x32_bf16 v[32:35], v[156:159], v[172:175], v[32:35]
	s_setprio 2
	s_barrier
	v_mfma_f32_16x16x32_bf16 v[20:23], v[148:151], v[180:183], v[20:23]
	v_mfma_f32_16x16x32_bf16 v[16:19], v[156:159], v[180:183], v[16:19]
	v_mfma_f32_16x16x32_bf16 v[4:7], v[148:151], v[204:207], v[4:7]
	v_mfma_f32_16x16x32_bf16 v[0:3], v[156:159], v[204:207], v[0:3]
	s_setprio 0
	s_add_i32 s65, 0, 0x18000
	s_add_i32 s66, 0, 0x1c000
	v_add_u32_e32 v140, s65, v232
	v_add_u32_e32 v156, s66, v232
	ds_read_b128 v[120:123], v140
	ds_read_b128 v[124:127], v140 offset:1024
	ds_read_b128 v[136:139], v140 offset:2048
	ds_read_b128 v[140:143], v140 offset:3072
	ds_read_b128 v[144:147], v156
	ds_read_b128 v[148:151], v156 offset:1024
	ds_read_b128 v[152:155], v156 offset:2048
	ds_read_b128 v[156:159], v156 offset:3072
	s_add_u32 s26, s36, 0xb0000
	s_addc_u32 s27, s37, 0
	s_mov_b32 m0, s46
	v_lshl_add_u64 v[216:217], s[26:27], 0, v[184:185]
	ds_read_b128 v[160:163], v235 offset:32768
	ds_read_b128 v[164:167], v235 offset:33792
	ds_read_b128 v[168:171], v235 offset:34816
	ds_read_b128 v[172:175], v235 offset:35840
	ds_read_b128 v[176:179], v235 offset:36864
	ds_read_b128 v[180:183], v235 offset:37888
	ds_read_b128 v[200:203], v235 offset:38912
	ds_read_b128 v[204:207], v235 offset:39936
	global_load_lds_dwordx4 v[216:217], off
	s_mov_b32 m0, s47
	v_lshl_add_u64 v[216:217], s[26:27], 0, v[188:189]
	global_load_lds_dwordx4 v[216:217], off
	s_waitcnt vmcnt(8)
	s_waitcnt lgkmcnt(0)
	s_barrier
	s_setprio 1
	s_waitcnt lgkmcnt(0)
	v_mfma_f32_16x16x32_bf16 v[132:135], v[120:123], v[160:163], v[132:135]
	v_mfma_f32_16x16x32_bf16 v[128:131], v[136:139], v[160:163], v[128:131]
	v_mfma_f32_16x16x32_bf16 v[108:111], v[120:123], v[168:171], v[108:111]
	v_mfma_f32_16x16x32_bf16 v[104:107], v[136:139], v[168:171], v[104:107]
	v_mfma_f32_16x16x32_bf16 v[92:95], v[120:123], v[176:179], v[92:95]
	v_mfma_f32_16x16x32_bf16 v[88:91], v[136:139], v[176:179], v[88:91]
	v_mfma_f32_16x16x32_bf16 v[76:79], v[120:123], v[200:203], v[76:79]
	v_mfma_f32_16x16x32_bf16 v[72:75], v[136:139], v[200:203], v[72:75]
	v_mfma_f32_16x16x32_bf16 v[132:135], v[124:127], v[164:167], v[132:135]
	v_mfma_f32_16x16x32_bf16 v[128:131], v[140:143], v[164:167], v[128:131]
	v_mfma_f32_16x16x32_bf16 v[108:111], v[124:127], v[172:175], v[108:111]
	v_mfma_f32_16x16x32_bf16 v[104:107], v[140:143], v[172:175], v[104:107]
	v_mfma_f32_16x16x32_bf16 v[92:95], v[124:127], v[180:183], v[92:95]
	v_mfma_f32_16x16x32_bf16 v[88:91], v[140:143], v[180:183], v[88:91]
	v_mfma_f32_16x16x32_bf16 v[76:79], v[124:127], v[204:207], v[76:79]
	v_mfma_f32_16x16x32_bf16 v[72:75], v[140:143], v[204:207], v[72:75]
	v_mfma_f32_16x16x32_bf16 v[116:119], v[144:147], v[160:163], v[116:119]
	v_mfma_f32_16x16x32_bf16 v[112:115], v[152:155], v[160:163], v[112:115]
	v_mfma_f32_16x16x32_bf16 v[100:103], v[144:147], v[168:171], v[100:103]
	v_mfma_f32_16x16x32_bf16 v[96:99], v[152:155], v[168:171], v[96:99]
	v_mfma_f32_16x16x32_bf16 v[84:87], v[144:147], v[176:179], v[84:87]
	v_mfma_f32_16x16x32_bf16 v[80:83], v[152:155], v[176:179], v[80:83]
	v_mfma_f32_16x16x32_bf16 v[68:71], v[144:147], v[200:203], v[68:71]
	v_mfma_f32_16x16x32_bf16 v[64:67], v[152:155], v[200:203], v[64:67]
	v_mfma_f32_16x16x32_bf16 v[116:119], v[148:151], v[164:167], v[116:119]
	v_mfma_f32_16x16x32_bf16 v[112:115], v[156:159], v[164:167], v[112:115]
	v_mfma_f32_16x16x32_bf16 v[100:103], v[148:151], v[172:175], v[100:103]
	v_mfma_f32_16x16x32_bf16 v[96:99], v[156:159], v[172:175], v[96:99]
	s_setprio 2
	s_barrier
	v_mfma_f32_16x16x32_bf16 v[84:87], v[148:151], v[180:183], v[84:87]
	v_mfma_f32_16x16x32_bf16 v[80:83], v[156:159], v[180:183], v[80:83]
	v_mfma_f32_16x16x32_bf16 v[68:71], v[148:151], v[204:207], v[68:71]
	v_mfma_f32_16x16x32_bf16 v[64:67], v[156:159], v[204:207], v[64:67]
	s_setprio 0
	s_add_i32 s26, s65, s43
	v_lshl_add_u64 v[208:209], v[208:209], 0, s[20:21]
	s_mov_b32 m0, s26
	ds_read_b128 v[160:163], v235 offset:49152
	ds_read_b128 v[164:167], v235 offset:50176
	ds_read_b128 v[168:171], v235 offset:51200
	ds_read_b128 v[172:175], v235 offset:52224
	ds_read_b128 v[176:179], v235 offset:53248
	ds_read_b128 v[180:183], v235 offset:54272
	ds_read_b128 v[200:203], v235 offset:55296
	ds_read_b128 v[204:207], v235 offset:56320
	global_load_lds_dwordx4 v[208:209], off
	s_add_i32 m0, s26, 0x2000
	s_add_u32 s26, s30, 0xb0080
	v_lshl_add_u64 v[208:209], v[210:211], 0, s[20:21]
	s_addc_u32 s27, s31, 0
	s_add_i32 s30, s66, s43
	global_load_lds_dwordx4 v[208:209], off
	s_mov_b32 m0, s30
	v_lshl_add_u64 v[208:209], s[26:27], 0, v[186:187]
	global_load_lds_dwordx4 v[208:209], off
	s_add_i32 m0, s30, 0x2000
	v_lshl_add_u64 v[208:209], s[26:27], 0, v[190:191]
	global_load_lds_dwordx4 v[208:209], off
	s_mov_b32 m0, s49
	v_lshl_add_u64 v[208:209], v[212:213], 0, s[20:21]
	global_load_lds_dwordx4 v[208:209], off
	s_mov_b32 m0, s50
	v_lshl_add_u64 v[208:209], v[214:215], 0, s[20:21]
	global_load_lds_dwordx4 v[208:209], off
	s_waitcnt vmcnt(8)
	s_waitcnt lgkmcnt(0)
	s_barrier
	s_setprio 1
	s_waitcnt lgkmcnt(0)
	v_mfma_f32_16x16x32_bf16 v[60:63], v[120:123], v[160:163], v[60:63]
	v_mfma_f32_16x16x32_bf16 v[56:59], v[136:139], v[160:163], v[56:59]
	v_mfma_f32_16x16x32_bf16 v[44:47], v[120:123], v[168:171], v[44:47]
	v_mfma_f32_16x16x32_bf16 v[40:43], v[136:139], v[168:171], v[40:43]
	v_mfma_f32_16x16x32_bf16 v[28:31], v[120:123], v[176:179], v[28:31]
	v_mfma_f32_16x16x32_bf16 v[24:27], v[136:139], v[176:179], v[24:27]
	v_mfma_f32_16x16x32_bf16 v[12:15], v[120:123], v[200:203], v[12:15]
	v_mfma_f32_16x16x32_bf16 v[8:11], v[136:139], v[200:203], v[8:11]
	v_mfma_f32_16x16x32_bf16 v[60:63], v[124:127], v[164:167], v[60:63]
	v_mfma_f32_16x16x32_bf16 v[56:59], v[140:143], v[164:167], v[56:59]
	v_mfma_f32_16x16x32_bf16 v[44:47], v[124:127], v[172:175], v[44:47]
	v_mfma_f32_16x16x32_bf16 v[40:43], v[140:143], v[172:175], v[40:43]
	v_mfma_f32_16x16x32_bf16 v[28:31], v[124:127], v[180:183], v[28:31]
	v_mfma_f32_16x16x32_bf16 v[24:27], v[140:143], v[180:183], v[24:27]
	v_mfma_f32_16x16x32_bf16 v[12:15], v[124:127], v[204:207], v[12:15]
	v_mfma_f32_16x16x32_bf16 v[8:11], v[140:143], v[204:207], v[8:11]
	v_mfma_f32_16x16x32_bf16 v[52:55], v[144:147], v[160:163], v[52:55]
	v_mfma_f32_16x16x32_bf16 v[48:51], v[152:155], v[160:163], v[48:51]
	v_mfma_f32_16x16x32_bf16 v[36:39], v[144:147], v[168:171], v[36:39]
	v_mfma_f32_16x16x32_bf16 v[32:35], v[152:155], v[168:171], v[32:35]
	v_mfma_f32_16x16x32_bf16 v[20:23], v[144:147], v[176:179], v[20:23]
	v_mfma_f32_16x16x32_bf16 v[16:19], v[152:155], v[176:179], v[16:19]
	v_mfma_f32_16x16x32_bf16 v[4:7], v[144:147], v[200:203], v[4:7]
	v_mfma_f32_16x16x32_bf16 v[0:3], v[152:155], v[200:203], v[0:3]
	v_mfma_f32_16x16x32_bf16 v[52:55], v[148:151], v[164:167], v[52:55]
	v_mfma_f32_16x16x32_bf16 v[48:51], v[156:159], v[164:167], v[48:51]
	v_mfma_f32_16x16x32_bf16 v[36:39], v[148:151], v[172:175], v[36:39]
	v_mfma_f32_16x16x32_bf16 v[32:35], v[156:159], v[172:175], v[32:35]
	s_setprio 2
	s_barrier
	v_mfma_f32_16x16x32_bf16 v[20:23], v[148:151], v[180:183], v[20:23]
	v_mfma_f32_16x16x32_bf16 v[16:19], v[156:159], v[180:183], v[16:19]
	v_mfma_f32_16x16x32_bf16 v[4:7], v[148:151], v[204:207], v[4:7]
	v_mfma_f32_16x16x32_bf16 v[0:3], v[156:159], v[204:207], v[0:3]
	s_setprio 0
	s_add_i32 s64, s64, 2
	s_add_u32 s62, s62, 0x100
	s_addc_u32 s63, s63, 0
	s_cmp_gt_u32 s64, 41
	s_mov_b64 s[26:27], s[28:29]
.LBB0_866:
	ds_read_b128 v[120:123], v233
	ds_read_b128 v[124:127], v233 offset:1024
	ds_read_b128 v[136:139], v233 offset:2048
	ds_read_b128 v[140:143], v233 offset:3072
	ds_read_b128 v[144:147], v234
	ds_read_b128 v[148:151], v234 offset:1024
	ds_read_b128 v[152:155], v234 offset:2048
	ds_read_b128 v[156:159], v234 offset:3072
	s_add_u32 s28, s26, 0x100
	s_addc_u32 s29, s27, 0
	s_cmp_eq_u32 s64, 40
	s_cselect_b32 s37, s7, s29
	s_cselect_b32 s36, s6, s28
	s_cselect_b32 s31, s25, s63
	s_cselect_b32 s30, s24, s62
	v_lshl_add_u64 v[208:209], s[26:27], 0, v[192:193]
	s_add_i32 m0, s44, 0xc000
	ds_read_b128 v[160:163], v235
	ds_read_b128 v[164:167], v235 offset:1024
	ds_read_b128 v[168:171], v235 offset:2048
	ds_read_b128 v[172:175], v235 offset:3072
	ds_read_b128 v[176:179], v235 offset:4096
	ds_read_b128 v[180:183], v235 offset:5120
	ds_read_b128 v[200:203], v235 offset:6144
	ds_read_b128 v[204:207], v235 offset:7168
	global_load_lds_dwordx4 v[208:209], off
	s_add_i32 m0, s44, 0xe000
	v_lshl_add_u64 v[208:209], s[26:27], 0, v[194:195]
	global_load_lds_dwordx4 v[208:209], off
	s_waitcnt vmcnt(8)
	s_waitcnt lgkmcnt(0)
	s_barrier
	s_setprio 1
	s_waitcnt lgkmcnt(0)
	v_mfma_f32_16x16x32_bf16 v[132:135], v[120:123], v[160:163], v[132:135]
	v_mfma_f32_16x16x32_bf16 v[128:131], v[136:139], v[160:163], v[128:131]
	v_mfma_f32_16x16x32_bf16 v[108:111], v[120:123], v[168:171], v[108:111]
	v_mfma_f32_16x16x32_bf16 v[104:107], v[136:139], v[168:171], v[104:107]
	v_mfma_f32_16x16x32_bf16 v[92:95], v[120:123], v[176:179], v[92:95]
	v_mfma_f32_16x16x32_bf16 v[88:91], v[136:139], v[176:179], v[88:91]
	v_mfma_f32_16x16x32_bf16 v[76:79], v[120:123], v[200:203], v[76:79]
	v_mfma_f32_16x16x32_bf16 v[72:75], v[136:139], v[200:203], v[72:75]
	v_mfma_f32_16x16x32_bf16 v[132:135], v[124:127], v[164:167], v[132:135]
	v_mfma_f32_16x16x32_bf16 v[128:131], v[140:143], v[164:167], v[128:131]
	v_mfma_f32_16x16x32_bf16 v[108:111], v[124:127], v[172:175], v[108:111]
	v_mfma_f32_16x16x32_bf16 v[104:107], v[140:143], v[172:175], v[104:107]
	v_mfma_f32_16x16x32_bf16 v[92:95], v[124:127], v[180:183], v[92:95]
	v_mfma_f32_16x16x32_bf16 v[88:91], v[140:143], v[180:183], v[88:91]
	v_mfma_f32_16x16x32_bf16 v[76:79], v[124:127], v[204:207], v[76:79]
	v_mfma_f32_16x16x32_bf16 v[72:75], v[140:143], v[204:207], v[72:75]
	v_mfma_f32_16x16x32_bf16 v[116:119], v[144:147], v[160:163], v[116:119]
	v_mfma_f32_16x16x32_bf16 v[112:115], v[152:155], v[160:163], v[112:115]
	v_mfma_f32_16x16x32_bf16 v[100:103], v[144:147], v[168:171], v[100:103]
	v_mfma_f32_16x16x32_bf16 v[96:99], v[152:155], v[168:171], v[96:99]
	v_mfma_f32_16x16x32_bf16 v[84:87], v[144:147], v[176:179], v[84:87]
	v_mfma_f32_16x16x32_bf16 v[80:83], v[152:155], v[176:179], v[80:83]
	v_mfma_f32_16x16x32_bf16 v[68:71], v[144:147], v[200:203], v[68:71]
	v_mfma_f32_16x16x32_bf16 v[64:67], v[152:155], v[200:203], v[64:67]
	v_mfma_f32_16x16x32_bf16 v[116:119], v[148:151], v[164:167], v[116:119]
	v_mfma_f32_16x16x32_bf16 v[112:115], v[156:159], v[164:167], v[112:115]
	v_mfma_f32_16x16x32_bf16 v[100:103], v[148:151], v[172:175], v[100:103]
	v_mfma_f32_16x16x32_bf16 v[96:99], v[156:159], v[172:175], v[96:99]
	s_setprio 2
	s_barrier
	v_mfma_f32_16x16x32_bf16 v[84:87], v[148:151], v[180:183], v[84:87]
	v_mfma_f32_16x16x32_bf16 v[80:83], v[156:159], v[180:183], v[80:83]
	v_mfma_f32_16x16x32_bf16 v[68:71], v[148:151], v[204:207], v[68:71]
	v_mfma_f32_16x16x32_bf16 v[64:67], v[156:159], v[204:207], v[64:67]
	s_setprio 0
	s_add_i32 s26, s56, s43
	v_lshl_add_u64 v[208:209], s[30:31], 0, v[186:187]
	s_mov_b32 m0, s26
	ds_read_b128 v[160:163], v235 offset:16384
	ds_read_b128 v[164:167], v235 offset:17408
	ds_read_b128 v[168:171], v235 offset:18432
	ds_read_b128 v[172:175], v235 offset:19456
	ds_read_b128 v[176:179], v235 offset:20480
	ds_read_b128 v[180:183], v235 offset:21504
	ds_read_b128 v[200:203], v235 offset:22528
	ds_read_b128 v[204:207], v235 offset:23552
	global_load_lds_dwordx4 v[208:209], off
	s_add_i32 m0, s26, 0x2000
	s_add_u32 s26, s30, 0xb0000
	v_lshl_add_u64 v[210:211], s[30:31], 0, v[190:191]
	s_addc_u32 s27, s31, 0
	s_add_i32 s65, s57, s43
	global_load_lds_dwordx4 v[210:211], off
	v_lshl_add_u64 v[212:213], s[26:27], 0, v[186:187]
	s_mov_b32 m0, s65
	v_lshl_add_u64 v[214:215], s[36:37], 0, v[188:189]
	global_load_lds_dwordx4 v[212:213], off
	s_add_i32 m0, s65, 0x2000
	v_lshl_add_u64 v[212:213], s[26:27], 0, v[190:191]
	global_load_lds_dwordx4 v[212:213], off
	s_mov_b32 m0, s44
	v_lshl_add_u64 v[212:213], s[36:37], 0, v[184:185]
	global_load_lds_dwordx4 v[212:213], off
	s_mov_b32 m0, s45
	s_nop 0
	global_load_lds_dwordx4 v[214:215], off
	s_waitcnt vmcnt(8)
	s_waitcnt lgkmcnt(0)
	s_barrier
	s_setprio 1
	s_waitcnt lgkmcnt(0)
	v_mfma_f32_16x16x32_bf16 v[60:63], v[120:123], v[160:163], v[60:63]
	v_mfma_f32_16x16x32_bf16 v[56:59], v[136:139], v[160:163], v[56:59]
	v_mfma_f32_16x16x32_bf16 v[44:47], v[120:123], v[168:171], v[44:47]
	v_mfma_f32_16x16x32_bf16 v[40:43], v[136:139], v[168:171], v[40:43]
	v_mfma_f32_16x16x32_bf16 v[28:31], v[120:123], v[176:179], v[28:31]
	v_mfma_f32_16x16x32_bf16 v[24:27], v[136:139], v[176:179], v[24:27]
	v_mfma_f32_16x16x32_bf16 v[12:15], v[120:123], v[200:203], v[12:15]
	v_mfma_f32_16x16x32_bf16 v[8:11], v[136:139], v[200:203], v[8:11]
	v_mfma_f32_16x16x32_bf16 v[60:63], v[124:127], v[164:167], v[60:63]
	v_mfma_f32_16x16x32_bf16 v[56:59], v[140:143], v[164:167], v[56:59]
	v_mfma_f32_16x16x32_bf16 v[44:47], v[124:127], v[172:175], v[44:47]
	v_mfma_f32_16x16x32_bf16 v[40:43], v[140:143], v[172:175], v[40:43]
	v_mfma_f32_16x16x32_bf16 v[28:31], v[124:127], v[180:183], v[28:31]
	v_mfma_f32_16x16x32_bf16 v[24:27], v[140:143], v[180:183], v[24:27]
	v_mfma_f32_16x16x32_bf16 v[12:15], v[124:127], v[204:207], v[12:15]
	v_mfma_f32_16x16x32_bf16 v[8:11], v[140:143], v[204:207], v[8:11]
	v_mfma_f32_16x16x32_bf16 v[52:55], v[144:147], v[160:163], v[52:55]
	v_mfma_f32_16x16x32_bf16 v[48:51], v[152:155], v[160:163], v[48:51]
	v_mfma_f32_16x16x32_bf16 v[36:39], v[144:147], v[168:171], v[36:39]
	v_mfma_f32_16x16x32_bf16 v[32:35], v[152:155], v[168:171], v[32:35]
	v_mfma_f32_16x16x32_bf16 v[20:23], v[144:147], v[176:179], v[20:23]
	v_mfma_f32_16x16x32_bf16 v[16:19], v[152:155], v[176:179], v[16:19]
	v_mfma_f32_16x16x32_bf16 v[4:7], v[144:147], v[200:203], v[4:7]
	v_mfma_f32_16x16x32_bf16 v[0:3], v[152:155], v[200:203], v[0:3]
	v_mfma_f32_16x16x32_bf16 v[52:55], v[148:151], v[164:167], v[52:55]
	v_mfma_f32_16x16x32_bf16 v[48:51], v[156:159], v[164:167], v[48:51]
	v_mfma_f32_16x16x32_bf16 v[36:39], v[148:151], v[172:175], v[36:39]
	v_mfma_f32_16x16x32_bf16 v[32:35], v[156:159], v[172:175], v[32:35]
	s_setprio 2
	s_barrier
	v_mfma_f32_16x16x32_bf16 v[20:23], v[148:151], v[180:183], v[20:23]
	v_mfma_f32_16x16x32_bf16 v[16:19], v[156:159], v[180:183], v[16:19]
	v_mfma_f32_16x16x32_bf16 v[4:7], v[148:151], v[204:207], v[4:7]
	v_mfma_f32_16x16x32_bf16 v[0:3], v[156:159], v[204:207], v[0:3]
	s_setprio 0
	s_add_i32 s65, 0, 0x18000
	s_add_i32 s66, 0, 0x1c000
	v_add_u32_e32 v140, s65, v232
	v_add_u32_e32 v156, s66, v232
	ds_read_b128 v[120:123], v140
	ds_read_b128 v[124:127], v140 offset:1024
	ds_read_b128 v[136:139], v140 offset:2048
	ds_read_b128 v[140:143], v140 offset:3072
	ds_read_b128 v[144:147], v156
	ds_read_b128 v[148:151], v156 offset:1024
	ds_read_b128 v[152:155], v156 offset:2048
	ds_read_b128 v[156:159], v156 offset:3072
	s_add_u32 s26, s36, 0xb0000
	s_addc_u32 s27, s37, 0
	s_mov_b32 m0, s46
	v_lshl_add_u64 v[216:217], s[26:27], 0, v[184:185]
	ds_read_b128 v[160:163], v235 offset:32768
	ds_read_b128 v[164:167], v235 offset:33792
	ds_read_b128 v[168:171], v235 offset:34816
	ds_read_b128 v[172:175], v235 offset:35840
	ds_read_b128 v[176:179], v235 offset:36864
	ds_read_b128 v[180:183], v235 offset:37888
	ds_read_b128 v[200:203], v235 offset:38912
	ds_read_b128 v[204:207], v235 offset:39936
	global_load_lds_dwordx4 v[216:217], off
	s_mov_b32 m0, s47
	v_lshl_add_u64 v[216:217], s[26:27], 0, v[188:189]
	global_load_lds_dwordx4 v[216:217], off
	s_waitcnt vmcnt(8)
	s_waitcnt lgkmcnt(0)
	s_barrier
	s_setprio 1
	s_waitcnt lgkmcnt(0)
	v_mfma_f32_16x16x32_bf16 v[132:135], v[120:123], v[160:163], v[132:135]
	v_mfma_f32_16x16x32_bf16 v[128:131], v[136:139], v[160:163], v[128:131]
	v_mfma_f32_16x16x32_bf16 v[108:111], v[120:123], v[168:171], v[108:111]
	v_mfma_f32_16x16x32_bf16 v[104:107], v[136:139], v[168:171], v[104:107]
	v_mfma_f32_16x16x32_bf16 v[92:95], v[120:123], v[176:179], v[92:95]
	v_mfma_f32_16x16x32_bf16 v[88:91], v[136:139], v[176:179], v[88:91]
	v_mfma_f32_16x16x32_bf16 v[76:79], v[120:123], v[200:203], v[76:79]
	v_mfma_f32_16x16x32_bf16 v[72:75], v[136:139], v[200:203], v[72:75]
	v_mfma_f32_16x16x32_bf16 v[132:135], v[124:127], v[164:167], v[132:135]
	v_mfma_f32_16x16x32_bf16 v[128:131], v[140:143], v[164:167], v[128:131]
	v_mfma_f32_16x16x32_bf16 v[108:111], v[124:127], v[172:175], v[108:111]
	v_mfma_f32_16x16x32_bf16 v[104:107], v[140:143], v[172:175], v[104:107]
	v_mfma_f32_16x16x32_bf16 v[92:95], v[124:127], v[180:183], v[92:95]
	v_mfma_f32_16x16x32_bf16 v[88:91], v[140:143], v[180:183], v[88:91]
	v_mfma_f32_16x16x32_bf16 v[76:79], v[124:127], v[204:207], v[76:79]
	v_mfma_f32_16x16x32_bf16 v[72:75], v[140:143], v[204:207], v[72:75]
	v_mfma_f32_16x16x32_bf16 v[116:119], v[144:147], v[160:163], v[116:119]
	v_mfma_f32_16x16x32_bf16 v[112:115], v[152:155], v[160:163], v[112:115]
	v_mfma_f32_16x16x32_bf16 v[100:103], v[144:147], v[168:171], v[100:103]
	v_mfma_f32_16x16x32_bf16 v[96:99], v[152:155], v[168:171], v[96:99]
	v_mfma_f32_16x16x32_bf16 v[84:87], v[144:147], v[176:179], v[84:87]
	v_mfma_f32_16x16x32_bf16 v[80:83], v[152:155], v[176:179], v[80:83]
	v_mfma_f32_16x16x32_bf16 v[68:71], v[144:147], v[200:203], v[68:71]
	v_mfma_f32_16x16x32_bf16 v[64:67], v[152:155], v[200:203], v[64:67]
	v_mfma_f32_16x16x32_bf16 v[116:119], v[148:151], v[164:167], v[116:119]
	v_mfma_f32_16x16x32_bf16 v[112:115], v[156:159], v[164:167], v[112:115]
	v_mfma_f32_16x16x32_bf16 v[100:103], v[148:151], v[172:175], v[100:103]
	v_mfma_f32_16x16x32_bf16 v[96:99], v[156:159], v[172:175], v[96:99]
	s_setprio 2
	s_barrier
	v_mfma_f32_16x16x32_bf16 v[84:87], v[148:151], v[180:183], v[84:87]
	v_mfma_f32_16x16x32_bf16 v[80:83], v[156:159], v[180:183], v[80:83]
	v_mfma_f32_16x16x32_bf16 v[68:71], v[148:151], v[204:207], v[68:71]
	v_mfma_f32_16x16x32_bf16 v[64:67], v[156:159], v[204:207], v[64:67]
	s_setprio 0
	s_add_i32 s26, s65, s43
	v_lshl_add_u64 v[208:209], v[208:209], 0, s[20:21]
	s_mov_b32 m0, s26
	ds_read_b128 v[160:163], v235 offset:49152
	ds_read_b128 v[164:167], v235 offset:50176
	ds_read_b128 v[168:171], v235 offset:51200
	ds_read_b128 v[172:175], v235 offset:52224
	ds_read_b128 v[176:179], v235 offset:53248
	ds_read_b128 v[180:183], v235 offset:54272
	ds_read_b128 v[200:203], v235 offset:55296
	ds_read_b128 v[204:207], v235 offset:56320
	global_load_lds_dwordx4 v[208:209], off
	s_add_i32 m0, s26, 0x2000
	s_add_u32 s26, s30, 0xb0080
	v_lshl_add_u64 v[208:209], v[210:211], 0, s[20:21]
	s_addc_u32 s27, s31, 0
	s_add_i32 s30, s66, s43
	global_load_lds_dwordx4 v[208:209], off
	s_mov_b32 m0, s30
	v_lshl_add_u64 v[208:209], s[26:27], 0, v[186:187]
	global_load_lds_dwordx4 v[208:209], off
	s_add_i32 m0, s30, 0x2000
	v_lshl_add_u64 v[208:209], s[26:27], 0, v[190:191]
	global_load_lds_dwordx4 v[208:209], off
	s_mov_b32 m0, s49
	v_lshl_add_u64 v[208:209], v[212:213], 0, s[20:21]
	global_load_lds_dwordx4 v[208:209], off
	s_mov_b32 m0, s50
	v_lshl_add_u64 v[208:209], v[214:215], 0, s[20:21]
	global_load_lds_dwordx4 v[208:209], off
	s_waitcnt vmcnt(8)
	s_waitcnt lgkmcnt(0)
	s_barrier
	s_setprio 1
	s_waitcnt lgkmcnt(0)
	v_mfma_f32_16x16x32_bf16 v[60:63], v[120:123], v[160:163], v[60:63]
	v_mfma_f32_16x16x32_bf16 v[56:59], v[136:139], v[160:163], v[56:59]
	v_mfma_f32_16x16x32_bf16 v[44:47], v[120:123], v[168:171], v[44:47]
	v_mfma_f32_16x16x32_bf16 v[40:43], v[136:139], v[168:171], v[40:43]
	v_mfma_f32_16x16x32_bf16 v[28:31], v[120:123], v[176:179], v[28:31]
	v_mfma_f32_16x16x32_bf16 v[24:27], v[136:139], v[176:179], v[24:27]
	v_mfma_f32_16x16x32_bf16 v[12:15], v[120:123], v[200:203], v[12:15]
	v_mfma_f32_16x16x32_bf16 v[8:11], v[136:139], v[200:203], v[8:11]
	v_mfma_f32_16x16x32_bf16 v[60:63], v[124:127], v[164:167], v[60:63]
	v_mfma_f32_16x16x32_bf16 v[56:59], v[140:143], v[164:167], v[56:59]
	v_mfma_f32_16x16x32_bf16 v[44:47], v[124:127], v[172:175], v[44:47]
	v_mfma_f32_16x16x32_bf16 v[40:43], v[140:143], v[172:175], v[40:43]
	v_mfma_f32_16x16x32_bf16 v[28:31], v[124:127], v[180:183], v[28:31]
	v_mfma_f32_16x16x32_bf16 v[24:27], v[140:143], v[180:183], v[24:27]
	v_mfma_f32_16x16x32_bf16 v[12:15], v[124:127], v[204:207], v[12:15]
	v_mfma_f32_16x16x32_bf16 v[8:11], v[140:143], v[204:207], v[8:11]
	v_mfma_f32_16x16x32_bf16 v[52:55], v[144:147], v[160:163], v[52:55]
	v_mfma_f32_16x16x32_bf16 v[48:51], v[152:155], v[160:163], v[48:51]
	v_mfma_f32_16x16x32_bf16 v[36:39], v[144:147], v[168:171], v[36:39]
	v_mfma_f32_16x16x32_bf16 v[32:35], v[152:155], v[168:171], v[32:35]
	v_mfma_f32_16x16x32_bf16 v[20:23], v[144:147], v[176:179], v[20:23]
	v_mfma_f32_16x16x32_bf16 v[16:19], v[152:155], v[176:179], v[16:19]
	v_mfma_f32_16x16x32_bf16 v[4:7], v[144:147], v[200:203], v[4:7]
	v_mfma_f32_16x16x32_bf16 v[0:3], v[152:155], v[200:203], v[0:3]
	v_mfma_f32_16x16x32_bf16 v[52:55], v[148:151], v[164:167], v[52:55]
	v_mfma_f32_16x16x32_bf16 v[48:51], v[156:159], v[164:167], v[48:51]
	v_mfma_f32_16x16x32_bf16 v[36:39], v[148:151], v[172:175], v[36:39]
	v_mfma_f32_16x16x32_bf16 v[32:35], v[156:159], v[172:175], v[32:35]
	s_setprio 2
	s_barrier
	v_mfma_f32_16x16x32_bf16 v[20:23], v[148:151], v[180:183], v[20:23]
	v_mfma_f32_16x16x32_bf16 v[16:19], v[156:159], v[180:183], v[16:19]
	v_mfma_f32_16x16x32_bf16 v[4:7], v[148:151], v[204:207], v[4:7]
	v_mfma_f32_16x16x32_bf16 v[0:3], v[156:159], v[204:207], v[0:3]
	s_setprio 0
	s_add_i32 s64, s64, 2
	s_add_u32 s62, s62, 0x100
	s_addc_u32 s63, s63, 0
	s_cmp_gt_u32 s64, 41
	s_mov_b64 s[26:27], s[28:29]
	s_cbranch_scc0 .LBB0_866

.LBB0_951:
	s_ashr_i32 s27, s26, 31
	s_lshl_b64 s[30:31], s[26:27], 19
	s_add_u32 s30, s47, s30
	s_addc_u32 s31, s48, s31
	s_and_b64 s[36:37], s[4:5], exec
	s_cselect_b32 s27, s31, s7
	s_cselect_b32 s39, s30, s6
	s_ashr_i32 s29, s28, 31
	s_lshl_b64 s[36:37], s[28:29], 19
	s_add_u32 s36, s49, s36
	s_addc_u32 s37, s50, s37
	s_and_b64 s[44:45], s[4:5], exec
	s_cselect_b32 s29, s37, s41
	s_cselect_b32 s43, s36, s40
	s_add_u32 s6, s6, 0x40080
	s_addc_u32 s7, s7, 0
	s_add_u32 s71, s40, 0x100
	s_addc_u32 s72, s41, 0
	s_mov_b32 s73, -2
	ds_read_b128 v[144:147], v179
	ds_read_b128 v[148:151], v179 offset:1024
	ds_read_b128 v[152:155], v179 offset:2048
	ds_read_b128 v[156:159], v179 offset:3072
	ds_read_b128 v[160:163], v180
	ds_read_b128 v[164:167], v180 offset:1024
	ds_read_b128 v[168:171], v180 offset:2048
	ds_read_b128 v[172:175], v180 offset:3072
	s_add_u32 s40, s6, 0xfffc0080
	s_addc_u32 s41, s7, -1
	s_cmp_eq_u32 s73, 12
	s_cselect_b32 s45, s27, s41
	s_cselect_b32 s44, s39, s40
	s_cselect_b32 s41, s29, s72
	s_cselect_b32 s40, s43, s71
	v_lshl_add_u64 v[176:177], s[6:7], 0, v[136:137]
	s_add_i32 m0, s54, 0xc000
	ds_read_b128 v[184:187], v181
	ds_read_b128 v[188:191], v181 offset:1024
	ds_read_b128 v[192:195], v181 offset:2048
	ds_read_b128 v[196:199], v181 offset:3072
	ds_read_b128 v[200:203], v181 offset:4096
	ds_read_b128 v[204:207], v181 offset:5120
	ds_read_b128 v[208:211], v181 offset:6144
	ds_read_b128 v[212:215], v181 offset:7168
	global_load_lds_dwordx4 v[176:177], off
	s_add_i32 m0, s54, 0xe000
	v_lshl_add_u64 v[176:177], s[6:7], 0, v[138:139]
	global_load_lds_dwordx4 v[176:177], off
	s_waitcnt vmcnt(8)
	s_waitcnt lgkmcnt(0)
	s_barrier
	s_setprio 1
	s_waitcnt lgkmcnt(0)
	v_mfma_f32_16x16x32_bf16 v[124:127], v[144:147], v[184:187], 0
	v_mfma_f32_16x16x32_bf16 v[120:123], v[152:155], v[184:187], 0
	v_mfma_f32_16x16x32_bf16 v[108:111], v[144:147], v[192:195], 0
	v_mfma_f32_16x16x32_bf16 v[104:107], v[152:155], v[192:195], 0
	v_mfma_f32_16x16x32_bf16 v[92:95], v[144:147], v[200:203], 0
	v_mfma_f32_16x16x32_bf16 v[88:91], v[152:155], v[200:203], 0
	v_mfma_f32_16x16x32_bf16 v[76:79], v[144:147], v[208:211], 0
	v_mfma_f32_16x16x32_bf16 v[72:75], v[152:155], v[208:211], 0
	v_mfma_f32_16x16x32_bf16 v[124:127], v[148:151], v[188:191], v[124:127]
	v_mfma_f32_16x16x32_bf16 v[120:123], v[156:159], v[188:191], v[120:123]
	v_mfma_f32_16x16x32_bf16 v[108:111], v[148:151], v[196:199], v[108:111]
	v_mfma_f32_16x16x32_bf16 v[104:107], v[156:159], v[196:199], v[104:107]
	v_mfma_f32_16x16x32_bf16 v[92:95], v[148:151], v[204:207], v[92:95]
	v_mfma_f32_16x16x32_bf16 v[88:91], v[156:159], v[204:207], v[88:91]
	v_mfma_f32_16x16x32_bf16 v[76:79], v[148:151], v[212:215], v[76:79]
	v_mfma_f32_16x16x32_bf16 v[72:75], v[156:159], v[212:215], v[72:75]
	v_mfma_f32_16x16x32_bf16 v[116:119], v[160:163], v[184:187], 0
	v_mfma_f32_16x16x32_bf16 v[112:115], v[168:171], v[184:187], 0
	v_mfma_f32_16x16x32_bf16 v[100:103], v[160:163], v[192:195], 0
	v_mfma_f32_16x16x32_bf16 v[96:99], v[168:171], v[192:195], 0
	v_mfma_f32_16x16x32_bf16 v[84:87], v[160:163], v[200:203], 0
	v_mfma_f32_16x16x32_bf16 v[80:83], v[168:171], v[200:203], 0
	v_mfma_f32_16x16x32_bf16 v[68:71], v[160:163], v[208:211], 0
	v_mfma_f32_16x16x32_bf16 v[64:67], v[168:171], v[208:211], 0
	v_mfma_f32_16x16x32_bf16 v[116:119], v[164:167], v[188:191], v[116:119]
	v_mfma_f32_16x16x32_bf16 v[112:115], v[172:175], v[188:191], v[112:115]
	v_mfma_f32_16x16x32_bf16 v[100:103], v[164:167], v[196:199], v[100:103]
	v_mfma_f32_16x16x32_bf16 v[96:99], v[172:175], v[196:199], v[96:99]
	s_setprio 2
	s_barrier
	v_mfma_f32_16x16x32_bf16 v[84:87], v[164:167], v[204:207], v[84:87]
	v_mfma_f32_16x16x32_bf16 v[80:83], v[172:175], v[204:207], v[80:83]
	v_mfma_f32_16x16x32_bf16 v[68:71], v[164:167], v[212:215], v[68:71]
	v_mfma_f32_16x16x32_bf16 v[64:67], v[172:175], v[212:215], v[64:67]
	s_setprio 0
	s_add_i32 s74, s69, s51
	v_lshl_add_u64 v[176:177], s[40:41], 0, v[130:131]
	s_mov_b32 m0, s74
	ds_read_b128 v[184:187], v181 offset:16384
	ds_read_b128 v[188:191], v181 offset:17408
	ds_read_b128 v[192:195], v181 offset:18432
	ds_read_b128 v[196:199], v181 offset:19456
	ds_read_b128 v[200:203], v181 offset:20480
	ds_read_b128 v[204:207], v181 offset:21504
	ds_read_b128 v[208:211], v181 offset:22528
	ds_read_b128 v[212:215], v181 offset:23552
	global_load_lds_dwordx4 v[176:177], off
	s_add_i32 m0, s74, 0x2000
	s_add_u32 s74, s40, 0x40000
	v_lshl_add_u64 v[216:217], s[40:41], 0, v[134:135]
	s_addc_u32 s75, s41, 0
	s_add_i32 s76, s70, s51
	global_load_lds_dwordx4 v[216:217], off
	v_lshl_add_u64 v[218:219], s[74:75], 0, v[130:131]
	s_mov_b32 m0, s76
	v_lshl_add_u64 v[220:221], s[44:45], 0, v[132:133]
	global_load_lds_dwordx4 v[218:219], off
	s_add_i32 m0, s76, 0x2000
	v_lshl_add_u64 v[218:219], s[74:75], 0, v[134:135]
	global_load_lds_dwordx4 v[218:219], off
	s_mov_b32 m0, s54
	v_lshl_add_u64 v[218:219], s[44:45], 0, v[128:129]
	global_load_lds_dwordx4 v[218:219], off
	s_mov_b32 m0, s55
	s_nop 0
	global_load_lds_dwordx4 v[220:221], off
	s_waitcnt vmcnt(8)
	s_waitcnt lgkmcnt(0)
	s_barrier
	s_setprio 1
	s_waitcnt lgkmcnt(0)
	v_mfma_f32_16x16x32_bf16 v[60:63], v[144:147], v[184:187], 0
	v_mfma_f32_16x16x32_bf16 v[56:59], v[152:155], v[184:187], 0
	v_mfma_f32_16x16x32_bf16 v[44:47], v[144:147], v[192:195], 0
	v_mfma_f32_16x16x32_bf16 v[40:43], v[152:155], v[192:195], 0
	v_mfma_f32_16x16x32_bf16 v[28:31], v[144:147], v[200:203], 0
	v_mfma_f32_16x16x32_bf16 v[24:27], v[152:155], v[200:203], 0
	v_mfma_f32_16x16x32_bf16 v[12:15], v[144:147], v[208:211], 0
	v_mfma_f32_16x16x32_bf16 v[8:11], v[152:155], v[208:211], 0
	v_mfma_f32_16x16x32_bf16 v[60:63], v[148:151], v[188:191], v[60:63]
	v_mfma_f32_16x16x32_bf16 v[56:59], v[156:159], v[188:191], v[56:59]
	v_mfma_f32_16x16x32_bf16 v[44:47], v[148:151], v[196:199], v[44:47]
	v_mfma_f32_16x16x32_bf16 v[40:43], v[156:159], v[196:199], v[40:43]
	v_mfma_f32_16x16x32_bf16 v[28:31], v[148:151], v[204:207], v[28:31]
	v_mfma_f32_16x16x32_bf16 v[24:27], v[156:159], v[204:207], v[24:27]
	v_mfma_f32_16x16x32_bf16 v[12:15], v[148:151], v[212:215], v[12:15]
	v_mfma_f32_16x16x32_bf16 v[8:11], v[156:159], v[212:215], v[8:11]
	v_mfma_f32_16x16x32_bf16 v[52:55], v[160:163], v[184:187], 0
	v_mfma_f32_16x16x32_bf16 v[48:51], v[168:171], v[184:187], 0
	v_mfma_f32_16x16x32_bf16 v[36:39], v[160:163], v[192:195], 0
	v_mfma_f32_16x16x32_bf16 v[32:35], v[168:171], v[192:195], 0
	v_mfma_f32_16x16x32_bf16 v[20:23], v[160:163], v[200:203], 0
	v_mfma_f32_16x16x32_bf16 v[16:19], v[168:171], v[200:203], 0
	v_mfma_f32_16x16x32_bf16 v[4:7], v[160:163], v[208:211], 0
	v_mfma_f32_16x16x32_bf16 v[0:3], v[168:171], v[208:211], 0
	v_mfma_f32_16x16x32_bf16 v[52:55], v[164:167], v[188:191], v[52:55]
	v_mfma_f32_16x16x32_bf16 v[48:51], v[172:175], v[188:191], v[48:51]
	v_mfma_f32_16x16x32_bf16 v[36:39], v[164:167], v[196:199], v[36:39]
	v_mfma_f32_16x16x32_bf16 v[32:35], v[172:175], v[196:199], v[32:35]
	s_setprio 2
	s_barrier
	v_mfma_f32_16x16x32_bf16 v[20:23], v[164:167], v[204:207], v[20:23]
	v_mfma_f32_16x16x32_bf16 v[16:19], v[172:175], v[204:207], v[16:19]
	v_mfma_f32_16x16x32_bf16 v[4:7], v[164:167], v[212:215], v[4:7]
	v_mfma_f32_16x16x32_bf16 v[0:3], v[172:175], v[212:215], v[0:3]
	s_setprio 0
	s_add_i32 s74, 0, 0x18000
	s_add_i32 s75, 0, 0x1c000
	v_add_u32_e32 v156, s74, v178
	v_add_u32_e32 v172, s75, v178
	ds_read_b128 v[144:147], v156
	ds_read_b128 v[148:151], v156 offset:1024
	ds_read_b128 v[152:155], v156 offset:2048
	ds_read_b128 v[156:159], v156 offset:3072
	ds_read_b128 v[160:163], v172
	ds_read_b128 v[164:167], v172 offset:1024
	ds_read_b128 v[168:171], v172 offset:2048
	ds_read_b128 v[172:175], v172 offset:3072
	s_add_u32 s44, s44, 0x40000
	s_addc_u32 s45, s45, 0
	s_mov_b32 m0, s56
	v_lshl_add_u64 v[222:223], s[44:45], 0, v[128:129]
	ds_read_b128 v[184:187], v181 offset:32768
	ds_read_b128 v[188:191], v181 offset:33792
	ds_read_b128 v[192:195], v181 offset:34816
	ds_read_b128 v[196:199], v181 offset:35840
	ds_read_b128 v[200:203], v181 offset:36864
	ds_read_b128 v[204:207], v181 offset:37888
	ds_read_b128 v[208:211], v181 offset:38912
	ds_read_b128 v[212:215], v181 offset:39936
	global_load_lds_dwordx4 v[222:223], off
	s_mov_b32 m0, s57
	v_lshl_add_u64 v[222:223], s[44:45], 0, v[132:133]
	global_load_lds_dwordx4 v[222:223], off
	s_waitcnt vmcnt(8)
	s_waitcnt lgkmcnt(0)
	s_barrier
	s_setprio 1
	s_waitcnt lgkmcnt(0)
	v_mfma_f32_16x16x32_bf16 v[124:127], v[144:147], v[184:187], v[124:127]
	v_mfma_f32_16x16x32_bf16 v[120:123], v[152:155], v[184:187], v[120:123]
	v_mfma_f32_16x16x32_bf16 v[108:111], v[144:147], v[192:195], v[108:111]
	v_mfma_f32_16x16x32_bf16 v[104:107], v[152:155], v[192:195], v[104:107]
	v_mfma_f32_16x16x32_bf16 v[92:95], v[144:147], v[200:203], v[92:95]
	v_mfma_f32_16x16x32_bf16 v[88:91], v[152:155], v[200:203], v[88:91]
	v_mfma_f32_16x16x32_bf16 v[76:79], v[144:147], v[208:211], v[76:79]
	v_mfma_f32_16x16x32_bf16 v[72:75], v[152:155], v[208:211], v[72:75]
	v_mfma_f32_16x16x32_bf16 v[124:127], v[148:151], v[188:191], v[124:127]
	v_mfma_f32_16x16x32_bf16 v[120:123], v[156:159], v[188:191], v[120:123]
	v_mfma_f32_16x16x32_bf16 v[108:111], v[148:151], v[196:199], v[108:111]
	v_mfma_f32_16x16x32_bf16 v[104:107], v[156:159], v[196:199], v[104:107]
	v_mfma_f32_16x16x32_bf16 v[92:95], v[148:151], v[204:207], v[92:95]
	v_mfma_f32_16x16x32_bf16 v[88:91], v[156:159], v[204:207], v[88:91]
	v_mfma_f32_16x16x32_bf16 v[76:79], v[148:151], v[212:215], v[76:79]
	v_mfma_f32_16x16x32_bf16 v[72:75], v[156:159], v[212:215], v[72:75]
	v_mfma_f32_16x16x32_bf16 v[116:119], v[160:163], v[184:187], v[116:119]
	v_mfma_f32_16x16x32_bf16 v[112:115], v[168:171], v[184:187], v[112:115]
	v_mfma_f32_16x16x32_bf16 v[100:103], v[160:163], v[192:195], v[100:103]
	v_mfma_f32_16x16x32_bf16 v[96:99], v[168:171], v[192:195], v[96:99]
	v_mfma_f32_16x16x32_bf16 v[84:87], v[160:163], v[200:203], v[84:87]
	v_mfma_f32_16x16x32_bf16 v[80:83], v[168:171], v[200:203], v[80:83]
	v_mfma_f32_16x16x32_bf16 v[68:71], v[160:163], v[208:211], v[68:71]
	v_mfma_f32_16x16x32_bf16 v[64:67], v[168:171], v[208:211], v[64:67]
	v_mfma_f32_16x16x32_bf16 v[116:119], v[164:167], v[188:191], v[116:119]
	v_mfma_f32_16x16x32_bf16 v[112:115], v[172:175], v[188:191], v[112:115]
	v_mfma_f32_16x16x32_bf16 v[100:103], v[164:167], v[196:199], v[100:103]
	v_mfma_f32_16x16x32_bf16 v[96:99], v[172:175], v[196:199], v[96:99]
	s_setprio 2
	s_barrier
	v_mfma_f32_16x16x32_bf16 v[84:87], v[164:167], v[204:207], v[84:87]
	v_mfma_f32_16x16x32_bf16 v[80:83], v[172:175], v[204:207], v[80:83]
	v_mfma_f32_16x16x32_bf16 v[68:71], v[164:167], v[212:215], v[68:71]
	v_mfma_f32_16x16x32_bf16 v[64:67], v[172:175], v[212:215], v[64:67]
	s_setprio 0
	s_add_i32 s44, s74, s51
	v_lshl_add_u64 v[176:177], v[176:177], 0, s[22:23]
	s_mov_b32 m0, s44
	ds_read_b128 v[184:187], v181 offset:49152
	ds_read_b128 v[188:191], v181 offset:50176
	ds_read_b128 v[192:195], v181 offset:51200
	ds_read_b128 v[196:199], v181 offset:52224
	ds_read_b128 v[200:203], v181 offset:53248
	ds_read_b128 v[204:207], v181 offset:54272
	ds_read_b128 v[208:211], v181 offset:55296
	ds_read_b128 v[212:215], v181 offset:56320
	global_load_lds_dwordx4 v[176:177], off
	s_add_i32 m0, s44, 0x2000
	s_add_u32 s40, s40, 0x40080
	v_lshl_add_u64 v[176:177], v[216:217], 0, s[22:23]
	s_addc_u32 s41, s41, 0
	s_add_i32 s44, s75, s51
	global_load_lds_dwordx4 v[176:177], off
	s_mov_b32 m0, s44
	v_lshl_add_u64 v[176:177], s[40:41], 0, v[130:131]
	global_load_lds_dwordx4 v[176:177], off
	s_add_i32 m0, s44, 0x2000
	v_lshl_add_u64 v[176:177], s[40:41], 0, v[134:135]
	global_load_lds_dwordx4 v[176:177], off
	s_mov_b32 m0, s64
	v_lshl_add_u64 v[176:177], v[218:219], 0, s[22:23]
	global_load_lds_dwordx4 v[176:177], off
	s_mov_b32 m0, s65
	v_lshl_add_u64 v[176:177], v[220:221], 0, s[22:23]
	global_load_lds_dwordx4 v[176:177], off
	s_waitcnt vmcnt(8)
	s_waitcnt lgkmcnt(0)
	s_barrier
	s_setprio 1
	s_waitcnt lgkmcnt(0)
	v_mfma_f32_16x16x32_bf16 v[60:63], v[144:147], v[184:187], v[60:63]
	v_mfma_f32_16x16x32_bf16 v[56:59], v[152:155], v[184:187], v[56:59]
	v_mfma_f32_16x16x32_bf16 v[44:47], v[144:147], v[192:195], v[44:47]
	v_mfma_f32_16x16x32_bf16 v[40:43], v[152:155], v[192:195], v[40:43]
	v_mfma_f32_16x16x32_bf16 v[28:31], v[144:147], v[200:203], v[28:31]
	v_mfma_f32_16x16x32_bf16 v[24:27], v[152:155], v[200:203], v[24:27]
	v_mfma_f32_16x16x32_bf16 v[12:15], v[144:147], v[208:211], v[12:15]
	v_mfma_f32_16x16x32_bf16 v[8:11], v[152:155], v[208:211], v[8:11]
	v_mfma_f32_16x16x32_bf16 v[60:63], v[148:151], v[188:191], v[60:63]
	v_mfma_f32_16x16x32_bf16 v[56:59], v[156:159], v[188:191], v[56:59]
	v_mfma_f32_16x16x32_bf16 v[44:47], v[148:151], v[196:199], v[44:47]
	v_mfma_f32_16x16x32_bf16 v[40:43], v[156:159], v[196:199], v[40:43]
	v_mfma_f32_16x16x32_bf16 v[28:31], v[148:151], v[204:207], v[28:31]
	v_mfma_f32_16x16x32_bf16 v[24:27], v[156:159], v[204:207], v[24:27]
	v_mfma_f32_16x16x32_bf16 v[12:15], v[148:151], v[212:215], v[12:15]
	v_mfma_f32_16x16x32_bf16 v[8:11], v[156:159], v[212:215], v[8:11]
	v_mfma_f32_16x16x32_bf16 v[52:55], v[160:163], v[184:187], v[52:55]
	v_mfma_f32_16x16x32_bf16 v[48:51], v[168:171], v[184:187], v[48:51]
	v_mfma_f32_16x16x32_bf16 v[36:39], v[160:163], v[192:195], v[36:39]
	v_mfma_f32_16x16x32_bf16 v[32:35], v[168:171], v[192:195], v[32:35]
	v_mfma_f32_16x16x32_bf16 v[20:23], v[160:163], v[200:203], v[20:23]
	v_mfma_f32_16x16x32_bf16 v[16:19], v[168:171], v[200:203], v[16:19]
	v_mfma_f32_16x16x32_bf16 v[4:7], v[160:163], v[208:211], v[4:7]
	v_mfma_f32_16x16x32_bf16 v[0:3], v[168:171], v[208:211], v[0:3]
	v_mfma_f32_16x16x32_bf16 v[52:55], v[164:167], v[188:191], v[52:55]
	v_mfma_f32_16x16x32_bf16 v[48:51], v[172:175], v[188:191], v[48:51]
	v_mfma_f32_16x16x32_bf16 v[36:39], v[164:167], v[196:199], v[36:39]
	v_mfma_f32_16x16x32_bf16 v[32:35], v[172:175], v[196:199], v[32:35]
	s_setprio 2
	s_barrier
	v_mfma_f32_16x16x32_bf16 v[20:23], v[164:167], v[204:207], v[20:23]
	v_mfma_f32_16x16x32_bf16 v[16:19], v[172:175], v[204:207], v[16:19]
	v_mfma_f32_16x16x32_bf16 v[4:7], v[164:167], v[212:215], v[4:7]
	v_mfma_f32_16x16x32_bf16 v[0:3], v[172:175], v[212:215], v[0:3]
	s_setprio 0
	s_add_i32 s73, s73, 2
	s_add_u32 s6, s6, 0x100
	s_addc_u32 s7, s7, 0
	s_add_u32 s71, s71, 0x100
	s_addc_u32 s72, s72, 0
	s_cmp_gt_u32 s73, 13
.LBB0_952:
	ds_read_b128 v[144:147], v179
	ds_read_b128 v[148:151], v179 offset:1024
	ds_read_b128 v[152:155], v179 offset:2048
	ds_read_b128 v[156:159], v179 offset:3072
	ds_read_b128 v[160:163], v180
	ds_read_b128 v[164:167], v180 offset:1024
	ds_read_b128 v[168:171], v180 offset:2048
	ds_read_b128 v[172:175], v180 offset:3072
	s_add_u32 s40, s6, 0xfffc0080
	s_addc_u32 s41, s7, -1
	s_cmp_eq_u32 s73, 12
	s_cselect_b32 s45, s27, s41
	s_cselect_b32 s44, s39, s40
	s_cselect_b32 s41, s29, s72
	s_cselect_b32 s40, s43, s71
	v_lshl_add_u64 v[176:177], s[6:7], 0, v[136:137]
	s_add_i32 m0, s54, 0xc000
	ds_read_b128 v[184:187], v181
	ds_read_b128 v[188:191], v181 offset:1024
	ds_read_b128 v[192:195], v181 offset:2048
	ds_read_b128 v[196:199], v181 offset:3072
	ds_read_b128 v[200:203], v181 offset:4096
	ds_read_b128 v[204:207], v181 offset:5120
	ds_read_b128 v[208:211], v181 offset:6144
	ds_read_b128 v[212:215], v181 offset:7168
	global_load_lds_dwordx4 v[176:177], off
	s_add_i32 m0, s54, 0xe000
	v_lshl_add_u64 v[176:177], s[6:7], 0, v[138:139]
	global_load_lds_dwordx4 v[176:177], off
	s_waitcnt vmcnt(8)
	s_waitcnt lgkmcnt(0)
	s_barrier
	s_setprio 1
	s_waitcnt lgkmcnt(0)
	v_mfma_f32_16x16x32_bf16 v[124:127], v[144:147], v[184:187], v[124:127]
	v_mfma_f32_16x16x32_bf16 v[120:123], v[152:155], v[184:187], v[120:123]
	v_mfma_f32_16x16x32_bf16 v[108:111], v[144:147], v[192:195], v[108:111]
	v_mfma_f32_16x16x32_bf16 v[104:107], v[152:155], v[192:195], v[104:107]
	v_mfma_f32_16x16x32_bf16 v[92:95], v[144:147], v[200:203], v[92:95]
	v_mfma_f32_16x16x32_bf16 v[88:91], v[152:155], v[200:203], v[88:91]
	v_mfma_f32_16x16x32_bf16 v[76:79], v[144:147], v[208:211], v[76:79]
	v_mfma_f32_16x16x32_bf16 v[72:75], v[152:155], v[208:211], v[72:75]
	v_mfma_f32_16x16x32_bf16 v[124:127], v[148:151], v[188:191], v[124:127]
	v_mfma_f32_16x16x32_bf16 v[120:123], v[156:159], v[188:191], v[120:123]
	v_mfma_f32_16x16x32_bf16 v[108:111], v[148:151], v[196:199], v[108:111]
	v_mfma_f32_16x16x32_bf16 v[104:107], v[156:159], v[196:199], v[104:107]
	v_mfma_f32_16x16x32_bf16 v[92:95], v[148:151], v[204:207], v[92:95]
	v_mfma_f32_16x16x32_bf16 v[88:91], v[156:159], v[204:207], v[88:91]
	v_mfma_f32_16x16x32_bf16 v[76:79], v[148:151], v[212:215], v[76:79]
	v_mfma_f32_16x16x32_bf16 v[72:75], v[156:159], v[212:215], v[72:75]
	v_mfma_f32_16x16x32_bf16 v[116:119], v[160:163], v[184:187], v[116:119]
	v_mfma_f32_16x16x32_bf16 v[112:115], v[168:171], v[184:187], v[112:115]
	v_mfma_f32_16x16x32_bf16 v[100:103], v[160:163], v[192:195], v[100:103]
	v_mfma_f32_16x16x32_bf16 v[96:99], v[168:171], v[192:195], v[96:99]
	v_mfma_f32_16x16x32_bf16 v[84:87], v[160:163], v[200:203], v[84:87]
	v_mfma_f32_16x16x32_bf16 v[80:83], v[168:171], v[200:203], v[80:83]
	v_mfma_f32_16x16x32_bf16 v[68:71], v[160:163], v[208:211], v[68:71]
	v_mfma_f32_16x16x32_bf16 v[64:67], v[168:171], v[208:211], v[64:67]
	v_mfma_f32_16x16x32_bf16 v[116:119], v[164:167], v[188:191], v[116:119]
	v_mfma_f32_16x16x32_bf16 v[112:115], v[172:175], v[188:191], v[112:115]
	v_mfma_f32_16x16x32_bf16 v[100:103], v[164:167], v[196:199], v[100:103]
	v_mfma_f32_16x16x32_bf16 v[96:99], v[172:175], v[196:199], v[96:99]
	s_setprio 2
	s_barrier
	v_mfma_f32_16x16x32_bf16 v[84:87], v[164:167], v[204:207], v[84:87]
	v_mfma_f32_16x16x32_bf16 v[80:83], v[172:175], v[204:207], v[80:83]
	v_mfma_f32_16x16x32_bf16 v[68:71], v[164:167], v[212:215], v[68:71]
	v_mfma_f32_16x16x32_bf16 v[64:67], v[172:175], v[212:215], v[64:67]
	s_setprio 0
	s_add_i32 s74, s69, s51
	v_lshl_add_u64 v[176:177], s[40:41], 0, v[130:131]
	s_mov_b32 m0, s74
	ds_read_b128 v[184:187], v181 offset:16384
	ds_read_b128 v[188:191], v181 offset:17408
	ds_read_b128 v[192:195], v181 offset:18432
	ds_read_b128 v[196:199], v181 offset:19456
	ds_read_b128 v[200:203], v181 offset:20480
	ds_read_b128 v[204:207], v181 offset:21504
	ds_read_b128 v[208:211], v181 offset:22528
	ds_read_b128 v[212:215], v181 offset:23552
	global_load_lds_dwordx4 v[176:177], off
	s_add_i32 m0, s74, 0x2000
	s_add_u32 s74, s40, 0x40000
	v_lshl_add_u64 v[216:217], s[40:41], 0, v[134:135]
	s_addc_u32 s75, s41, 0
	s_add_i32 s76, s70, s51
	global_load_lds_dwordx4 v[216:217], off
	v_lshl_add_u64 v[218:219], s[74:75], 0, v[130:131]
	s_mov_b32 m0, s76
	v_lshl_add_u64 v[220:221], s[44:45], 0, v[132:133]
	global_load_lds_dwordx4 v[218:219], off
	s_add_i32 m0, s76, 0x2000
	v_lshl_add_u64 v[218:219], s[74:75], 0, v[134:135]
	global_load_lds_dwordx4 v[218:219], off
	s_mov_b32 m0, s54
	v_lshl_add_u64 v[218:219], s[44:45], 0, v[128:129]
	global_load_lds_dwordx4 v[218:219], off
	s_mov_b32 m0, s55
	s_nop 0
	global_load_lds_dwordx4 v[220:221], off
	s_waitcnt vmcnt(8)
	s_waitcnt lgkmcnt(0)
	s_barrier
	s_setprio 1
	s_waitcnt lgkmcnt(0)
	v_mfma_f32_16x16x32_bf16 v[60:63], v[144:147], v[184:187], v[60:63]
	v_mfma_f32_16x16x32_bf16 v[56:59], v[152:155], v[184:187], v[56:59]
	v_mfma_f32_16x16x32_bf16 v[44:47], v[144:147], v[192:195], v[44:47]
	v_mfma_f32_16x16x32_bf16 v[40:43], v[152:155], v[192:195], v[40:43]
	v_mfma_f32_16x16x32_bf16 v[28:31], v[144:147], v[200:203], v[28:31]
	v_mfma_f32_16x16x32_bf16 v[24:27], v[152:155], v[200:203], v[24:27]
	v_mfma_f32_16x16x32_bf16 v[12:15], v[144:147], v[208:211], v[12:15]
	v_mfma_f32_16x16x32_bf16 v[8:11], v[152:155], v[208:211], v[8:11]
	v_mfma_f32_16x16x32_bf16 v[60:63], v[148:151], v[188:191], v[60:63]
	v_mfma_f32_16x16x32_bf16 v[56:59], v[156:159], v[188:191], v[56:59]
	v_mfma_f32_16x16x32_bf16 v[44:47], v[148:151], v[196:199], v[44:47]
	v_mfma_f32_16x16x32_bf16 v[40:43], v[156:159], v[196:199], v[40:43]
	v_mfma_f32_16x16x32_bf16 v[28:31], v[148:151], v[204:207], v[28:31]
	v_mfma_f32_16x16x32_bf16 v[24:27], v[156:159], v[204:207], v[24:27]
	v_mfma_f32_16x16x32_bf16 v[12:15], v[148:151], v[212:215], v[12:15]
	v_mfma_f32_16x16x32_bf16 v[8:11], v[156:159], v[212:215], v[8:11]
	v_mfma_f32_16x16x32_bf16 v[52:55], v[160:163], v[184:187], v[52:55]
	v_mfma_f32_16x16x32_bf16 v[48:51], v[168:171], v[184:187], v[48:51]
	v_mfma_f32_16x16x32_bf16 v[36:39], v[160:163], v[192:195], v[36:39]
	v_mfma_f32_16x16x32_bf16 v[32:35], v[168:171], v[192:195], v[32:35]
	v_mfma_f32_16x16x32_bf16 v[20:23], v[160:163], v[200:203], v[20:23]
	v_mfma_f32_16x16x32_bf16 v[16:19], v[168:171], v[200:203], v[16:19]
	v_mfma_f32_16x16x32_bf16 v[4:7], v[160:163], v[208:211], v[4:7]
	v_mfma_f32_16x16x32_bf16 v[0:3], v[168:171], v[208:211], v[0:3]
	v_mfma_f32_16x16x32_bf16 v[52:55], v[164:167], v[188:191], v[52:55]
	v_mfma_f32_16x16x32_bf16 v[48:51], v[172:175], v[188:191], v[48:51]
	v_mfma_f32_16x16x32_bf16 v[36:39], v[164:167], v[196:199], v[36:39]
	v_mfma_f32_16x16x32_bf16 v[32:35], v[172:175], v[196:199], v[32:35]
	s_setprio 2
	s_barrier
	v_mfma_f32_16x16x32_bf16 v[20:23], v[164:167], v[204:207], v[20:23]
	v_mfma_f32_16x16x32_bf16 v[16:19], v[172:175], v[204:207], v[16:19]
	v_mfma_f32_16x16x32_bf16 v[4:7], v[164:167], v[212:215], v[4:7]
	v_mfma_f32_16x16x32_bf16 v[0:3], v[172:175], v[212:215], v[0:3]
	s_setprio 0
	s_add_i32 s74, 0, 0x18000
	s_add_i32 s75, 0, 0x1c000
	v_add_u32_e32 v156, s74, v178
	v_add_u32_e32 v172, s75, v178
	ds_read_b128 v[144:147], v156
	ds_read_b128 v[148:151], v156 offset:1024
	ds_read_b128 v[152:155], v156 offset:2048
	ds_read_b128 v[156:159], v156 offset:3072
	ds_read_b128 v[160:163], v172
	ds_read_b128 v[164:167], v172 offset:1024
	ds_read_b128 v[168:171], v172 offset:2048
	ds_read_b128 v[172:175], v172 offset:3072
	s_add_u32 s44, s44, 0x40000
	s_addc_u32 s45, s45, 0
	s_mov_b32 m0, s56
	v_lshl_add_u64 v[222:223], s[44:45], 0, v[128:129]
	ds_read_b128 v[184:187], v181 offset:32768
	ds_read_b128 v[188:191], v181 offset:33792
	ds_read_b128 v[192:195], v181 offset:34816
	ds_read_b128 v[196:199], v181 offset:35840
	ds_read_b128 v[200:203], v181 offset:36864
	ds_read_b128 v[204:207], v181 offset:37888
	ds_read_b128 v[208:211], v181 offset:38912
	ds_read_b128 v[212:215], v181 offset:39936
	global_load_lds_dwordx4 v[222:223], off
	s_mov_b32 m0, s57
	v_lshl_add_u64 v[222:223], s[44:45], 0, v[132:133]
	global_load_lds_dwordx4 v[222:223], off
	s_waitcnt vmcnt(8)
	s_waitcnt lgkmcnt(0)
	s_barrier
	s_setprio 1
	s_waitcnt lgkmcnt(0)
	v_mfma_f32_16x16x32_bf16 v[124:127], v[144:147], v[184:187], v[124:127]
	v_mfma_f32_16x16x32_bf16 v[120:123], v[152:155], v[184:187], v[120:123]
	v_mfma_f32_16x16x32_bf16 v[108:111], v[144:147], v[192:195], v[108:111]
	v_mfma_f32_16x16x32_bf16 v[104:107], v[152:155], v[192:195], v[104:107]
	v_mfma_f32_16x16x32_bf16 v[92:95], v[144:147], v[200:203], v[92:95]
	v_mfma_f32_16x16x32_bf16 v[88:91], v[152:155], v[200:203], v[88:91]
	v_mfma_f32_16x16x32_bf16 v[76:79], v[144:147], v[208:211], v[76:79]
	v_mfma_f32_16x16x32_bf16 v[72:75], v[152:155], v[208:211], v[72:75]
	v_mfma_f32_16x16x32_bf16 v[124:127], v[148:151], v[188:191], v[124:127]
	v_mfma_f32_16x16x32_bf16 v[120:123], v[156:159], v[188:191], v[120:123]
	v_mfma_f32_16x16x32_bf16 v[108:111], v[148:151], v[196:199], v[108:111]
	v_mfma_f32_16x16x32_bf16 v[104:107], v[156:159], v[196:199], v[104:107]
	v_mfma_f32_16x16x32_bf16 v[92:95], v[148:151], v[204:207], v[92:95]
	v_mfma_f32_16x16x32_bf16 v[88:91], v[156:159], v[204:207], v[88:91]
	v_mfma_f32_16x16x32_bf16 v[76:79], v[148:151], v[212:215], v[76:79]
	v_mfma_f32_16x16x32_bf16 v[72:75], v[156:159], v[212:215], v[72:75]
	v_mfma_f32_16x16x32_bf16 v[116:119], v[160:163], v[184:187], v[116:119]
	v_mfma_f32_16x16x32_bf16 v[112:115], v[168:171], v[184:187], v[112:115]
	v_mfma_f32_16x16x32_bf16 v[100:103], v[160:163], v[192:195], v[100:103]
	v_mfma_f32_16x16x32_bf16 v[96:99], v[168:171], v[192:195], v[96:99]
	v_mfma_f32_16x16x32_bf16 v[84:87], v[160:163], v[200:203], v[84:87]
	v_mfma_f32_16x16x32_bf16 v[80:83], v[168:171], v[200:203], v[80:83]
	v_mfma_f32_16x16x32_bf16 v[68:71], v[160:163], v[208:211], v[68:71]
	v_mfma_f32_16x16x32_bf16 v[64:67], v[168:171], v[208:211], v[64:67]
	v_mfma_f32_16x16x32_bf16 v[116:119], v[164:167], v[188:191], v[116:119]
	v_mfma_f32_16x16x32_bf16 v[112:115], v[172:175], v[188:191], v[112:115]
	v_mfma_f32_16x16x32_bf16 v[100:103], v[164:167], v[196:199], v[100:103]
	v_mfma_f32_16x16x32_bf16 v[96:99], v[172:175], v[196:199], v[96:99]
	s_setprio 2
	s_barrier
	v_mfma_f32_16x16x32_bf16 v[84:87], v[164:167], v[204:207], v[84:87]
	v_mfma_f32_16x16x32_bf16 v[80:83], v[172:175], v[204:207], v[80:83]
	v_mfma_f32_16x16x32_bf16 v[68:71], v[164:167], v[212:215], v[68:71]
	v_mfma_f32_16x16x32_bf16 v[64:67], v[172:175], v[212:215], v[64:67]
	s_setprio 0
	s_add_i32 s44, s74, s51
	v_lshl_add_u64 v[176:177], v[176:177], 0, s[22:23]
	s_mov_b32 m0, s44
	ds_read_b128 v[184:187], v181 offset:49152
	ds_read_b128 v[188:191], v181 offset:50176
	ds_read_b128 v[192:195], v181 offset:51200
	ds_read_b128 v[196:199], v181 offset:52224
	ds_read_b128 v[200:203], v181 offset:53248
	ds_read_b128 v[204:207], v181 offset:54272
	ds_read_b128 v[208:211], v181 offset:55296
	ds_read_b128 v[212:215], v181 offset:56320
	global_load_lds_dwordx4 v[176:177], off
	s_add_i32 m0, s44, 0x2000
	s_add_u32 s40, s40, 0x40080
	v_lshl_add_u64 v[176:177], v[216:217], 0, s[22:23]
	s_addc_u32 s41, s41, 0
	s_add_i32 s44, s75, s51
	global_load_lds_dwordx4 v[176:177], off
	s_mov_b32 m0, s44
	v_lshl_add_u64 v[176:177], s[40:41], 0, v[130:131]
	global_load_lds_dwordx4 v[176:177], off
	s_add_i32 m0, s44, 0x2000
	v_lshl_add_u64 v[176:177], s[40:41], 0, v[134:135]
	global_load_lds_dwordx4 v[176:177], off
	s_mov_b32 m0, s64
	v_lshl_add_u64 v[176:177], v[218:219], 0, s[22:23]
	global_load_lds_dwordx4 v[176:177], off
	s_mov_b32 m0, s65
	v_lshl_add_u64 v[176:177], v[220:221], 0, s[22:23]
	global_load_lds_dwordx4 v[176:177], off
	s_waitcnt vmcnt(8)
	s_waitcnt lgkmcnt(0)
	s_barrier
	s_setprio 1
	s_waitcnt lgkmcnt(0)
	v_mfma_f32_16x16x32_bf16 v[60:63], v[144:147], v[184:187], v[60:63]
	v_mfma_f32_16x16x32_bf16 v[56:59], v[152:155], v[184:187], v[56:59]
	v_mfma_f32_16x16x32_bf16 v[44:47], v[144:147], v[192:195], v[44:47]
	v_mfma_f32_16x16x32_bf16 v[40:43], v[152:155], v[192:195], v[40:43]
	v_mfma_f32_16x16x32_bf16 v[28:31], v[144:147], v[200:203], v[28:31]
	v_mfma_f32_16x16x32_bf16 v[24:27], v[152:155], v[200:203], v[24:27]
	v_mfma_f32_16x16x32_bf16 v[12:15], v[144:147], v[208:211], v[12:15]
	v_mfma_f32_16x16x32_bf16 v[8:11], v[152:155], v[208:211], v[8:11]
	v_mfma_f32_16x16x32_bf16 v[60:63], v[148:151], v[188:191], v[60:63]
	v_mfma_f32_16x16x32_bf16 v[56:59], v[156:159], v[188:191], v[56:59]
	v_mfma_f32_16x16x32_bf16 v[44:47], v[148:151], v[196:199], v[44:47]
	v_mfma_f32_16x16x32_bf16 v[40:43], v[156:159], v[196:199], v[40:43]
	v_mfma_f32_16x16x32_bf16 v[28:31], v[148:151], v[204:207], v[28:31]
	v_mfma_f32_16x16x32_bf16 v[24:27], v[156:159], v[204:207], v[24:27]
	v_mfma_f32_16x16x32_bf16 v[12:15], v[148:151], v[212:215], v[12:15]
	v_mfma_f32_16x16x32_bf16 v[8:11], v[156:159], v[212:215], v[8:11]
	v_mfma_f32_16x16x32_bf16 v[52:55], v[160:163], v[184:187], v[52:55]
	v_mfma_f32_16x16x32_bf16 v[48:51], v[168:171], v[184:187], v[48:51]
	v_mfma_f32_16x16x32_bf16 v[36:39], v[160:163], v[192:195], v[36:39]
	v_mfma_f32_16x16x32_bf16 v[32:35], v[168:171], v[192:195], v[32:35]
	v_mfma_f32_16x16x32_bf16 v[20:23], v[160:163], v[200:203], v[20:23]
	v_mfma_f32_16x16x32_bf16 v[16:19], v[168:171], v[200:203], v[16:19]
	v_mfma_f32_16x16x32_bf16 v[4:7], v[160:163], v[208:211], v[4:7]
	v_mfma_f32_16x16x32_bf16 v[0:3], v[168:171], v[208:211], v[0:3]
	v_mfma_f32_16x16x32_bf16 v[52:55], v[164:167], v[188:191], v[52:55]
	v_mfma_f32_16x16x32_bf16 v[48:51], v[172:175], v[188:191], v[48:51]
	v_mfma_f32_16x16x32_bf16 v[36:39], v[164:167], v[196:199], v[36:39]
	v_mfma_f32_16x16x32_bf16 v[32:35], v[172:175], v[196:199], v[32:35]
	s_setprio 2
	s_barrier
	v_mfma_f32_16x16x32_bf16 v[20:23], v[164:167], v[204:207], v[20:23]
	v_mfma_f32_16x16x32_bf16 v[16:19], v[172:175], v[204:207], v[16:19]
	v_mfma_f32_16x16x32_bf16 v[4:7], v[164:167], v[212:215], v[4:7]
	v_mfma_f32_16x16x32_bf16 v[0:3], v[172:175], v[212:215], v[0:3]
	s_setprio 0
	s_add_i32 s73, s73, 2
	s_add_u32 s6, s6, 0x100
	s_addc_u32 s7, s7, 0
	s_add_u32 s71, s71, 0x100
	s_addc_u32 s72, s72, 0
	s_cmp_gt_u32 s73, 13
	s_cbranch_scc0 .LBB0_952

.LBB0_1145:
	s_ashr_i32 s23, s22, 31
	s_lshl_b64 s[26:27], s[22:23], 19
	s_add_u32 s26, s45, s26
	s_addc_u32 s27, s46, s27
	s_and_b64 s[28:29], s[4:5], exec
	s_cselect_b32 s23, s27, s39
	s_cselect_b32 s31, s26, s38
	s_ashr_i32 s25, s24, 31
	s_lshl_b64 s[28:29], s[24:25], 19
	s_add_u32 s28, s47, s28
	s_addc_u32 s29, s48, s29
	s_and_b64 s[42:43], s[4:5], exec
	s_cselect_b32 s25, s29, s41
	s_cselect_b32 s37, s28, s40
	s_add_u32 s38, s38, 0x40080
	s_addc_u32 s39, s39, 0
	s_add_u32 s64, s40, 0x100
	s_addc_u32 s65, s41, 0
	s_mov_b32 s66, -2
	ds_read_b128 v[120:123], v233
	ds_read_b128 v[132:135], v233 offset:1024
	ds_read_b128 v[136:139], v233 offset:2048
	ds_read_b128 v[140:143], v233 offset:3072
	ds_read_b128 v[144:147], v234
	ds_read_b128 v[148:151], v234 offset:1024
	ds_read_b128 v[152:155], v234 offset:2048
	ds_read_b128 v[156:159], v234 offset:3072
	s_add_u32 s40, s38, 0xfffc0080
	s_addc_u32 s41, s39, -1
	s_cmp_eq_u32 s66, 12
	s_cselect_b32 s43, s23, s41
	s_cselect_b32 s42, s31, s40
	s_cselect_b32 s41, s25, s65
	s_cselect_b32 s40, s37, s64
	v_lshl_add_u64 v[208:209], s[38:39], 0, v[192:193]
	s_add_i32 m0, s50, 0xc000
	ds_read_b128 v[160:163], v235
	ds_read_b128 v[164:167], v235 offset:1024
	ds_read_b128 v[168:171], v235 offset:2048
	ds_read_b128 v[172:175], v235 offset:3072
	ds_read_b128 v[176:179], v235 offset:4096
	ds_read_b128 v[180:183], v235 offset:5120
	ds_read_b128 v[200:203], v235 offset:6144
	ds_read_b128 v[204:207], v235 offset:7168
	global_load_lds_dwordx4 v[208:209], off
	s_add_i32 m0, s50, 0xe000
	v_lshl_add_u64 v[208:209], s[38:39], 0, v[194:195]
	global_load_lds_dwordx4 v[208:209], off
	s_waitcnt vmcnt(8)
	s_waitcnt lgkmcnt(0)
	s_barrier
	s_setprio 1
	s_waitcnt lgkmcnt(0)
	v_mfma_f32_16x16x32_bf16 v[128:131], v[120:123], v[160:163], 0
	v_mfma_f32_16x16x32_bf16 v[124:127], v[136:139], v[160:163], 0
	v_mfma_f32_16x16x32_bf16 v[108:111], v[120:123], v[168:171], 0
	v_mfma_f32_16x16x32_bf16 v[104:107], v[136:139], v[168:171], 0
	v_mfma_f32_16x16x32_bf16 v[92:95], v[120:123], v[176:179], 0
	v_mfma_f32_16x16x32_bf16 v[88:91], v[136:139], v[176:179], 0
	v_mfma_f32_16x16x32_bf16 v[76:79], v[120:123], v[200:203], 0
	v_mfma_f32_16x16x32_bf16 v[72:75], v[136:139], v[200:203], 0
	v_mfma_f32_16x16x32_bf16 v[128:131], v[132:135], v[164:167], v[128:131]
	v_mfma_f32_16x16x32_bf16 v[124:127], v[140:143], v[164:167], v[124:127]
	v_mfma_f32_16x16x32_bf16 v[108:111], v[132:135], v[172:175], v[108:111]
	v_mfma_f32_16x16x32_bf16 v[104:107], v[140:143], v[172:175], v[104:107]
	v_mfma_f32_16x16x32_bf16 v[92:95], v[132:135], v[180:183], v[92:95]
	v_mfma_f32_16x16x32_bf16 v[88:91], v[140:143], v[180:183], v[88:91]
	v_mfma_f32_16x16x32_bf16 v[76:79], v[132:135], v[204:207], v[76:79]
	v_mfma_f32_16x16x32_bf16 v[72:75], v[140:143], v[204:207], v[72:75]
	v_mfma_f32_16x16x32_bf16 v[116:119], v[144:147], v[160:163], 0
	v_mfma_f32_16x16x32_bf16 v[112:115], v[152:155], v[160:163], 0
	v_mfma_f32_16x16x32_bf16 v[100:103], v[144:147], v[168:171], 0
	v_mfma_f32_16x16x32_bf16 v[96:99], v[152:155], v[168:171], 0
	v_mfma_f32_16x16x32_bf16 v[84:87], v[144:147], v[176:179], 0
	v_mfma_f32_16x16x32_bf16 v[80:83], v[152:155], v[176:179], 0
	v_mfma_f32_16x16x32_bf16 v[68:71], v[144:147], v[200:203], 0
	v_mfma_f32_16x16x32_bf16 v[64:67], v[152:155], v[200:203], 0
	v_mfma_f32_16x16x32_bf16 v[116:119], v[148:151], v[164:167], v[116:119]
	v_mfma_f32_16x16x32_bf16 v[112:115], v[156:159], v[164:167], v[112:115]
	v_mfma_f32_16x16x32_bf16 v[100:103], v[148:151], v[172:175], v[100:103]
	v_mfma_f32_16x16x32_bf16 v[96:99], v[156:159], v[172:175], v[96:99]
	s_setprio 2
	s_barrier
	v_mfma_f32_16x16x32_bf16 v[84:87], v[148:151], v[180:183], v[84:87]
	v_mfma_f32_16x16x32_bf16 v[80:83], v[156:159], v[180:183], v[80:83]
	v_mfma_f32_16x16x32_bf16 v[68:71], v[148:151], v[204:207], v[68:71]
	v_mfma_f32_16x16x32_bf16 v[64:67], v[156:159], v[204:207], v[64:67]
	s_setprio 0
	s_add_i32 s67, s62, s49
	v_lshl_add_u64 v[208:209], s[40:41], 0, v[186:187]
	s_mov_b32 m0, s67
	ds_read_b128 v[160:163], v235 offset:16384
	ds_read_b128 v[164:167], v235 offset:17408
	ds_read_b128 v[168:171], v235 offset:18432
	ds_read_b128 v[172:175], v235 offset:19456
	ds_read_b128 v[176:179], v235 offset:20480
	ds_read_b128 v[180:183], v235 offset:21504
	ds_read_b128 v[200:203], v235 offset:22528
	ds_read_b128 v[204:207], v235 offset:23552
	global_load_lds_dwordx4 v[208:209], off
	s_add_i32 m0, s67, 0x2000
	s_add_u32 s68, s40, 0x40000
	v_lshl_add_u64 v[210:211], s[40:41], 0, v[190:191]
	s_addc_u32 s69, s41, 0
	s_add_i32 s67, s63, s49
	global_load_lds_dwordx4 v[210:211], off
	v_lshl_add_u64 v[212:213], s[68:69], 0, v[186:187]
	s_mov_b32 m0, s67
	v_lshl_add_u64 v[214:215], s[42:43], 0, v[188:189]
	global_load_lds_dwordx4 v[212:213], off
	s_add_i32 m0, s67, 0x2000
	v_lshl_add_u64 v[212:213], s[68:69], 0, v[190:191]
	global_load_lds_dwordx4 v[212:213], off
	s_mov_b32 m0, s50
	v_lshl_add_u64 v[212:213], s[42:43], 0, v[184:185]
	global_load_lds_dwordx4 v[212:213], off
	s_mov_b32 m0, s51
	s_nop 0
	global_load_lds_dwordx4 v[214:215], off
	s_waitcnt vmcnt(8)
	s_waitcnt lgkmcnt(0)
	s_barrier
	s_setprio 1
	s_waitcnt lgkmcnt(0)
	v_mfma_f32_16x16x32_bf16 v[60:63], v[120:123], v[160:163], 0
	v_mfma_f32_16x16x32_bf16 v[56:59], v[136:139], v[160:163], 0
	v_mfma_f32_16x16x32_bf16 v[44:47], v[120:123], v[168:171], 0
	v_mfma_f32_16x16x32_bf16 v[40:43], v[136:139], v[168:171], 0
	v_mfma_f32_16x16x32_bf16 v[28:31], v[120:123], v[176:179], 0
	v_mfma_f32_16x16x32_bf16 v[24:27], v[136:139], v[176:179], 0
	v_mfma_f32_16x16x32_bf16 v[12:15], v[120:123], v[200:203], 0
	v_mfma_f32_16x16x32_bf16 v[8:11], v[136:139], v[200:203], 0
	v_mfma_f32_16x16x32_bf16 v[60:63], v[132:135], v[164:167], v[60:63]
	v_mfma_f32_16x16x32_bf16 v[56:59], v[140:143], v[164:167], v[56:59]
	v_mfma_f32_16x16x32_bf16 v[44:47], v[132:135], v[172:175], v[44:47]
	v_mfma_f32_16x16x32_bf16 v[40:43], v[140:143], v[172:175], v[40:43]
	v_mfma_f32_16x16x32_bf16 v[28:31], v[132:135], v[180:183], v[28:31]
	v_mfma_f32_16x16x32_bf16 v[24:27], v[140:143], v[180:183], v[24:27]
	v_mfma_f32_16x16x32_bf16 v[12:15], v[132:135], v[204:207], v[12:15]
	v_mfma_f32_16x16x32_bf16 v[8:11], v[140:143], v[204:207], v[8:11]
	v_mfma_f32_16x16x32_bf16 v[52:55], v[144:147], v[160:163], 0
	v_mfma_f32_16x16x32_bf16 v[48:51], v[152:155], v[160:163], 0
	v_mfma_f32_16x16x32_bf16 v[36:39], v[144:147], v[168:171], 0
	v_mfma_f32_16x16x32_bf16 v[32:35], v[152:155], v[168:171], 0
	v_mfma_f32_16x16x32_bf16 v[20:23], v[144:147], v[176:179], 0
	v_mfma_f32_16x16x32_bf16 v[16:19], v[152:155], v[176:179], 0
	v_mfma_f32_16x16x32_bf16 v[4:7], v[144:147], v[200:203], 0
	v_mfma_f32_16x16x32_bf16 v[0:3], v[152:155], v[200:203], 0
	v_mfma_f32_16x16x32_bf16 v[52:55], v[148:151], v[164:167], v[52:55]
	v_mfma_f32_16x16x32_bf16 v[48:51], v[156:159], v[164:167], v[48:51]
	v_mfma_f32_16x16x32_bf16 v[36:39], v[148:151], v[172:175], v[36:39]
	v_mfma_f32_16x16x32_bf16 v[32:35], v[156:159], v[172:175], v[32:35]
	s_setprio 2
	s_barrier
	v_mfma_f32_16x16x32_bf16 v[20:23], v[148:151], v[180:183], v[20:23]
	v_mfma_f32_16x16x32_bf16 v[16:19], v[156:159], v[180:183], v[16:19]
	v_mfma_f32_16x16x32_bf16 v[4:7], v[148:151], v[204:207], v[4:7]
	v_mfma_f32_16x16x32_bf16 v[0:3], v[156:159], v[204:207], v[0:3]
	s_setprio 0
	s_add_i32 s67, 0, 0x18000
	s_add_i32 s68, 0, 0x1c000
	v_add_u32_e32 v140, s67, v232
	v_add_u32_e32 v156, s68, v232
	ds_read_b128 v[120:123], v140
	ds_read_b128 v[132:135], v140 offset:1024
	ds_read_b128 v[136:139], v140 offset:2048
	ds_read_b128 v[140:143], v140 offset:3072
	ds_read_b128 v[144:147], v156
	ds_read_b128 v[148:151], v156 offset:1024
	ds_read_b128 v[152:155], v156 offset:2048
	ds_read_b128 v[156:159], v156 offset:3072
	s_add_u32 s42, s42, 0x40000
	s_addc_u32 s43, s43, 0
	s_mov_b32 m0, s54
	v_lshl_add_u64 v[216:217], s[42:43], 0, v[184:185]
	ds_read_b128 v[160:163], v235 offset:32768
	ds_read_b128 v[164:167], v235 offset:33792
	ds_read_b128 v[168:171], v235 offset:34816
	ds_read_b128 v[172:175], v235 offset:35840
	ds_read_b128 v[176:179], v235 offset:36864
	ds_read_b128 v[180:183], v235 offset:37888
	ds_read_b128 v[200:203], v235 offset:38912
	ds_read_b128 v[204:207], v235 offset:39936
	global_load_lds_dwordx4 v[216:217], off
	s_mov_b32 m0, s55
	v_lshl_add_u64 v[216:217], s[42:43], 0, v[188:189]
	global_load_lds_dwordx4 v[216:217], off
	s_waitcnt vmcnt(8)
	s_waitcnt lgkmcnt(0)
	s_barrier
	s_setprio 1
	s_waitcnt lgkmcnt(0)
	v_mfma_f32_16x16x32_bf16 v[128:131], v[120:123], v[160:163], v[128:131]
	v_mfma_f32_16x16x32_bf16 v[124:127], v[136:139], v[160:163], v[124:127]
	v_mfma_f32_16x16x32_bf16 v[108:111], v[120:123], v[168:171], v[108:111]
	v_mfma_f32_16x16x32_bf16 v[104:107], v[136:139], v[168:171], v[104:107]
	v_mfma_f32_16x16x32_bf16 v[92:95], v[120:123], v[176:179], v[92:95]
	v_mfma_f32_16x16x32_bf16 v[88:91], v[136:139], v[176:179], v[88:91]
	v_mfma_f32_16x16x32_bf16 v[76:79], v[120:123], v[200:203], v[76:79]
	v_mfma_f32_16x16x32_bf16 v[72:75], v[136:139], v[200:203], v[72:75]
	v_mfma_f32_16x16x32_bf16 v[128:131], v[132:135], v[164:167], v[128:131]
	v_mfma_f32_16x16x32_bf16 v[124:127], v[140:143], v[164:167], v[124:127]
	v_mfma_f32_16x16x32_bf16 v[108:111], v[132:135], v[172:175], v[108:111]
	v_mfma_f32_16x16x32_bf16 v[104:107], v[140:143], v[172:175], v[104:107]
	v_mfma_f32_16x16x32_bf16 v[92:95], v[132:135], v[180:183], v[92:95]
	v_mfma_f32_16x16x32_bf16 v[88:91], v[140:143], v[180:183], v[88:91]
	v_mfma_f32_16x16x32_bf16 v[76:79], v[132:135], v[204:207], v[76:79]
	v_mfma_f32_16x16x32_bf16 v[72:75], v[140:143], v[204:207], v[72:75]
	v_mfma_f32_16x16x32_bf16 v[116:119], v[144:147], v[160:163], v[116:119]
	v_mfma_f32_16x16x32_bf16 v[112:115], v[152:155], v[160:163], v[112:115]
	v_mfma_f32_16x16x32_bf16 v[100:103], v[144:147], v[168:171], v[100:103]
	v_mfma_f32_16x16x32_bf16 v[96:99], v[152:155], v[168:171], v[96:99]
	v_mfma_f32_16x16x32_bf16 v[84:87], v[144:147], v[176:179], v[84:87]
	v_mfma_f32_16x16x32_bf16 v[80:83], v[152:155], v[176:179], v[80:83]
	v_mfma_f32_16x16x32_bf16 v[68:71], v[144:147], v[200:203], v[68:71]
	v_mfma_f32_16x16x32_bf16 v[64:67], v[152:155], v[200:203], v[64:67]
	v_mfma_f32_16x16x32_bf16 v[116:119], v[148:151], v[164:167], v[116:119]
	v_mfma_f32_16x16x32_bf16 v[112:115], v[156:159], v[164:167], v[112:115]
	v_mfma_f32_16x16x32_bf16 v[100:103], v[148:151], v[172:175], v[100:103]
	v_mfma_f32_16x16x32_bf16 v[96:99], v[156:159], v[172:175], v[96:99]
	s_setprio 2
	s_barrier
	v_mfma_f32_16x16x32_bf16 v[84:87], v[148:151], v[180:183], v[84:87]
	v_mfma_f32_16x16x32_bf16 v[80:83], v[156:159], v[180:183], v[80:83]
	v_mfma_f32_16x16x32_bf16 v[68:71], v[148:151], v[204:207], v[68:71]
	v_mfma_f32_16x16x32_bf16 v[64:67], v[156:159], v[204:207], v[64:67]
	s_setprio 0
	s_add_i32 s42, s67, s49
	v_lshl_add_u64 v[208:209], v[208:209], 0, s[18:19]
	s_mov_b32 m0, s42
	ds_read_b128 v[160:163], v235 offset:49152
	ds_read_b128 v[164:167], v235 offset:50176
	ds_read_b128 v[168:171], v235 offset:51200
	ds_read_b128 v[172:175], v235 offset:52224
	ds_read_b128 v[176:179], v235 offset:53248
	ds_read_b128 v[180:183], v235 offset:54272
	ds_read_b128 v[200:203], v235 offset:55296
	ds_read_b128 v[204:207], v235 offset:56320
	global_load_lds_dwordx4 v[208:209], off
	s_add_i32 m0, s42, 0x2000
	s_add_u32 s40, s40, 0x40080
	v_lshl_add_u64 v[208:209], v[210:211], 0, s[18:19]
	s_addc_u32 s41, s41, 0
	s_add_i32 s42, s68, s49
	global_load_lds_dwordx4 v[208:209], off
	s_mov_b32 m0, s42
	v_lshl_add_u64 v[208:209], s[40:41], 0, v[186:187]
	global_load_lds_dwordx4 v[208:209], off
	s_add_i32 m0, s42, 0x2000
	v_lshl_add_u64 v[208:209], s[40:41], 0, v[190:191]
	global_load_lds_dwordx4 v[208:209], off
	s_mov_b32 m0, s57
	v_lshl_add_u64 v[208:209], v[212:213], 0, s[18:19]
	global_load_lds_dwordx4 v[208:209], off
	s_mov_b32 m0, s58
	v_lshl_add_u64 v[208:209], v[214:215], 0, s[18:19]
	global_load_lds_dwordx4 v[208:209], off
	s_waitcnt vmcnt(8)
	s_waitcnt lgkmcnt(0)
	s_barrier
	s_setprio 1
	s_waitcnt lgkmcnt(0)
	v_mfma_f32_16x16x32_bf16 v[60:63], v[120:123], v[160:163], v[60:63]
	v_mfma_f32_16x16x32_bf16 v[56:59], v[136:139], v[160:163], v[56:59]
	v_mfma_f32_16x16x32_bf16 v[44:47], v[120:123], v[168:171], v[44:47]
	v_mfma_f32_16x16x32_bf16 v[40:43], v[136:139], v[168:171], v[40:43]
	v_mfma_f32_16x16x32_bf16 v[28:31], v[120:123], v[176:179], v[28:31]
	v_mfma_f32_16x16x32_bf16 v[24:27], v[136:139], v[176:179], v[24:27]
	v_mfma_f32_16x16x32_bf16 v[12:15], v[120:123], v[200:203], v[12:15]
	v_mfma_f32_16x16x32_bf16 v[8:11], v[136:139], v[200:203], v[8:11]
	v_mfma_f32_16x16x32_bf16 v[60:63], v[132:135], v[164:167], v[60:63]
	v_mfma_f32_16x16x32_bf16 v[56:59], v[140:143], v[164:167], v[56:59]
	v_mfma_f32_16x16x32_bf16 v[44:47], v[132:135], v[172:175], v[44:47]
	v_mfma_f32_16x16x32_bf16 v[40:43], v[140:143], v[172:175], v[40:43]
	v_mfma_f32_16x16x32_bf16 v[28:31], v[132:135], v[180:183], v[28:31]
	v_mfma_f32_16x16x32_bf16 v[24:27], v[140:143], v[180:183], v[24:27]
	v_mfma_f32_16x16x32_bf16 v[12:15], v[132:135], v[204:207], v[12:15]
	v_mfma_f32_16x16x32_bf16 v[8:11], v[140:143], v[204:207], v[8:11]
	v_mfma_f32_16x16x32_bf16 v[52:55], v[144:147], v[160:163], v[52:55]
	v_mfma_f32_16x16x32_bf16 v[48:51], v[152:155], v[160:163], v[48:51]
	v_mfma_f32_16x16x32_bf16 v[36:39], v[144:147], v[168:171], v[36:39]
	v_mfma_f32_16x16x32_bf16 v[32:35], v[152:155], v[168:171], v[32:35]
	v_mfma_f32_16x16x32_bf16 v[20:23], v[144:147], v[176:179], v[20:23]
	v_mfma_f32_16x16x32_bf16 v[16:19], v[152:155], v[176:179], v[16:19]
	v_mfma_f32_16x16x32_bf16 v[4:7], v[144:147], v[200:203], v[4:7]
	v_mfma_f32_16x16x32_bf16 v[0:3], v[152:155], v[200:203], v[0:3]
	v_mfma_f32_16x16x32_bf16 v[52:55], v[148:151], v[164:167], v[52:55]
	v_mfma_f32_16x16x32_bf16 v[48:51], v[156:159], v[164:167], v[48:51]
	v_mfma_f32_16x16x32_bf16 v[36:39], v[148:151], v[172:175], v[36:39]
	v_mfma_f32_16x16x32_bf16 v[32:35], v[156:159], v[172:175], v[32:35]
	s_setprio 2
	s_barrier
	v_mfma_f32_16x16x32_bf16 v[20:23], v[148:151], v[180:183], v[20:23]
	v_mfma_f32_16x16x32_bf16 v[16:19], v[156:159], v[180:183], v[16:19]
	v_mfma_f32_16x16x32_bf16 v[4:7], v[148:151], v[204:207], v[4:7]
	v_mfma_f32_16x16x32_bf16 v[0:3], v[156:159], v[204:207], v[0:3]
	s_setprio 0
	s_add_i32 s66, s66, 2
	s_add_u32 s38, s38, 0x100
	s_addc_u32 s39, s39, 0
	s_add_u32 s64, s64, 0x100
	s_addc_u32 s65, s65, 0
	s_cmp_gt_u32 s66, 13
.LBB0_1146:
	ds_read_b128 v[120:123], v233
	ds_read_b128 v[132:135], v233 offset:1024
	ds_read_b128 v[136:139], v233 offset:2048
	ds_read_b128 v[140:143], v233 offset:3072
	ds_read_b128 v[144:147], v234
	ds_read_b128 v[148:151], v234 offset:1024
	ds_read_b128 v[152:155], v234 offset:2048
	ds_read_b128 v[156:159], v234 offset:3072
	s_add_u32 s40, s38, 0xfffc0080
	s_addc_u32 s41, s39, -1
	s_cmp_eq_u32 s66, 12
	s_cselect_b32 s43, s23, s41
	s_cselect_b32 s42, s31, s40
	s_cselect_b32 s41, s25, s65
	s_cselect_b32 s40, s37, s64
	v_lshl_add_u64 v[208:209], s[38:39], 0, v[192:193]
	s_add_i32 m0, s50, 0xc000
	ds_read_b128 v[160:163], v235
	ds_read_b128 v[164:167], v235 offset:1024
	ds_read_b128 v[168:171], v235 offset:2048
	ds_read_b128 v[172:175], v235 offset:3072
	ds_read_b128 v[176:179], v235 offset:4096
	ds_read_b128 v[180:183], v235 offset:5120
	ds_read_b128 v[200:203], v235 offset:6144
	ds_read_b128 v[204:207], v235 offset:7168
	global_load_lds_dwordx4 v[208:209], off
	s_add_i32 m0, s50, 0xe000
	v_lshl_add_u64 v[208:209], s[38:39], 0, v[194:195]
	global_load_lds_dwordx4 v[208:209], off
	s_waitcnt vmcnt(8)
	s_waitcnt lgkmcnt(0)
	s_barrier
	s_setprio 1
	s_waitcnt lgkmcnt(0)
	v_mfma_f32_16x16x32_bf16 v[128:131], v[120:123], v[160:163], v[128:131]
	v_mfma_f32_16x16x32_bf16 v[124:127], v[136:139], v[160:163], v[124:127]
	v_mfma_f32_16x16x32_bf16 v[108:111], v[120:123], v[168:171], v[108:111]
	v_mfma_f32_16x16x32_bf16 v[104:107], v[136:139], v[168:171], v[104:107]
	v_mfma_f32_16x16x32_bf16 v[92:95], v[120:123], v[176:179], v[92:95]
	v_mfma_f32_16x16x32_bf16 v[88:91], v[136:139], v[176:179], v[88:91]
	v_mfma_f32_16x16x32_bf16 v[76:79], v[120:123], v[200:203], v[76:79]
	v_mfma_f32_16x16x32_bf16 v[72:75], v[136:139], v[200:203], v[72:75]
	v_mfma_f32_16x16x32_bf16 v[128:131], v[132:135], v[164:167], v[128:131]
	v_mfma_f32_16x16x32_bf16 v[124:127], v[140:143], v[164:167], v[124:127]
	v_mfma_f32_16x16x32_bf16 v[108:111], v[132:135], v[172:175], v[108:111]
	v_mfma_f32_16x16x32_bf16 v[104:107], v[140:143], v[172:175], v[104:107]
	v_mfma_f32_16x16x32_bf16 v[92:95], v[132:135], v[180:183], v[92:95]
	v_mfma_f32_16x16x32_bf16 v[88:91], v[140:143], v[180:183], v[88:91]
	v_mfma_f32_16x16x32_bf16 v[76:79], v[132:135], v[204:207], v[76:79]
	v_mfma_f32_16x16x32_bf16 v[72:75], v[140:143], v[204:207], v[72:75]
	v_mfma_f32_16x16x32_bf16 v[116:119], v[144:147], v[160:163], v[116:119]
	v_mfma_f32_16x16x32_bf16 v[112:115], v[152:155], v[160:163], v[112:115]
	v_mfma_f32_16x16x32_bf16 v[100:103], v[144:147], v[168:171], v[100:103]
	v_mfma_f32_16x16x32_bf16 v[96:99], v[152:155], v[168:171], v[96:99]
	v_mfma_f32_16x16x32_bf16 v[84:87], v[144:147], v[176:179], v[84:87]
	v_mfma_f32_16x16x32_bf16 v[80:83], v[152:155], v[176:179], v[80:83]
	v_mfma_f32_16x16x32_bf16 v[68:71], v[144:147], v[200:203], v[68:71]
	v_mfma_f32_16x16x32_bf16 v[64:67], v[152:155], v[200:203], v[64:67]
	v_mfma_f32_16x16x32_bf16 v[116:119], v[148:151], v[164:167], v[116:119]
	v_mfma_f32_16x16x32_bf16 v[112:115], v[156:159], v[164:167], v[112:115]
	v_mfma_f32_16x16x32_bf16 v[100:103], v[148:151], v[172:175], v[100:103]
	v_mfma_f32_16x16x32_bf16 v[96:99], v[156:159], v[172:175], v[96:99]
	s_setprio 2
	s_barrier
	v_mfma_f32_16x16x32_bf16 v[84:87], v[148:151], v[180:183], v[84:87]
	v_mfma_f32_16x16x32_bf16 v[80:83], v[156:159], v[180:183], v[80:83]
	v_mfma_f32_16x16x32_bf16 v[68:71], v[148:151], v[204:207], v[68:71]
	v_mfma_f32_16x16x32_bf16 v[64:67], v[156:159], v[204:207], v[64:67]
	s_setprio 0
	s_add_i32 s67, s62, s49
	v_lshl_add_u64 v[208:209], s[40:41], 0, v[186:187]
	s_mov_b32 m0, s67
	ds_read_b128 v[160:163], v235 offset:16384
	ds_read_b128 v[164:167], v235 offset:17408
	ds_read_b128 v[168:171], v235 offset:18432
	ds_read_b128 v[172:175], v235 offset:19456
	ds_read_b128 v[176:179], v235 offset:20480
	ds_read_b128 v[180:183], v235 offset:21504
	ds_read_b128 v[200:203], v235 offset:22528
	ds_read_b128 v[204:207], v235 offset:23552
	global_load_lds_dwordx4 v[208:209], off
	s_add_i32 m0, s67, 0x2000
	s_add_u32 s68, s40, 0x40000
	v_lshl_add_u64 v[210:211], s[40:41], 0, v[190:191]
	s_addc_u32 s69, s41, 0
	s_add_i32 s67, s63, s49
	global_load_lds_dwordx4 v[210:211], off
	v_lshl_add_u64 v[212:213], s[68:69], 0, v[186:187]
	s_mov_b32 m0, s67
	v_lshl_add_u64 v[214:215], s[42:43], 0, v[188:189]
	global_load_lds_dwordx4 v[212:213], off
	s_add_i32 m0, s67, 0x2000
	v_lshl_add_u64 v[212:213], s[68:69], 0, v[190:191]
	global_load_lds_dwordx4 v[212:213], off
	s_mov_b32 m0, s50
	v_lshl_add_u64 v[212:213], s[42:43], 0, v[184:185]
	global_load_lds_dwordx4 v[212:213], off
	s_mov_b32 m0, s51
	s_nop 0
	global_load_lds_dwordx4 v[214:215], off
	s_waitcnt vmcnt(8)
	s_waitcnt lgkmcnt(0)
	s_barrier
	s_setprio 1
	s_waitcnt lgkmcnt(0)
	v_mfma_f32_16x16x32_bf16 v[60:63], v[120:123], v[160:163], v[60:63]
	v_mfma_f32_16x16x32_bf16 v[56:59], v[136:139], v[160:163], v[56:59]
	v_mfma_f32_16x16x32_bf16 v[44:47], v[120:123], v[168:171], v[44:47]
	v_mfma_f32_16x16x32_bf16 v[40:43], v[136:139], v[168:171], v[40:43]
	v_mfma_f32_16x16x32_bf16 v[28:31], v[120:123], v[176:179], v[28:31]
	v_mfma_f32_16x16x32_bf16 v[24:27], v[136:139], v[176:179], v[24:27]
	v_mfma_f32_16x16x32_bf16 v[12:15], v[120:123], v[200:203], v[12:15]
	v_mfma_f32_16x16x32_bf16 v[8:11], v[136:139], v[200:203], v[8:11]
	v_mfma_f32_16x16x32_bf16 v[60:63], v[132:135], v[164:167], v[60:63]
	v_mfma_f32_16x16x32_bf16 v[56:59], v[140:143], v[164:167], v[56:59]
	v_mfma_f32_16x16x32_bf16 v[44:47], v[132:135], v[172:175], v[44:47]
	v_mfma_f32_16x16x32_bf16 v[40:43], v[140:143], v[172:175], v[40:43]
	v_mfma_f32_16x16x32_bf16 v[28:31], v[132:135], v[180:183], v[28:31]
	v_mfma_f32_16x16x32_bf16 v[24:27], v[140:143], v[180:183], v[24:27]
	v_mfma_f32_16x16x32_bf16 v[12:15], v[132:135], v[204:207], v[12:15]
	v_mfma_f32_16x16x32_bf16 v[8:11], v[140:143], v[204:207], v[8:11]
	v_mfma_f32_16x16x32_bf16 v[52:55], v[144:147], v[160:163], v[52:55]
	v_mfma_f32_16x16x32_bf16 v[48:51], v[152:155], v[160:163], v[48:51]
	v_mfma_f32_16x16x32_bf16 v[36:39], v[144:147], v[168:171], v[36:39]
	v_mfma_f32_16x16x32_bf16 v[32:35], v[152:155], v[168:171], v[32:35]
	v_mfma_f32_16x16x32_bf16 v[20:23], v[144:147], v[176:179], v[20:23]
	v_mfma_f32_16x16x32_bf16 v[16:19], v[152:155], v[176:179], v[16:19]
	v_mfma_f32_16x16x32_bf16 v[4:7], v[144:147], v[200:203], v[4:7]
	v_mfma_f32_16x16x32_bf16 v[0:3], v[152:155], v[200:203], v[0:3]
	v_mfma_f32_16x16x32_bf16 v[52:55], v[148:151], v[164:167], v[52:55]
	v_mfma_f32_16x16x32_bf16 v[48:51], v[156:159], v[164:167], v[48:51]
	v_mfma_f32_16x16x32_bf16 v[36:39], v[148:151], v[172:175], v[36:39]
	v_mfma_f32_16x16x32_bf16 v[32:35], v[156:159], v[172:175], v[32:35]
	s_setprio 2
	s_barrier
	v_mfma_f32_16x16x32_bf16 v[20:23], v[148:151], v[180:183], v[20:23]
	v_mfma_f32_16x16x32_bf16 v[16:19], v[156:159], v[180:183], v[16:19]
	v_mfma_f32_16x16x32_bf16 v[4:7], v[148:151], v[204:207], v[4:7]
	v_mfma_f32_16x16x32_bf16 v[0:3], v[156:159], v[204:207], v[0:3]
	s_setprio 0
	s_add_i32 s67, 0, 0x18000
	s_add_i32 s68, 0, 0x1c000
	v_add_u32_e32 v140, s67, v232
	v_add_u32_e32 v156, s68, v232
	ds_read_b128 v[120:123], v140
	ds_read_b128 v[132:135], v140 offset:1024
	ds_read_b128 v[136:139], v140 offset:2048
	ds_read_b128 v[140:143], v140 offset:3072
	ds_read_b128 v[144:147], v156
	ds_read_b128 v[148:151], v156 offset:1024
	ds_read_b128 v[152:155], v156 offset:2048
	ds_read_b128 v[156:159], v156 offset:3072
	s_add_u32 s42, s42, 0x40000
	s_addc_u32 s43, s43, 0
	s_mov_b32 m0, s54
	v_lshl_add_u64 v[216:217], s[42:43], 0, v[184:185]
	ds_read_b128 v[160:163], v235 offset:32768
	ds_read_b128 v[164:167], v235 offset:33792
	ds_read_b128 v[168:171], v235 offset:34816
	ds_read_b128 v[172:175], v235 offset:35840
	ds_read_b128 v[176:179], v235 offset:36864
	ds_read_b128 v[180:183], v235 offset:37888
	ds_read_b128 v[200:203], v235 offset:38912
	ds_read_b128 v[204:207], v235 offset:39936
	global_load_lds_dwordx4 v[216:217], off
	s_mov_b32 m0, s55
	v_lshl_add_u64 v[216:217], s[42:43], 0, v[188:189]
	global_load_lds_dwordx4 v[216:217], off
	s_waitcnt vmcnt(8)
	s_waitcnt lgkmcnt(0)
	s_barrier
	s_setprio 1
	s_waitcnt lgkmcnt(0)
	v_mfma_f32_16x16x32_bf16 v[128:131], v[120:123], v[160:163], v[128:131]
	v_mfma_f32_16x16x32_bf16 v[124:127], v[136:139], v[160:163], v[124:127]
	v_mfma_f32_16x16x32_bf16 v[108:111], v[120:123], v[168:171], v[108:111]
	v_mfma_f32_16x16x32_bf16 v[104:107], v[136:139], v[168:171], v[104:107]
	v_mfma_f32_16x16x32_bf16 v[92:95], v[120:123], v[176:179], v[92:95]
	v_mfma_f32_16x16x32_bf16 v[88:91], v[136:139], v[176:179], v[88:91]
	v_mfma_f32_16x16x32_bf16 v[76:79], v[120:123], v[200:203], v[76:79]
	v_mfma_f32_16x16x32_bf16 v[72:75], v[136:139], v[200:203], v[72:75]
	v_mfma_f32_16x16x32_bf16 v[128:131], v[132:135], v[164:167], v[128:131]
	v_mfma_f32_16x16x32_bf16 v[124:127], v[140:143], v[164:167], v[124:127]
	v_mfma_f32_16x16x32_bf16 v[108:111], v[132:135], v[172:175], v[108:111]
	v_mfma_f32_16x16x32_bf16 v[104:107], v[140:143], v[172:175], v[104:107]
	v_mfma_f32_16x16x32_bf16 v[92:95], v[132:135], v[180:183], v[92:95]
	v_mfma_f32_16x16x32_bf16 v[88:91], v[140:143], v[180:183], v[88:91]
	v_mfma_f32_16x16x32_bf16 v[76:79], v[132:135], v[204:207], v[76:79]
	v_mfma_f32_16x16x32_bf16 v[72:75], v[140:143], v[204:207], v[72:75]
	v_mfma_f32_16x16x32_bf16 v[116:119], v[144:147], v[160:163], v[116:119]
	v_mfma_f32_16x16x32_bf16 v[112:115], v[152:155], v[160:163], v[112:115]
	v_mfma_f32_16x16x32_bf16 v[100:103], v[144:147], v[168:171], v[100:103]
	v_mfma_f32_16x16x32_bf16 v[96:99], v[152:155], v[168:171], v[96:99]
	v_mfma_f32_16x16x32_bf16 v[84:87], v[144:147], v[176:179], v[84:87]
	v_mfma_f32_16x16x32_bf16 v[80:83], v[152:155], v[176:179], v[80:83]
	v_mfma_f32_16x16x32_bf16 v[68:71], v[144:147], v[200:203], v[68:71]
	v_mfma_f32_16x16x32_bf16 v[64:67], v[152:155], v[200:203], v[64:67]
	v_mfma_f32_16x16x32_bf16 v[116:119], v[148:151], v[164:167], v[116:119]
	v_mfma_f32_16x16x32_bf16 v[112:115], v[156:159], v[164:167], v[112:115]
	v_mfma_f32_16x16x32_bf16 v[100:103], v[148:151], v[172:175], v[100:103]
	v_mfma_f32_16x16x32_bf16 v[96:99], v[156:159], v[172:175], v[96:99]
	s_setprio 2
	s_barrier
	v_mfma_f32_16x16x32_bf16 v[84:87], v[148:151], v[180:183], v[84:87]
	v_mfma_f32_16x16x32_bf16 v[80:83], v[156:159], v[180:183], v[80:83]
	v_mfma_f32_16x16x32_bf16 v[68:71], v[148:151], v[204:207], v[68:71]
	v_mfma_f32_16x16x32_bf16 v[64:67], v[156:159], v[204:207], v[64:67]
	s_setprio 0
	s_add_i32 s42, s67, s49
	v_lshl_add_u64 v[208:209], v[208:209], 0, s[18:19]
	s_mov_b32 m0, s42
	ds_read_b128 v[160:163], v235 offset:49152
	ds_read_b128 v[164:167], v235 offset:50176
	ds_read_b128 v[168:171], v235 offset:51200
	ds_read_b128 v[172:175], v235 offset:52224
	ds_read_b128 v[176:179], v235 offset:53248
	ds_read_b128 v[180:183], v235 offset:54272
	ds_read_b128 v[200:203], v235 offset:55296
	ds_read_b128 v[204:207], v235 offset:56320
	global_load_lds_dwordx4 v[208:209], off
	s_add_i32 m0, s42, 0x2000
	s_add_u32 s40, s40, 0x40080
	v_lshl_add_u64 v[208:209], v[210:211], 0, s[18:19]
	s_addc_u32 s41, s41, 0
	s_add_i32 s42, s68, s49
	global_load_lds_dwordx4 v[208:209], off
	s_mov_b32 m0, s42
	v_lshl_add_u64 v[208:209], s[40:41], 0, v[186:187]
	global_load_lds_dwordx4 v[208:209], off
	s_add_i32 m0, s42, 0x2000
	v_lshl_add_u64 v[208:209], s[40:41], 0, v[190:191]
	global_load_lds_dwordx4 v[208:209], off
	s_mov_b32 m0, s57
	v_lshl_add_u64 v[208:209], v[212:213], 0, s[18:19]
	global_load_lds_dwordx4 v[208:209], off
	s_mov_b32 m0, s58
	v_lshl_add_u64 v[208:209], v[214:215], 0, s[18:19]
	global_load_lds_dwordx4 v[208:209], off
	s_waitcnt vmcnt(8)
	s_waitcnt lgkmcnt(0)
	s_barrier
	s_setprio 1
	s_waitcnt lgkmcnt(0)
	v_mfma_f32_16x16x32_bf16 v[60:63], v[120:123], v[160:163], v[60:63]
	v_mfma_f32_16x16x32_bf16 v[56:59], v[136:139], v[160:163], v[56:59]
	v_mfma_f32_16x16x32_bf16 v[44:47], v[120:123], v[168:171], v[44:47]
	v_mfma_f32_16x16x32_bf16 v[40:43], v[136:139], v[168:171], v[40:43]
	v_mfma_f32_16x16x32_bf16 v[28:31], v[120:123], v[176:179], v[28:31]
	v_mfma_f32_16x16x32_bf16 v[24:27], v[136:139], v[176:179], v[24:27]
	v_mfma_f32_16x16x32_bf16 v[12:15], v[120:123], v[200:203], v[12:15]
	v_mfma_f32_16x16x32_bf16 v[8:11], v[136:139], v[200:203], v[8:11]
	v_mfma_f32_16x16x32_bf16 v[60:63], v[132:135], v[164:167], v[60:63]
	v_mfma_f32_16x16x32_bf16 v[56:59], v[140:143], v[164:167], v[56:59]
	v_mfma_f32_16x16x32_bf16 v[44:47], v[132:135], v[172:175], v[44:47]
	v_mfma_f32_16x16x32_bf16 v[40:43], v[140:143], v[172:175], v[40:43]
	v_mfma_f32_16x16x32_bf16 v[28:31], v[132:135], v[180:183], v[28:31]
	v_mfma_f32_16x16x32_bf16 v[24:27], v[140:143], v[180:183], v[24:27]
	v_mfma_f32_16x16x32_bf16 v[12:15], v[132:135], v[204:207], v[12:15]
	v_mfma_f32_16x16x32_bf16 v[8:11], v[140:143], v[204:207], v[8:11]
	v_mfma_f32_16x16x32_bf16 v[52:55], v[144:147], v[160:163], v[52:55]
	v_mfma_f32_16x16x32_bf16 v[48:51], v[152:155], v[160:163], v[48:51]
	v_mfma_f32_16x16x32_bf16 v[36:39], v[144:147], v[168:171], v[36:39]
	v_mfma_f32_16x16x32_bf16 v[32:35], v[152:155], v[168:171], v[32:35]
	v_mfma_f32_16x16x32_bf16 v[20:23], v[144:147], v[176:179], v[20:23]
	v_mfma_f32_16x16x32_bf16 v[16:19], v[152:155], v[176:179], v[16:19]
	v_mfma_f32_16x16x32_bf16 v[4:7], v[144:147], v[200:203], v[4:7]
	v_mfma_f32_16x16x32_bf16 v[0:3], v[152:155], v[200:203], v[0:3]
	v_mfma_f32_16x16x32_bf16 v[52:55], v[148:151], v[164:167], v[52:55]
	v_mfma_f32_16x16x32_bf16 v[48:51], v[156:159], v[164:167], v[48:51]
	v_mfma_f32_16x16x32_bf16 v[36:39], v[148:151], v[172:175], v[36:39]
	v_mfma_f32_16x16x32_bf16 v[32:35], v[156:159], v[172:175], v[32:35]
	s_setprio 2
	s_barrier
	v_mfma_f32_16x16x32_bf16 v[20:23], v[148:151], v[180:183], v[20:23]
	v_mfma_f32_16x16x32_bf16 v[16:19], v[156:159], v[180:183], v[16:19]
	v_mfma_f32_16x16x32_bf16 v[4:7], v[148:151], v[204:207], v[4:7]
	v_mfma_f32_16x16x32_bf16 v[0:3], v[156:159], v[204:207], v[0:3]
	s_setprio 0
	s_add_i32 s66, s66, 2
	s_add_u32 s38, s38, 0x100
	s_addc_u32 s39, s39, 0
	s_add_u32 s64, s64, 0x100
	s_addc_u32 s65, s65, 0
	s_cmp_gt_u32 s66, 13
	s_cbranch_scc0 .LBB0_1146

.LBB0_1309:
	s_add_u32 s51, s26, 0x100
	s_addc_u32 s52, s27, 0
	s_mov_b32 s53, -2
	ds_read_b128 v[128:131], v197
	ds_read_b128 v[132:135], v197 offset:1024
	ds_read_b128 v[136:139], v197 offset:2048
	ds_read_b128 v[140:143], v197 offset:3072
	ds_read_b128 v[144:147], v198
	ds_read_b128 v[148:151], v198 offset:1024
	ds_read_b128 v[152:155], v198 offset:2048
	ds_read_b128 v[156:159], v198 offset:3072
	s_add_u32 s4, s24, 0x100
	s_addc_u32 s5, s25, 0
	s_cmp_eq_u32 s53, 40
	s_cselect_b32 s29, s21, s5
	s_cselect_b32 s28, s20, s4
	s_cselect_b32 s27, s23, s52
	s_cselect_b32 s26, s22, s51
	v_lshl_add_u64 v[212:213], s[24:25], 0, v[172:173]
	s_add_i32 m0, s36, 0xc000
	ds_read_b128 v[160:163], v199
	ds_read_b128 v[180:183], v199 offset:1024
	ds_read_b128 v[184:187], v199 offset:2048
	ds_read_b128 v[188:191], v199 offset:3072
	ds_read_b128 v[192:195], v199 offset:4096
	ds_read_b128 v[200:203], v199 offset:5120
	ds_read_b128 v[204:207], v199 offset:6144
	ds_read_b128 v[208:211], v199 offset:7168
	global_load_lds_dwordx4 v[212:213], off
	s_add_i32 m0, s36, 0xe000
	v_lshl_add_u64 v[212:213], s[24:25], 0, v[174:175]
	global_load_lds_dwordx4 v[212:213], off
	s_waitcnt vmcnt(8)
	s_waitcnt lgkmcnt(0)
	s_barrier
	s_setprio 1
	s_waitcnt lgkmcnt(0)
	v_mfma_f32_16x16x32_bf16 v[124:127], v[128:131], v[160:163], 0
	v_mfma_f32_16x16x32_bf16 v[120:123], v[136:139], v[160:163], 0
	v_mfma_f32_16x16x32_bf16 v[116:119], v[128:131], v[184:187], 0
	v_mfma_f32_16x16x32_bf16 v[108:111], v[136:139], v[184:187], 0
	v_mfma_f32_16x16x32_bf16 v[88:91], v[128:131], v[192:195], 0
	v_mfma_f32_16x16x32_bf16 v[100:103], v[136:139], v[192:195], 0
	v_mfma_f32_16x16x32_bf16 v[72:75], v[128:131], v[204:207], 0
	v_mfma_f32_16x16x32_bf16 v[76:79], v[136:139], v[204:207], 0
	v_mfma_f32_16x16x32_bf16 v[124:127], v[132:135], v[180:183], v[124:127]
	v_mfma_f32_16x16x32_bf16 v[120:123], v[140:143], v[180:183], v[120:123]
	v_mfma_f32_16x16x32_bf16 v[116:119], v[132:135], v[188:191], v[116:119]
	v_mfma_f32_16x16x32_bf16 v[108:111], v[140:143], v[188:191], v[108:111]
	v_mfma_f32_16x16x32_bf16 v[88:91], v[132:135], v[200:203], v[88:91]
	v_mfma_f32_16x16x32_bf16 v[100:103], v[140:143], v[200:203], v[100:103]
	v_mfma_f32_16x16x32_bf16 v[72:75], v[132:135], v[208:211], v[72:75]
	v_mfma_f32_16x16x32_bf16 v[76:79], v[140:143], v[208:211], v[76:79]
	v_mfma_f32_16x16x32_bf16 v[112:115], v[144:147], v[160:163], 0
	v_mfma_f32_16x16x32_bf16 v[104:107], v[152:155], v[160:163], 0
	v_mfma_f32_16x16x32_bf16 v[96:99], v[144:147], v[184:187], 0
	v_mfma_f32_16x16x32_bf16 v[92:95], v[152:155], v[184:187], 0
	v_mfma_f32_16x16x32_bf16 v[80:83], v[144:147], v[192:195], 0
	v_mfma_f32_16x16x32_bf16 v[84:87], v[152:155], v[192:195], 0
	v_mfma_f32_16x16x32_bf16 v[64:67], v[144:147], v[204:207], 0
	v_mfma_f32_16x16x32_bf16 v[68:71], v[152:155], v[204:207], 0
	v_mfma_f32_16x16x32_bf16 v[112:115], v[148:151], v[180:183], v[112:115]
	v_mfma_f32_16x16x32_bf16 v[104:107], v[156:159], v[180:183], v[104:107]
	v_mfma_f32_16x16x32_bf16 v[96:99], v[148:151], v[188:191], v[96:99]
	v_mfma_f32_16x16x32_bf16 v[92:95], v[156:159], v[188:191], v[92:95]
	s_setprio 2
	s_barrier
	v_mfma_f32_16x16x32_bf16 v[80:83], v[148:151], v[200:203], v[80:83]
	v_mfma_f32_16x16x32_bf16 v[84:87], v[156:159], v[200:203], v[84:87]
	v_mfma_f32_16x16x32_bf16 v[64:67], v[148:151], v[208:211], v[64:67]
	v_mfma_f32_16x16x32_bf16 v[68:71], v[156:159], v[208:211], v[68:71]
	s_setprio 0
	s_add_i32 s24, s45, s35
	v_lshl_add_u64 v[212:213], s[26:27], 0, v[166:167]
	s_mov_b32 m0, s24
	ds_read_b128 v[160:163], v199 offset:16384
	ds_read_b128 v[180:183], v199 offset:17408
	ds_read_b128 v[184:187], v199 offset:18432
	ds_read_b128 v[188:191], v199 offset:19456
	ds_read_b128 v[192:195], v199 offset:20480
	ds_read_b128 v[200:203], v199 offset:21504
	ds_read_b128 v[204:207], v199 offset:22528
	ds_read_b128 v[208:211], v199 offset:23552
	global_load_lds_dwordx4 v[212:213], off
	s_add_i32 m0, s24, 0x2000
	s_add_u32 s24, s26, 0xb0000
	v_lshl_add_u64 v[214:215], s[26:27], 0, v[170:171]
	s_addc_u32 s25, s27, 0
	s_add_i32 s54, s46, s35
	global_load_lds_dwordx4 v[214:215], off
	v_lshl_add_u64 v[216:217], s[24:25], 0, v[166:167]
	s_mov_b32 m0, s54
	v_lshl_add_u64 v[218:219], s[28:29], 0, v[168:169]
	global_load_lds_dwordx4 v[216:217], off
	s_add_i32 m0, s54, 0x2000
	v_lshl_add_u64 v[216:217], s[24:25], 0, v[170:171]
	global_load_lds_dwordx4 v[216:217], off
	s_mov_b32 m0, s36
	v_lshl_add_u64 v[216:217], s[28:29], 0, v[164:165]
	global_load_lds_dwordx4 v[216:217], off
	s_mov_b32 m0, s37
	s_nop 0
	global_load_lds_dwordx4 v[218:219], off
	s_waitcnt vmcnt(8)
	s_waitcnt lgkmcnt(0)
	s_barrier
	s_setprio 1
	s_waitcnt lgkmcnt(0)
	v_mfma_f32_16x16x32_bf16 v[56:59], v[128:131], v[160:163], 0
	v_mfma_f32_16x16x32_bf16 v[60:63], v[136:139], v[160:163], 0
	v_mfma_f32_16x16x32_bf16 v[40:43], v[128:131], v[184:187], 0
	v_mfma_f32_16x16x32_bf16 v[44:47], v[136:139], v[184:187], 0
	v_mfma_f32_16x16x32_bf16 v[24:27], v[128:131], v[192:195], 0
	v_mfma_f32_16x16x32_bf16 v[28:31], v[136:139], v[192:195], 0
	v_mfma_f32_16x16x32_bf16 v[8:11], v[128:131], v[204:207], 0
	v_mfma_f32_16x16x32_bf16 v[12:15], v[136:139], v[204:207], 0
	v_mfma_f32_16x16x32_bf16 v[56:59], v[132:135], v[180:183], v[56:59]
	v_mfma_f32_16x16x32_bf16 v[60:63], v[140:143], v[180:183], v[60:63]
	v_mfma_f32_16x16x32_bf16 v[40:43], v[132:135], v[188:191], v[40:43]
	v_mfma_f32_16x16x32_bf16 v[44:47], v[140:143], v[188:191], v[44:47]
	v_mfma_f32_16x16x32_bf16 v[24:27], v[132:135], v[200:203], v[24:27]
	v_mfma_f32_16x16x32_bf16 v[28:31], v[140:143], v[200:203], v[28:31]
	v_mfma_f32_16x16x32_bf16 v[8:11], v[132:135], v[208:211], v[8:11]
	v_mfma_f32_16x16x32_bf16 v[12:15], v[140:143], v[208:211], v[12:15]
	v_mfma_f32_16x16x32_bf16 v[48:51], v[144:147], v[160:163], 0
	v_mfma_f32_16x16x32_bf16 v[52:55], v[152:155], v[160:163], 0
	v_mfma_f32_16x16x32_bf16 v[32:35], v[144:147], v[184:187], 0
	v_mfma_f32_16x16x32_bf16 v[36:39], v[152:155], v[184:187], 0
	v_mfma_f32_16x16x32_bf16 v[16:19], v[144:147], v[192:195], 0
	v_mfma_f32_16x16x32_bf16 v[20:23], v[152:155], v[192:195], 0
	v_mfma_f32_16x16x32_bf16 v[0:3], v[144:147], v[204:207], 0
	v_mfma_f32_16x16x32_bf16 v[4:7], v[152:155], v[204:207], 0
	v_mfma_f32_16x16x32_bf16 v[48:51], v[148:151], v[180:183], v[48:51]
	v_mfma_f32_16x16x32_bf16 v[52:55], v[156:159], v[180:183], v[52:55]
	v_mfma_f32_16x16x32_bf16 v[32:35], v[148:151], v[188:191], v[32:35]
	v_mfma_f32_16x16x32_bf16 v[36:39], v[156:159], v[188:191], v[36:39]
	s_setprio 2
	s_barrier
	v_mfma_f32_16x16x32_bf16 v[16:19], v[148:151], v[200:203], v[16:19]
	v_mfma_f32_16x16x32_bf16 v[20:23], v[156:159], v[200:203], v[20:23]
	v_mfma_f32_16x16x32_bf16 v[0:3], v[148:151], v[208:211], v[0:3]
	v_mfma_f32_16x16x32_bf16 v[4:7], v[156:159], v[208:211], v[4:7]
	s_setprio 0
	s_add_i32 s54, 0, 0x18000
	s_add_i32 s55, 0, 0x1c000
	v_add_u32_e32 v140, s54, v196
	v_add_u32_e32 v156, s55, v196
	ds_read_b128 v[128:131], v140
	ds_read_b128 v[132:135], v140 offset:1024
	ds_read_b128 v[136:139], v140 offset:2048
	ds_read_b128 v[140:143], v140 offset:3072
	ds_read_b128 v[144:147], v156
	ds_read_b128 v[148:151], v156 offset:1024
	ds_read_b128 v[152:155], v156 offset:2048
	ds_read_b128 v[156:159], v156 offset:3072
	s_add_u32 s24, s28, 0xb0000
	s_addc_u32 s25, s29, 0
	s_mov_b32 m0, s38
	v_lshl_add_u64 v[220:221], s[24:25], 0, v[164:165]
	ds_read_b128 v[160:163], v199 offset:32768
	ds_read_b128 v[180:183], v199 offset:33792
	ds_read_b128 v[184:187], v199 offset:34816
	ds_read_b128 v[188:191], v199 offset:35840
	ds_read_b128 v[192:195], v199 offset:36864
	ds_read_b128 v[200:203], v199 offset:37888
	ds_read_b128 v[204:207], v199 offset:38912
	ds_read_b128 v[208:211], v199 offset:39936
	global_load_lds_dwordx4 v[220:221], off
	s_mov_b32 m0, s39
	v_lshl_add_u64 v[220:221], s[24:25], 0, v[168:169]
	global_load_lds_dwordx4 v[220:221], off
	s_waitcnt vmcnt(8)
	s_waitcnt lgkmcnt(0)
	s_barrier
	s_setprio 1
	s_waitcnt lgkmcnt(0)
	v_mfma_f32_16x16x32_bf16 v[124:127], v[128:131], v[160:163], v[124:127]
	v_mfma_f32_16x16x32_bf16 v[120:123], v[136:139], v[160:163], v[120:123]
	v_mfma_f32_16x16x32_bf16 v[116:119], v[128:131], v[184:187], v[116:119]
	v_mfma_f32_16x16x32_bf16 v[108:111], v[136:139], v[184:187], v[108:111]
	v_mfma_f32_16x16x32_bf16 v[88:91], v[128:131], v[192:195], v[88:91]
	v_mfma_f32_16x16x32_bf16 v[100:103], v[136:139], v[192:195], v[100:103]
	v_mfma_f32_16x16x32_bf16 v[72:75], v[128:131], v[204:207], v[72:75]
	v_mfma_f32_16x16x32_bf16 v[76:79], v[136:139], v[204:207], v[76:79]
	v_mfma_f32_16x16x32_bf16 v[124:127], v[132:135], v[180:183], v[124:127]
	v_mfma_f32_16x16x32_bf16 v[120:123], v[140:143], v[180:183], v[120:123]
	v_mfma_f32_16x16x32_bf16 v[116:119], v[132:135], v[188:191], v[116:119]
	v_mfma_f32_16x16x32_bf16 v[108:111], v[140:143], v[188:191], v[108:111]
	v_mfma_f32_16x16x32_bf16 v[88:91], v[132:135], v[200:203], v[88:91]
	v_mfma_f32_16x16x32_bf16 v[100:103], v[140:143], v[200:203], v[100:103]
	v_mfma_f32_16x16x32_bf16 v[72:75], v[132:135], v[208:211], v[72:75]
	v_mfma_f32_16x16x32_bf16 v[76:79], v[140:143], v[208:211], v[76:79]
	v_mfma_f32_16x16x32_bf16 v[112:115], v[144:147], v[160:163], v[112:115]
	v_mfma_f32_16x16x32_bf16 v[104:107], v[152:155], v[160:163], v[104:107]
	v_mfma_f32_16x16x32_bf16 v[96:99], v[144:147], v[184:187], v[96:99]
	v_mfma_f32_16x16x32_bf16 v[92:95], v[152:155], v[184:187], v[92:95]
	v_mfma_f32_16x16x32_bf16 v[80:83], v[144:147], v[192:195], v[80:83]
	v_mfma_f32_16x16x32_bf16 v[84:87], v[152:155], v[192:195], v[84:87]
	v_mfma_f32_16x16x32_bf16 v[64:67], v[144:147], v[204:207], v[64:67]
	v_mfma_f32_16x16x32_bf16 v[68:71], v[152:155], v[204:207], v[68:71]
	v_mfma_f32_16x16x32_bf16 v[112:115], v[148:151], v[180:183], v[112:115]
	v_mfma_f32_16x16x32_bf16 v[104:107], v[156:159], v[180:183], v[104:107]
	v_mfma_f32_16x16x32_bf16 v[96:99], v[148:151], v[188:191], v[96:99]
	v_mfma_f32_16x16x32_bf16 v[92:95], v[156:159], v[188:191], v[92:95]
	s_setprio 2
	s_barrier
	v_mfma_f32_16x16x32_bf16 v[80:83], v[148:151], v[200:203], v[80:83]
	v_mfma_f32_16x16x32_bf16 v[84:87], v[156:159], v[200:203], v[84:87]
	v_mfma_f32_16x16x32_bf16 v[64:67], v[148:151], v[208:211], v[64:67]
	v_mfma_f32_16x16x32_bf16 v[68:71], v[156:159], v[208:211], v[68:71]
	s_setprio 0
	s_add_i32 s24, s54, s35
	v_lshl_add_u64 v[212:213], v[212:213], 0, s[16:17]
	s_mov_b32 m0, s24
	ds_read_b128 v[160:163], v199 offset:49152
	ds_read_b128 v[180:183], v199 offset:50176
	ds_read_b128 v[184:187], v199 offset:51200
	ds_read_b128 v[188:191], v199 offset:52224
	ds_read_b128 v[192:195], v199 offset:53248
	ds_read_b128 v[200:203], v199 offset:54272
	ds_read_b128 v[204:207], v199 offset:55296
	ds_read_b128 v[208:211], v199 offset:56320
	global_load_lds_dwordx4 v[212:213], off
	s_add_i32 m0, s24, 0x2000
	s_add_u32 s24, s26, 0xb0080
	v_lshl_add_u64 v[212:213], v[214:215], 0, s[16:17]
	s_addc_u32 s25, s27, 0
	s_add_i32 s26, s55, s35
	global_load_lds_dwordx4 v[212:213], off
	s_mov_b32 m0, s26
	v_lshl_add_u64 v[212:213], s[24:25], 0, v[166:167]
	global_load_lds_dwordx4 v[212:213], off
	s_add_i32 m0, s26, 0x2000
	v_lshl_add_u64 v[212:213], s[24:25], 0, v[170:171]
	global_load_lds_dwordx4 v[212:213], off
	s_mov_b32 m0, s41
	v_lshl_add_u64 v[212:213], v[216:217], 0, s[16:17]
	global_load_lds_dwordx4 v[212:213], off
	s_mov_b32 m0, s42
	v_lshl_add_u64 v[212:213], v[218:219], 0, s[16:17]
	global_load_lds_dwordx4 v[212:213], off
	s_waitcnt vmcnt(8)
	s_waitcnt lgkmcnt(0)
	s_barrier
	s_setprio 1
	s_waitcnt lgkmcnt(0)
	v_mfma_f32_16x16x32_bf16 v[56:59], v[128:131], v[160:163], v[56:59]
	v_mfma_f32_16x16x32_bf16 v[60:63], v[136:139], v[160:163], v[60:63]
	v_mfma_f32_16x16x32_bf16 v[40:43], v[128:131], v[184:187], v[40:43]
	v_mfma_f32_16x16x32_bf16 v[44:47], v[136:139], v[184:187], v[44:47]
	v_mfma_f32_16x16x32_bf16 v[24:27], v[128:131], v[192:195], v[24:27]
	v_mfma_f32_16x16x32_bf16 v[28:31], v[136:139], v[192:195], v[28:31]
	v_mfma_f32_16x16x32_bf16 v[8:11], v[128:131], v[204:207], v[8:11]
	v_mfma_f32_16x16x32_bf16 v[12:15], v[136:139], v[204:207], v[12:15]
	v_mfma_f32_16x16x32_bf16 v[56:59], v[132:135], v[180:183], v[56:59]
	v_mfma_f32_16x16x32_bf16 v[60:63], v[140:143], v[180:183], v[60:63]
	v_mfma_f32_16x16x32_bf16 v[40:43], v[132:135], v[188:191], v[40:43]
	v_mfma_f32_16x16x32_bf16 v[44:47], v[140:143], v[188:191], v[44:47]
	v_mfma_f32_16x16x32_bf16 v[24:27], v[132:135], v[200:203], v[24:27]
	v_mfma_f32_16x16x32_bf16 v[28:31], v[140:143], v[200:203], v[28:31]
	v_mfma_f32_16x16x32_bf16 v[8:11], v[132:135], v[208:211], v[8:11]
	v_mfma_f32_16x16x32_bf16 v[12:15], v[140:143], v[208:211], v[12:15]
	v_mfma_f32_16x16x32_bf16 v[48:51], v[144:147], v[160:163], v[48:51]
	v_mfma_f32_16x16x32_bf16 v[52:55], v[152:155], v[160:163], v[52:55]
	v_mfma_f32_16x16x32_bf16 v[32:35], v[144:147], v[184:187], v[32:35]
	v_mfma_f32_16x16x32_bf16 v[36:39], v[152:155], v[184:187], v[36:39]
	v_mfma_f32_16x16x32_bf16 v[16:19], v[144:147], v[192:195], v[16:19]
	v_mfma_f32_16x16x32_bf16 v[20:23], v[152:155], v[192:195], v[20:23]
	v_mfma_f32_16x16x32_bf16 v[0:3], v[144:147], v[204:207], v[0:3]
	v_mfma_f32_16x16x32_bf16 v[4:7], v[152:155], v[204:207], v[4:7]
	v_mfma_f32_16x16x32_bf16 v[48:51], v[148:151], v[180:183], v[48:51]
	v_mfma_f32_16x16x32_bf16 v[52:55], v[156:159], v[180:183], v[52:55]
	v_mfma_f32_16x16x32_bf16 v[32:35], v[148:151], v[188:191], v[32:35]
	v_mfma_f32_16x16x32_bf16 v[36:39], v[156:159], v[188:191], v[36:39]
	s_setprio 2
	s_barrier
	v_mfma_f32_16x16x32_bf16 v[16:19], v[148:151], v[200:203], v[16:19]
	v_mfma_f32_16x16x32_bf16 v[20:23], v[156:159], v[200:203], v[20:23]
	v_mfma_f32_16x16x32_bf16 v[0:3], v[148:151], v[208:211], v[0:3]
	v_mfma_f32_16x16x32_bf16 v[4:7], v[156:159], v[208:211], v[4:7]
	s_setprio 0
	s_add_i32 s53, s53, 2
	s_add_u32 s51, s51, 0x100
	s_addc_u32 s52, s52, 0
	s_cmp_gt_u32 s53, 41
	s_mov_b64 s[24:25], s[4:5]
.LBB0_1310:
	ds_read_b128 v[128:131], v197
	ds_read_b128 v[132:135], v197 offset:1024
	ds_read_b128 v[136:139], v197 offset:2048
	ds_read_b128 v[140:143], v197 offset:3072
	ds_read_b128 v[144:147], v198
	ds_read_b128 v[148:151], v198 offset:1024
	ds_read_b128 v[152:155], v198 offset:2048
	ds_read_b128 v[156:159], v198 offset:3072
	s_add_u32 s4, s24, 0x100
	s_addc_u32 s5, s25, 0
	s_cmp_eq_u32 s53, 40
	s_cselect_b32 s29, s21, s5
	s_cselect_b32 s28, s20, s4
	s_cselect_b32 s27, s23, s52
	s_cselect_b32 s26, s22, s51
	v_lshl_add_u64 v[212:213], s[24:25], 0, v[172:173]
	s_add_i32 m0, s36, 0xc000
	ds_read_b128 v[160:163], v199
	ds_read_b128 v[180:183], v199 offset:1024
	ds_read_b128 v[184:187], v199 offset:2048
	ds_read_b128 v[188:191], v199 offset:3072
	ds_read_b128 v[192:195], v199 offset:4096
	ds_read_b128 v[200:203], v199 offset:5120
	ds_read_b128 v[204:207], v199 offset:6144
	ds_read_b128 v[208:211], v199 offset:7168
	global_load_lds_dwordx4 v[212:213], off
	s_add_i32 m0, s36, 0xe000
	v_lshl_add_u64 v[212:213], s[24:25], 0, v[174:175]
	global_load_lds_dwordx4 v[212:213], off
	s_waitcnt vmcnt(8)
	s_waitcnt lgkmcnt(0)
	s_barrier
	s_setprio 1
	s_waitcnt lgkmcnt(0)
	v_mfma_f32_16x16x32_bf16 v[124:127], v[128:131], v[160:163], v[124:127]
	v_mfma_f32_16x16x32_bf16 v[120:123], v[136:139], v[160:163], v[120:123]
	v_mfma_f32_16x16x32_bf16 v[116:119], v[128:131], v[184:187], v[116:119]
	v_mfma_f32_16x16x32_bf16 v[108:111], v[136:139], v[184:187], v[108:111]
	v_mfma_f32_16x16x32_bf16 v[88:91], v[128:131], v[192:195], v[88:91]
	v_mfma_f32_16x16x32_bf16 v[100:103], v[136:139], v[192:195], v[100:103]
	v_mfma_f32_16x16x32_bf16 v[72:75], v[128:131], v[204:207], v[72:75]
	v_mfma_f32_16x16x32_bf16 v[76:79], v[136:139], v[204:207], v[76:79]
	v_mfma_f32_16x16x32_bf16 v[124:127], v[132:135], v[180:183], v[124:127]
	v_mfma_f32_16x16x32_bf16 v[120:123], v[140:143], v[180:183], v[120:123]
	v_mfma_f32_16x16x32_bf16 v[116:119], v[132:135], v[188:191], v[116:119]
	v_mfma_f32_16x16x32_bf16 v[108:111], v[140:143], v[188:191], v[108:111]
	v_mfma_f32_16x16x32_bf16 v[88:91], v[132:135], v[200:203], v[88:91]
	v_mfma_f32_16x16x32_bf16 v[100:103], v[140:143], v[200:203], v[100:103]
	v_mfma_f32_16x16x32_bf16 v[72:75], v[132:135], v[208:211], v[72:75]
	v_mfma_f32_16x16x32_bf16 v[76:79], v[140:143], v[208:211], v[76:79]
	v_mfma_f32_16x16x32_bf16 v[112:115], v[144:147], v[160:163], v[112:115]
	v_mfma_f32_16x16x32_bf16 v[104:107], v[152:155], v[160:163], v[104:107]
	v_mfma_f32_16x16x32_bf16 v[96:99], v[144:147], v[184:187], v[96:99]
	v_mfma_f32_16x16x32_bf16 v[92:95], v[152:155], v[184:187], v[92:95]
	v_mfma_f32_16x16x32_bf16 v[80:83], v[144:147], v[192:195], v[80:83]
	v_mfma_f32_16x16x32_bf16 v[84:87], v[152:155], v[192:195], v[84:87]
	v_mfma_f32_16x16x32_bf16 v[64:67], v[144:147], v[204:207], v[64:67]
	v_mfma_f32_16x16x32_bf16 v[68:71], v[152:155], v[204:207], v[68:71]
	v_mfma_f32_16x16x32_bf16 v[112:115], v[148:151], v[180:183], v[112:115]
	v_mfma_f32_16x16x32_bf16 v[104:107], v[156:159], v[180:183], v[104:107]
	v_mfma_f32_16x16x32_bf16 v[96:99], v[148:151], v[188:191], v[96:99]
	v_mfma_f32_16x16x32_bf16 v[92:95], v[156:159], v[188:191], v[92:95]
	s_setprio 2
	s_barrier
	v_mfma_f32_16x16x32_bf16 v[80:83], v[148:151], v[200:203], v[80:83]
	v_mfma_f32_16x16x32_bf16 v[84:87], v[156:159], v[200:203], v[84:87]
	v_mfma_f32_16x16x32_bf16 v[64:67], v[148:151], v[208:211], v[64:67]
	v_mfma_f32_16x16x32_bf16 v[68:71], v[156:159], v[208:211], v[68:71]
	s_setprio 0
	s_add_i32 s24, s45, s35
	v_lshl_add_u64 v[212:213], s[26:27], 0, v[166:167]
	s_mov_b32 m0, s24
	ds_read_b128 v[160:163], v199 offset:16384
	ds_read_b128 v[180:183], v199 offset:17408
	ds_read_b128 v[184:187], v199 offset:18432
	ds_read_b128 v[188:191], v199 offset:19456
	ds_read_b128 v[192:195], v199 offset:20480
	ds_read_b128 v[200:203], v199 offset:21504
	ds_read_b128 v[204:207], v199 offset:22528
	ds_read_b128 v[208:211], v199 offset:23552
	global_load_lds_dwordx4 v[212:213], off
	s_add_i32 m0, s24, 0x2000
	s_add_u32 s24, s26, 0xb0000
	v_lshl_add_u64 v[214:215], s[26:27], 0, v[170:171]
	s_addc_u32 s25, s27, 0
	s_add_i32 s54, s46, s35
	global_load_lds_dwordx4 v[214:215], off
	v_lshl_add_u64 v[216:217], s[24:25], 0, v[166:167]
	s_mov_b32 m0, s54
	v_lshl_add_u64 v[218:219], s[28:29], 0, v[168:169]
	global_load_lds_dwordx4 v[216:217], off
	s_add_i32 m0, s54, 0x2000
	v_lshl_add_u64 v[216:217], s[24:25], 0, v[170:171]
	global_load_lds_dwordx4 v[216:217], off
	s_mov_b32 m0, s36
	v_lshl_add_u64 v[216:217], s[28:29], 0, v[164:165]
	global_load_lds_dwordx4 v[216:217], off
	s_mov_b32 m0, s37
	s_nop 0
	global_load_lds_dwordx4 v[218:219], off
	s_waitcnt vmcnt(8)
	s_waitcnt lgkmcnt(0)
	s_barrier
	s_setprio 1
	s_waitcnt lgkmcnt(0)
	v_mfma_f32_16x16x32_bf16 v[56:59], v[128:131], v[160:163], v[56:59]
	v_mfma_f32_16x16x32_bf16 v[60:63], v[136:139], v[160:163], v[60:63]
	v_mfma_f32_16x16x32_bf16 v[40:43], v[128:131], v[184:187], v[40:43]
	v_mfma_f32_16x16x32_bf16 v[44:47], v[136:139], v[184:187], v[44:47]
	v_mfma_f32_16x16x32_bf16 v[24:27], v[128:131], v[192:195], v[24:27]
	v_mfma_f32_16x16x32_bf16 v[28:31], v[136:139], v[192:195], v[28:31]
	v_mfma_f32_16x16x32_bf16 v[8:11], v[128:131], v[204:207], v[8:11]
	v_mfma_f32_16x16x32_bf16 v[12:15], v[136:139], v[204:207], v[12:15]
	v_mfma_f32_16x16x32_bf16 v[56:59], v[132:135], v[180:183], v[56:59]
	v_mfma_f32_16x16x32_bf16 v[60:63], v[140:143], v[180:183], v[60:63]
	v_mfma_f32_16x16x32_bf16 v[40:43], v[132:135], v[188:191], v[40:43]
	v_mfma_f32_16x16x32_bf16 v[44:47], v[140:143], v[188:191], v[44:47]
	v_mfma_f32_16x16x32_bf16 v[24:27], v[132:135], v[200:203], v[24:27]
	v_mfma_f32_16x16x32_bf16 v[28:31], v[140:143], v[200:203], v[28:31]
	v_mfma_f32_16x16x32_bf16 v[8:11], v[132:135], v[208:211], v[8:11]
	v_mfma_f32_16x16x32_bf16 v[12:15], v[140:143], v[208:211], v[12:15]
	v_mfma_f32_16x16x32_bf16 v[48:51], v[144:147], v[160:163], v[48:51]
	v_mfma_f32_16x16x32_bf16 v[52:55], v[152:155], v[160:163], v[52:55]
	v_mfma_f32_16x16x32_bf16 v[32:35], v[144:147], v[184:187], v[32:35]
	v_mfma_f32_16x16x32_bf16 v[36:39], v[152:155], v[184:187], v[36:39]
	v_mfma_f32_16x16x32_bf16 v[16:19], v[144:147], v[192:195], v[16:19]
	v_mfma_f32_16x16x32_bf16 v[20:23], v[152:155], v[192:195], v[20:23]
	v_mfma_f32_16x16x32_bf16 v[0:3], v[144:147], v[204:207], v[0:3]
	v_mfma_f32_16x16x32_bf16 v[4:7], v[152:155], v[204:207], v[4:7]
	v_mfma_f32_16x16x32_bf16 v[48:51], v[148:151], v[180:183], v[48:51]
	v_mfma_f32_16x16x32_bf16 v[52:55], v[156:159], v[180:183], v[52:55]
	v_mfma_f32_16x16x32_bf16 v[32:35], v[148:151], v[188:191], v[32:35]
	v_mfma_f32_16x16x32_bf16 v[36:39], v[156:159], v[188:191], v[36:39]
	s_setprio 2
	s_barrier
	v_mfma_f32_16x16x32_bf16 v[16:19], v[148:151], v[200:203], v[16:19]
	v_mfma_f32_16x16x32_bf16 v[20:23], v[156:159], v[200:203], v[20:23]
	v_mfma_f32_16x16x32_bf16 v[0:3], v[148:151], v[208:211], v[0:3]
	v_mfma_f32_16x16x32_bf16 v[4:7], v[156:159], v[208:211], v[4:7]
	s_setprio 0
	s_add_i32 s54, 0, 0x18000
	s_add_i32 s55, 0, 0x1c000
	v_add_u32_e32 v140, s54, v196
	v_add_u32_e32 v156, s55, v196
	ds_read_b128 v[128:131], v140
	ds_read_b128 v[132:135], v140 offset:1024
	ds_read_b128 v[136:139], v140 offset:2048
	ds_read_b128 v[140:143], v140 offset:3072
	ds_read_b128 v[144:147], v156
	ds_read_b128 v[148:151], v156 offset:1024
	ds_read_b128 v[152:155], v156 offset:2048
	ds_read_b128 v[156:159], v156 offset:3072
	s_add_u32 s24, s28, 0xb0000
	s_addc_u32 s25, s29, 0
	s_mov_b32 m0, s38
	v_lshl_add_u64 v[220:221], s[24:25], 0, v[164:165]
	ds_read_b128 v[160:163], v199 offset:32768
	ds_read_b128 v[180:183], v199 offset:33792
	ds_read_b128 v[184:187], v199 offset:34816
	ds_read_b128 v[188:191], v199 offset:35840
	ds_read_b128 v[192:195], v199 offset:36864
	ds_read_b128 v[200:203], v199 offset:37888
	ds_read_b128 v[204:207], v199 offset:38912
	ds_read_b128 v[208:211], v199 offset:39936
	global_load_lds_dwordx4 v[220:221], off
	s_mov_b32 m0, s39
	v_lshl_add_u64 v[220:221], s[24:25], 0, v[168:169]
	global_load_lds_dwordx4 v[220:221], off
	s_waitcnt vmcnt(8)
	s_waitcnt lgkmcnt(0)
	s_barrier
	s_setprio 1
	s_waitcnt lgkmcnt(0)
	v_mfma_f32_16x16x32_bf16 v[124:127], v[128:131], v[160:163], v[124:127]
	v_mfma_f32_16x16x32_bf16 v[120:123], v[136:139], v[160:163], v[120:123]
	v_mfma_f32_16x16x32_bf16 v[116:119], v[128:131], v[184:187], v[116:119]
	v_mfma_f32_16x16x32_bf16 v[108:111], v[136:139], v[184:187], v[108:111]
	v_mfma_f32_16x16x32_bf16 v[88:91], v[128:131], v[192:195], v[88:91]
	v_mfma_f32_16x16x32_bf16 v[100:103], v[136:139], v[192:195], v[100:103]
	v_mfma_f32_16x16x32_bf16 v[72:75], v[128:131], v[204:207], v[72:75]
	v_mfma_f32_16x16x32_bf16 v[76:79], v[136:139], v[204:207], v[76:79]
	v_mfma_f32_16x16x32_bf16 v[124:127], v[132:135], v[180:183], v[124:127]
	v_mfma_f32_16x16x32_bf16 v[120:123], v[140:143], v[180:183], v[120:123]
	v_mfma_f32_16x16x32_bf16 v[116:119], v[132:135], v[188:191], v[116:119]
	v_mfma_f32_16x16x32_bf16 v[108:111], v[140:143], v[188:191], v[108:111]
	v_mfma_f32_16x16x32_bf16 v[88:91], v[132:135], v[200:203], v[88:91]
	v_mfma_f32_16x16x32_bf16 v[100:103], v[140:143], v[200:203], v[100:103]
	v_mfma_f32_16x16x32_bf16 v[72:75], v[132:135], v[208:211], v[72:75]
	v_mfma_f32_16x16x32_bf16 v[76:79], v[140:143], v[208:211], v[76:79]
	v_mfma_f32_16x16x32_bf16 v[112:115], v[144:147], v[160:163], v[112:115]
	v_mfma_f32_16x16x32_bf16 v[104:107], v[152:155], v[160:163], v[104:107]
	v_mfma_f32_16x16x32_bf16 v[96:99], v[144:147], v[184:187], v[96:99]
	v_mfma_f32_16x16x32_bf16 v[92:95], v[152:155], v[184:187], v[92:95]
	v_mfma_f32_16x16x32_bf16 v[80:83], v[144:147], v[192:195], v[80:83]
	v_mfma_f32_16x16x32_bf16 v[84:87], v[152:155], v[192:195], v[84:87]
	v_mfma_f32_16x16x32_bf16 v[64:67], v[144:147], v[204:207], v[64:67]
	v_mfma_f32_16x16x32_bf16 v[68:71], v[152:155], v[204:207], v[68:71]
	v_mfma_f32_16x16x32_bf16 v[112:115], v[148:151], v[180:183], v[112:115]
	v_mfma_f32_16x16x32_bf16 v[104:107], v[156:159], v[180:183], v[104:107]
	v_mfma_f32_16x16x32_bf16 v[96:99], v[148:151], v[188:191], v[96:99]
	v_mfma_f32_16x16x32_bf16 v[92:95], v[156:159], v[188:191], v[92:95]
	s_setprio 2
	s_barrier
	v_mfma_f32_16x16x32_bf16 v[80:83], v[148:151], v[200:203], v[80:83]
	v_mfma_f32_16x16x32_bf16 v[84:87], v[156:159], v[200:203], v[84:87]
	v_mfma_f32_16x16x32_bf16 v[64:67], v[148:151], v[208:211], v[64:67]
	v_mfma_f32_16x16x32_bf16 v[68:71], v[156:159], v[208:211], v[68:71]
	s_setprio 0
	s_add_i32 s24, s54, s35
	v_lshl_add_u64 v[212:213], v[212:213], 0, s[16:17]
	s_mov_b32 m0, s24
	ds_read_b128 v[160:163], v199 offset:49152
	ds_read_b128 v[180:183], v199 offset:50176
	ds_read_b128 v[184:187], v199 offset:51200
	ds_read_b128 v[188:191], v199 offset:52224
	ds_read_b128 v[192:195], v199 offset:53248
	ds_read_b128 v[200:203], v199 offset:54272
	ds_read_b128 v[204:207], v199 offset:55296
	ds_read_b128 v[208:211], v199 offset:56320
	global_load_lds_dwordx4 v[212:213], off
	s_add_i32 m0, s24, 0x2000
	s_add_u32 s24, s26, 0xb0080
	v_lshl_add_u64 v[212:213], v[214:215], 0, s[16:17]
	s_addc_u32 s25, s27, 0
	s_add_i32 s26, s55, s35
	global_load_lds_dwordx4 v[212:213], off
	s_mov_b32 m0, s26
	v_lshl_add_u64 v[212:213], s[24:25], 0, v[166:167]
	global_load_lds_dwordx4 v[212:213], off
	s_add_i32 m0, s26, 0x2000
	v_lshl_add_u64 v[212:213], s[24:25], 0, v[170:171]
	global_load_lds_dwordx4 v[212:213], off
	s_mov_b32 m0, s41
	v_lshl_add_u64 v[212:213], v[216:217], 0, s[16:17]
	global_load_lds_dwordx4 v[212:213], off
	s_mov_b32 m0, s42
	v_lshl_add_u64 v[212:213], v[218:219], 0, s[16:17]
	global_load_lds_dwordx4 v[212:213], off
	s_waitcnt vmcnt(8)
	s_waitcnt lgkmcnt(0)
	s_barrier
	s_setprio 1
	s_waitcnt lgkmcnt(0)
	v_mfma_f32_16x16x32_bf16 v[56:59], v[128:131], v[160:163], v[56:59]
	v_mfma_f32_16x16x32_bf16 v[60:63], v[136:139], v[160:163], v[60:63]
	v_mfma_f32_16x16x32_bf16 v[40:43], v[128:131], v[184:187], v[40:43]
	v_mfma_f32_16x16x32_bf16 v[44:47], v[136:139], v[184:187], v[44:47]
	v_mfma_f32_16x16x32_bf16 v[24:27], v[128:131], v[192:195], v[24:27]
	v_mfma_f32_16x16x32_bf16 v[28:31], v[136:139], v[192:195], v[28:31]
	v_mfma_f32_16x16x32_bf16 v[8:11], v[128:131], v[204:207], v[8:11]
	v_mfma_f32_16x16x32_bf16 v[12:15], v[136:139], v[204:207], v[12:15]
	v_mfma_f32_16x16x32_bf16 v[56:59], v[132:135], v[180:183], v[56:59]
	v_mfma_f32_16x16x32_bf16 v[60:63], v[140:143], v[180:183], v[60:63]
	v_mfma_f32_16x16x32_bf16 v[40:43], v[132:135], v[188:191], v[40:43]
	v_mfma_f32_16x16x32_bf16 v[44:47], v[140:143], v[188:191], v[44:47]
	v_mfma_f32_16x16x32_bf16 v[24:27], v[132:135], v[200:203], v[24:27]
	v_mfma_f32_16x16x32_bf16 v[28:31], v[140:143], v[200:203], v[28:31]
	v_mfma_f32_16x16x32_bf16 v[8:11], v[132:135], v[208:211], v[8:11]
	v_mfma_f32_16x16x32_bf16 v[12:15], v[140:143], v[208:211], v[12:15]
	v_mfma_f32_16x16x32_bf16 v[48:51], v[144:147], v[160:163], v[48:51]
	v_mfma_f32_16x16x32_bf16 v[52:55], v[152:155], v[160:163], v[52:55]
	v_mfma_f32_16x16x32_bf16 v[32:35], v[144:147], v[184:187], v[32:35]
	v_mfma_f32_16x16x32_bf16 v[36:39], v[152:155], v[184:187], v[36:39]
	v_mfma_f32_16x16x32_bf16 v[16:19], v[144:147], v[192:195], v[16:19]
	v_mfma_f32_16x16x32_bf16 v[20:23], v[152:155], v[192:195], v[20:23]
	v_mfma_f32_16x16x32_bf16 v[0:3], v[144:147], v[204:207], v[0:3]
	v_mfma_f32_16x16x32_bf16 v[4:7], v[152:155], v[204:207], v[4:7]
	v_mfma_f32_16x16x32_bf16 v[48:51], v[148:151], v[180:183], v[48:51]
	v_mfma_f32_16x16x32_bf16 v[52:55], v[156:159], v[180:183], v[52:55]
	v_mfma_f32_16x16x32_bf16 v[32:35], v[148:151], v[188:191], v[32:35]
	v_mfma_f32_16x16x32_bf16 v[36:39], v[156:159], v[188:191], v[36:39]
	s_setprio 2
	s_barrier
	v_mfma_f32_16x16x32_bf16 v[16:19], v[148:151], v[200:203], v[16:19]
	v_mfma_f32_16x16x32_bf16 v[20:23], v[156:159], v[200:203], v[20:23]
	v_mfma_f32_16x16x32_bf16 v[0:3], v[148:151], v[208:211], v[0:3]
	v_mfma_f32_16x16x32_bf16 v[4:7], v[156:159], v[208:211], v[4:7]
	s_setprio 0
	s_add_i32 s53, s53, 2
	s_add_u32 s51, s51, 0x100
	s_addc_u32 s52, s52, 0
	s_cmp_gt_u32 s53, 41
	s_mov_b64 s[24:25], s[4:5]
	s_cbranch_scc0 .LBB0_1310
